# 16-byte stores (lane-row exchange with v_permlane32/16_swap) also in the attention item epilogue and the phase-4 uq/uk GEMM epilogues
# speedup vs baseline: 1.0493x; 1.0121x over previous
; #define GLDS16(gp, lp) __builtin_amdgcn_global_load_lds((const unsigned*)(gp), (__attribute__((address_space(3))) unsigned*)(lp), 16, 0, 0)
; template <bool SWAP, class Epi, bool THIN = false> ...
;     ...
;     if (w < full * 8 * NT) { const int sr = w / (8 * NT), rem = w - sr * 8 * NT; nt = rem >> 3; mt = sr * 8 + (rem & 7); }
;     else { const int w2 = w - full * 8 * NT, rl = MT - full * 8; nt = w2 / rl; mt = full * 8 + (w2 - nt * rl); }
;     unsigned ap[4], bp[4];
; #pragma unroll
;     for (int i = 0; i < 4; ++i) {
;       const int r = (tid >> 3) + 64 * i;
;       const int cs = tid & 7;
;       const int c = ((cs ^ ((r >> 1) & 7)) << 3);
;       const int sub = 2 * mt + (r >> 7);
;       const int g = sub / tpg, ti = sub - g * tpg;
;       int rig = ti * step - halo + (r & 127); rig = rig < 0 ? 0 : (rig > grows - 1 ? grows - 1 : rig);
;       ap[i] = (unsigned)((g * a_gstride + a_goff + rig) * lda + c);
;       int br = nt * 256 + r; br = br > N - 1 ? N - 1 : br;
;       bp[i] = (unsigned)(br * K + c);
;     }
;     const bool have_next = false;
;     f32x4 acc[4][8];
; #pragma unroll
;     for (int m = 0; m < 4; ++m)
; #pragma unroll
;       for (int n = 0; n < 8; ++n) acc[m][n] = (f32x4){0.f, 0.f, 0.f, 0.f};
;     if (!pre_issued) {
; #pragma unroll
;       for (int i = 0; i < 4; ++i) { GLDS16(A + (size_t)ap[i], smem + tid * 16 + i * 8192); GLDS16(Bt + (size_t)bp[i], smem + 32768 + tid * 16 + i * 8192); }
;     }
;     pre_issued = have_next;
;     for (int st = 0; st < ns; ++st) {
;       asm volatile("s_waitcnt vmcnt(0)" ::: "memory");
;       __builtin_amdgcn_s_barrier();
;       asm volatile("" ::: "memory");
;       if (st + 1 < ns) {
;         char* nb = smem + ((st + 1) & 1) * 65536;
;         const int ko = (st + 1) * 64;
; #pragma unroll
;         for (int i = 0; i < 4; ++i) { GLDS16(A + (size_t)(ap[i] + ko), nb + tid * 16 + i * 8192); GLDS16(Bt + (size_t)(bp[i] + ko), nb + 32768 + tid * 16 + i * 8192); }
.LBB0_1749:
	s_mul_hi_i32 s4, s33, 0x2aaaaaab
	s_lshr_b32 s5, s4, 31
	s_ashr_i32 s4, s4, 3
	s_add_i32 s4, s4, s5
	s_lshl_b32 s5, s4, 4
	s_and_b32 s6, s46, 14
	s_or_b32 s5, s5, s6
	v_add_u32_e32 v2, s5, v143
	v_ashrrev_i32_e32 v3, 31, v2
	v_lshrrev_b32_e32 v3, 28, v3
	v_add_u32_e32 v3, v2, v3
	v_ashrrev_i32_e32 v3, 4, v3
	v_lshlrev_b32_e32 v4, 11, v3
	v_lshlrev_b32_e32 v2, 7, v2
	v_sub_u32_e32 v2, v2, v4
	v_or_b32_e32 v4, v2, v144
	v_min_i32_e32 v4, 0x7ff, v4
	s_mulk_i32 s4, 0xfa00
	v_lshlrev_b32_e32 v4, 9, v4
	v_cmp_lt_i32_e32 vcc, -1, v2
	s_add_i32 s4, s48, s4
	s_and_b32 s4, s4, 0xffffff00
	v_cndmask_b32_e32 v2, 0, v4, vcc
	v_lshl_add_u32 v2, v3, 20, v2
	v_or_b32_e32 v130, v2, v141
	v_add_u32_e32 v2, s4, v140
	v_min_i32_e32 v2, 0x5ff, v2
	v_lshl_or_b32 v4, v2, 9, v141
	v_add_u32_e32 v2, s5, v146
	v_ashrrev_i32_e32 v3, 31, v2
	v_lshrrev_b32_e32 v3, 28, v3
	v_add_u32_e32 v3, v2, v3
	v_ashrrev_i32_e32 v3, 4, v3
	v_lshlrev_b32_e32 v5, 11, v3
	v_lshlrev_b32_e32 v2, 7, v2
	v_sub_u32_e32 v2, v2, v5
	v_or_b32_e32 v5, v2, v147
	v_min_i32_e32 v5, 0x7ff, v5
	v_lshlrev_b32_e32 v5, 9, v5
	v_cmp_lt_i32_e32 vcc, -1, v2
	v_readfirstlane_b32 s44, v142
	s_mov_b32 m0, s44
	v_cndmask_b32_e32 v2, 0, v5, vcc
	v_lshl_add_u32 v2, v3, 20, v2
	v_or_b32_e32 v6, v2, v141
	v_add_u32_e32 v2, s4, v145
	v_min_i32_e32 v2, 0x5ff, v2
	v_lshl_or_b32 v8, v2, 9, v141
	v_add_u32_e32 v2, s5, v149
	v_ashrrev_i32_e32 v3, 31, v2
	v_lshrrev_b32_e32 v3, 28, v3
	v_add_u32_e32 v3, v2, v3
	v_ashrrev_i32_e32 v3, 4, v3
	v_lshlrev_b32_e32 v5, 11, v3
	v_lshlrev_b32_e32 v2, 7, v2
	v_sub_u32_e32 v2, v2, v5
	v_or_b32_e32 v5, v2, v144
	v_min_i32_e32 v5, 0x7ff, v5
	v_lshlrev_b32_e32 v5, 9, v5
	v_cmp_lt_i32_e32 vcc, -1, v2
	v_readfirstlane_b32 s14, v153
	v_mov_b32_e32 v7, v131
	v_cndmask_b32_e32 v2, 0, v5, vcc
	v_lshl_add_u32 v2, v3, 20, v2
	v_or_b32_e32 v10, v2, v141
	v_add_u32_e32 v2, s4, v148
	v_min_i32_e32 v2, 0x5ff, v2
	v_lshl_or_b32 v12, v2, 9, v141
	v_add_u32_e32 v2, s5, v151
	v_ashrrev_i32_e32 v3, 31, v2
	v_lshrrev_b32_e32 v3, 28, v3
	v_add_u32_e32 v3, v2, v3
	v_ashrrev_i32_e32 v3, 4, v3
	v_lshlrev_b32_e32 v5, 11, v3
	v_lshlrev_b32_e32 v2, 7, v2
	v_sub_u32_e32 v2, v2, v5
	v_or_b32_e32 v5, v2, v152
	v_min_i32_e32 v5, 0x7ff, v5
	v_lshlrev_b32_e32 v5, 9, v5
	v_cmp_lt_i32_e32 vcc, -1, v2
	v_readfirstlane_b32 s15, v154
	v_lshl_add_u64 v[6:7], v[6:7], 1, s[24:25]
	v_cndmask_b32_e32 v2, 0, v5, vcc
	v_lshl_add_u32 v2, v3, 20, v2
	v_or_b32_e32 v14, v2, v141
	v_add_u32_e32 v2, s4, v150
	v_min_i32_e32 v2, 0x5ff, v2
	v_lshl_or_b32 v16, v2, 9, v141
	v_lshl_add_u64 v[2:3], v[130:131], 1, s[24:25]
	v_mov_b32_e32 v5, v131
	global_load_lds_dwordx4 v[2:3], off
	v_lshl_add_u64 v[4:5], v[4:5], 1, s[26:27]
	s_mov_b32 m0, s14
	v_mov_b32_e32 v9, v131
	global_load_lds_dwordx4 v[4:5], off
	s_mov_b32 m0, s15
	v_readfirstlane_b32 s16, v155
	global_load_lds_dwordx4 v[6:7], off
	v_lshl_add_u64 v[8:9], v[8:9], 1, s[26:27]
	s_mov_b32 m0, s16
	v_mov_b32_e32 v11, v131
	v_readfirstlane_b32 s17, v156
	global_load_lds_dwordx4 v[8:9], off
	v_lshl_add_u64 v[10:11], v[10:11], 1, s[24:25]
	s_mov_b32 m0, s17
	v_mov_b32_e32 v13, v131
	v_readfirstlane_b32 s18, v157
	global_load_lds_dwordx4 v[10:11], off
	v_lshl_add_u64 v[12:13], v[12:13], 1, s[26:27]
	s_mov_b32 m0, s18
	v_mov_b32_e32 v15, v131
	v_readfirstlane_b32 s19, v158
	global_load_lds_dwordx4 v[12:13], off
	v_lshl_add_u64 v[14:15], v[14:15], 1, s[24:25]
	s_mov_b32 m0, s19
	v_mov_b32_e32 v17, v131
	v_readfirstlane_b32 s45, v159
	global_load_lds_dwordx4 v[14:15], off
	v_lshl_add_u64 v[16:17], v[16:17], 1, s[26:27]
	s_mov_b32 m0, s45
	v_readfirstlane_b32 s13, v160
	global_load_lds_dwordx4 v[16:17], off
	s_waitcnt vmcnt(0)
	s_barrier
	v_lshl_add_u64 v[18:19], v[2:3], 0, s[28:29]
	s_mov_b32 m0, s13
	v_readfirstlane_b32 s8, v161
	global_load_lds_dwordx4 v[18:19], off
	v_lshl_add_u64 v[18:19], v[4:5], 0, s[28:29]
	s_mov_b32 m0, s8
	v_readfirstlane_b32 s7, v162
	global_load_lds_dwordx4 v[18:19], off
	v_lshl_add_u64 v[18:19], v[6:7], 0, s[28:29]
	s_mov_b32 m0, s7
	v_readfirstlane_b32 s6, v163
	global_load_lds_dwordx4 v[18:19], off
	v_lshl_add_u64 v[18:19], v[8:9], 0, s[28:29]
	s_mov_b32 m0, s6
	v_readfirstlane_b32 s9, v164
	global_load_lds_dwordx4 v[18:19], off
	v_lshl_add_u64 v[18:19], v[10:11], 0, s[28:29]
	s_mov_b32 m0, s9
	v_readfirstlane_b32 s10, v165
	global_load_lds_dwordx4 v[18:19], off
	v_lshl_add_u64 v[18:19], v[12:13], 0, s[28:29]
	s_mov_b32 m0, s10
	v_readfirstlane_b32 s11, v166
	global_load_lds_dwordx4 v[18:19], off
	v_lshl_add_u64 v[18:19], v[14:15], 0, s[28:29]
	s_mov_b32 m0, s11
	v_readfirstlane_b32 s12, v167
	global_load_lds_dwordx4 v[18:19], off
	v_lshl_add_u64 v[18:19], v[16:17], 0, s[28:29]
	s_mov_b32 m0, s12
	s_nop 0
	global_load_lds_dwordx4 v[18:19], off
	ds_read_b128 v[18:21], v168
	ds_read_b128 v[22:25], v168 offset:2048
	ds_read_b128 v[26:29], v168 offset:4096
	ds_read_b128 v[30:33], v168 offset:6144
	ds_read_b128 v[34:37], v169 offset:32768
	ds_read_b128 v[38:41], v169 offset:34816
	ds_read_b128 v[42:45], v169 offset:36864
	ds_read_b128 v[46:49], v169 offset:38912
	ds_read_b128 v[74:77], v169 offset:40960
	ds_read_b128 v[78:81], v169 offset:43008
	s_waitcnt lgkmcnt(0)
; template <bool SWAP, class Epi, bool THIN = false> ...
;     ...
;       bf16x8 afA[4], afB[4], bfb[2][2];
; #pragma unroll
;       for (int m = 0; m < 4; ++m) afA[m] = *(const bf16x8*)(sa + m * 2048 + ((fq ^ swz) << 4));
; #pragma unroll
;       for (int n = 0; n < 2; ++n) bfb[0][n] = *(const bf16x8*)(sb + n * 2048 + ((fq ^ swz) << 4));
; #pragma unroll
;       for (int gq = 0; gq < 8; ++gq) {
;         const int ks = gq >> 2, nh = gq & 3;
;         if (gq < 7) {
;           const int ks2 = (gq + 1) >> 2, nh2 = (gq + 1) & 3;
; #pragma unroll
;           for (int n = 0; n < 2; ++n) bfb[(gq + 1) & 1][n] = *(const bf16x8*)(sb + (nh2 * 2 + n) * 2048 + (((ks2 * 4 + fq) ^ swz) << 4));
;         }
;         if (gq == 3) {
; #pragma unroll
;           for (int m = 0; m < 4; ++m) afB[m] = *(const bf16x8*)(sa + m * 2048 + (((4 + fq) ^ swz) << 4));
;         }
;         __builtin_amdgcn_sched_barrier(0);
; #pragma unroll
;         for (int m = 0; m < 4; ++m)
; #pragma unroll
;           for (int n = 0; n < 2; ++n) {
;             const bf16x8 av = ks ? afB[m] : afA[m];
;             acc[m][nh * 2 + n] = SWAP ? __builtin_amdgcn_mfma_f32_16x16x32_bf16(bfb[gq & 1][n], av, acc[m][nh * 2 + n], 0, 0, 0)
;                                       : __builtin_amdgcn_mfma_f32_16x16x32_bf16(av, bfb[gq & 1][n], acc[m][nh * 2 + n], 0, 0, 0);
;           }
;       }
	v_mfma_f32_16x16x32_bf16 v[50:53], v[34:37], v[18:21], 0
	v_mfma_f32_16x16x32_bf16 v[54:57], v[38:41], v[18:21], 0
	v_mfma_f32_16x16x32_bf16 v[58:61], v[34:37], v[22:25], 0
	v_mfma_f32_16x16x32_bf16 v[62:65], v[38:41], v[22:25], 0
	v_mfma_f32_16x16x32_bf16 v[66:69], v[34:37], v[26:29], 0
	v_mfma_f32_16x16x32_bf16 v[70:73], v[38:41], v[26:29], 0
	v_mfma_f32_16x16x32_bf16 v[34:37], v[34:37], v[30:33], 0
	v_mfma_f32_16x16x32_bf16 v[38:41], v[38:41], v[30:33], 0
	ds_read_b128 v[106:109], v169 offset:45056
	ds_read_b128 v[110:113], v169 offset:47104
	v_mfma_f32_16x16x32_bf16 v[82:85], v[42:45], v[18:21], 0
	v_mfma_f32_16x16x32_bf16 v[86:89], v[46:49], v[18:21], 0
	v_mfma_f32_16x16x32_bf16 v[90:93], v[42:45], v[22:25], 0
	v_mfma_f32_16x16x32_bf16 v[94:97], v[46:49], v[22:25], 0
	v_mfma_f32_16x16x32_bf16 v[98:101], v[42:45], v[26:29], 0
	v_mfma_f32_16x16x32_bf16 v[102:105], v[46:49], v[26:29], 0
	v_mfma_f32_16x16x32_bf16 v[42:45], v[42:45], v[30:33], 0
	v_mfma_f32_16x16x32_bf16 v[46:49], v[46:49], v[30:33], 0
	ds_read_b128 v[178:181], v170 offset:32768
	ds_read_b128 v[182:185], v170 offset:34816
	ds_read_b128 v[186:189], v171
	ds_read_b128 v[190:193], v171 offset:2048
	ds_read_b128 v[194:197], v171 offset:4096
	ds_read_b128 v[198:201], v171 offset:6144
	v_mfma_f32_16x16x32_bf16 v[114:117], v[74:77], v[18:21], 0
	v_mfma_f32_16x16x32_bf16 v[118:121], v[78:81], v[18:21], 0
	v_mfma_f32_16x16x32_bf16 v[122:125], v[74:77], v[22:25], 0
	v_mfma_f32_16x16x32_bf16 v[126:129], v[78:81], v[22:25], 0
	v_mfma_f32_16x16x32_bf16 v[132:135], v[74:77], v[26:29], 0
	v_mfma_f32_16x16x32_bf16 v[136:139], v[78:81], v[26:29], 0
	v_mfma_f32_16x16x32_bf16 v[74:77], v[74:77], v[30:33], 0
	v_mfma_f32_16x16x32_bf16 v[78:81], v[78:81], v[30:33], 0
	ds_read_b128 v[214:217], v170 offset:36864
	ds_read_b128 v[218:221], v170 offset:38912
	s_waitcnt lgkmcnt(0)
	v_mfma_f32_16x16x32_bf16 v[202:205], v[106:109], v[18:21], 0
	v_mfma_f32_16x16x32_bf16 v[18:21], v[110:113], v[18:21], 0
	v_mfma_f32_16x16x32_bf16 v[206:209], v[106:109], v[22:25], 0
	v_mfma_f32_16x16x32_bf16 v[22:25], v[110:113], v[22:25], 0
	v_mfma_f32_16x16x32_bf16 v[210:213], v[106:109], v[26:29], 0
	v_mfma_f32_16x16x32_bf16 v[26:29], v[110:113], v[26:29], 0
	v_mfma_f32_16x16x32_bf16 v[106:109], v[106:109], v[30:33], 0
	v_mfma_f32_16x16x32_bf16 v[30:33], v[110:113], v[30:33], 0
	v_mfma_f32_16x16x32_bf16 v[50:53], v[178:181], v[186:189], v[50:53]
	v_mfma_f32_16x16x32_bf16 v[58:61], v[178:181], v[190:193], v[58:61]
	v_mfma_f32_16x16x32_bf16 v[66:69], v[178:181], v[194:197], v[66:69]
	v_mfma_f32_16x16x32_bf16 v[34:37], v[178:181], v[198:201], v[34:37]
	ds_read_b128 v[110:113], v170 offset:40960
	ds_read_b128 v[178:181], v170 offset:43008
	v_mfma_f32_16x16x32_bf16 v[54:57], v[182:185], v[186:189], v[54:57]
	v_mfma_f32_16x16x32_bf16 v[62:65], v[182:185], v[190:193], v[62:65]
	v_mfma_f32_16x16x32_bf16 v[70:73], v[182:185], v[194:197], v[70:73]
	v_mfma_f32_16x16x32_bf16 v[38:41], v[182:185], v[198:201], v[38:41]
	v_mfma_f32_16x16x32_bf16 v[82:85], v[214:217], v[186:189], v[82:85]
	v_mfma_f32_16x16x32_bf16 v[90:93], v[214:217], v[190:193], v[90:93]
	v_mfma_f32_16x16x32_bf16 v[98:101], v[214:217], v[194:197], v[98:101]
	v_mfma_f32_16x16x32_bf16 v[42:45], v[214:217], v[198:201], v[42:45]
	ds_read_b128 v[182:185], v170 offset:45056
	ds_read_b128 v[214:217], v170 offset:47104
	v_mfma_f32_16x16x32_bf16 v[86:89], v[218:221], v[186:189], v[86:89]
	v_mfma_f32_16x16x32_bf16 v[94:97], v[218:221], v[190:193], v[94:97]
	v_mfma_f32_16x16x32_bf16 v[102:105], v[218:221], v[194:197], v[102:105]
	v_mfma_f32_16x16x32_bf16 v[46:49], v[218:221], v[198:201], v[46:49]
	s_waitcnt lgkmcnt(0)
	v_mfma_f32_16x16x32_bf16 v[114:117], v[110:113], v[186:189], v[114:117]
	v_mfma_f32_16x16x32_bf16 v[118:121], v[178:181], v[186:189], v[118:121]
	v_mfma_f32_16x16x32_bf16 v[122:125], v[110:113], v[190:193], v[122:125]
	v_mfma_f32_16x16x32_bf16 v[126:129], v[178:181], v[190:193], v[126:129]
	v_mfma_f32_16x16x32_bf16 v[132:135], v[110:113], v[194:197], v[132:135]
	v_mfma_f32_16x16x32_bf16 v[136:139], v[178:181], v[194:197], v[136:139]
	v_mfma_f32_16x16x32_bf16 v[74:77], v[110:113], v[198:201], v[74:77]
	v_mfma_f32_16x16x32_bf16 v[78:81], v[178:181], v[198:201], v[78:81]
	s_mov_b32 m0, s44
	v_mfma_f32_16x16x32_bf16 v[110:113], v[182:185], v[186:189], v[202:205]
	s_waitcnt vmcnt(0)
	s_barrier
; template <bool SWAP, class Epi, bool THIN = false> ...
;     ...
;     for (int st = 0; st < ns; ++st) {
;       asm volatile("s_waitcnt vmcnt(0)" ::: "memory");
;       __builtin_amdgcn_s_barrier();
;       asm volatile("" ::: "memory");
;       if (st + 1 < ns) {
;         char* nb = smem + ((st + 1) & 1) * 65536;
;         const int ko = (st + 1) * 64;
; #pragma unroll
;         for (int i = 0; i < 4; ++i) { GLDS16(A + (size_t)(ap[i] + ko), nb + tid * 16 + i * 8192); GLDS16(Bt + (size_t)(bp[i] + ko), nb + 32768 + tid * 16 + i * 8192); }
;       }
;       const char* sa = smem + (st & 1) * 65536 + (wr * 64 + fr) * 128;
;       const char* sb = smem + (st & 1) * 65536 + 32768 + (wc * 128 + fr) * 128;
;       if constexpr (THIN) {
;         if (wc == 0) {
; #pragma unroll
;           for (int ks = 0; ks < 2; ++ks) {
;             bf16x8 af[4], bf[2];
; #pragma unroll
;             for (int m = 0; m < 4; ++m) af[m] = *(const bf16x8*)(sa + m * 2048 + (((ks * 4 + fq) ^ swz) << 4));
; #pragma unroll
;             for (int n = 0; n < 2; ++n) bf[n] = *(const bf16x8*)(sb + n * 2048 + (((ks * 4 + fq) ^ swz) << 4));
; #pragma unroll
;             for (int m = 0; m < 4; ++m)
; #pragma unroll
;               for (int n = 0; n < 2; ++n)
;                 acc[m][n] = SWAP ? __builtin_amdgcn_mfma_f32_16x16x32_bf16(bf[n], af[m], acc[m][n], 0, 0, 0)
;                                  : __builtin_amdgcn_mfma_f32_16x16x32_bf16(af[m], bf[n], acc[m][n], 0, 0, 0);
;           }
;         }
;       } else {
;       bf16x8 afA[4], afB[4], bfb[2][2];
; #pragma unroll
;       for (int m = 0; m < 4; ++m) afA[m] = *(const bf16x8*)(sa + m * 2048 + ((fq ^ swz) << 4));
; #pragma unroll
;       for (int n = 0; n < 2; ++n) bfb[0][n] = *(const bf16x8*)(sb + n * 2048 + ((fq ^ swz) << 4));
; #pragma unroll
;       for (int gq = 0; gq < 8; ++gq) {
;         const int ks = gq >> 2, nh = gq & 3;
;         if (gq < 7) {
;           const int ks2 = (gq + 1) >> 2, nh2 = (gq + 1) & 3;
; #pragma unroll
;           for (int n = 0; n < 2; ++n) bfb[(gq + 1) & 1][n] = *(const bf16x8*)(sb + (nh2 * 2 + n) * 2048 + (((ks2 * 4 + fq) ^ swz) << 4));
;         }
;         if (gq == 3) {
; #pragma unroll
;           for (int m = 0; m < 4; ++m) afB[m] = *(const bf16x8*)(sa + m * 2048 + (((4 + fq) ^ swz) << 4));
;         }
;         __builtin_amdgcn_sched_barrier(0);
; #pragma unroll
	v_mfma_f32_16x16x32_bf16 v[18:21], v[214:217], v[186:189], v[18:21]
	v_lshl_add_u64 v[186:187], v[2:3], 0, s[30:31]
	global_load_lds_dwordx4 v[186:187], off
	v_lshl_add_u64 v[186:187], v[4:5], 0, s[30:31]
	s_mov_b32 m0, s14
	v_mfma_f32_16x16x32_bf16 v[178:181], v[182:185], v[190:193], v[206:209]
	global_load_lds_dwordx4 v[186:187], off
	s_mov_b32 m0, s15
	v_mfma_f32_16x16x32_bf16 v[22:25], v[214:217], v[190:193], v[22:25]
	v_lshl_add_u64 v[190:191], v[6:7], 0, s[30:31]
	global_load_lds_dwordx4 v[190:191], off
	v_lshl_add_u64 v[190:191], v[8:9], 0, s[30:31]
	s_mov_b32 m0, s16
	v_mfma_f32_16x16x32_bf16 v[186:189], v[182:185], v[194:197], v[210:213]
	global_load_lds_dwordx4 v[190:191], off
	v_lshl_add_u64 v[190:191], v[10:11], 0, s[30:31]
	s_mov_b32 m0, s17
	v_mfma_f32_16x16x32_bf16 v[26:29], v[214:217], v[194:197], v[26:29]
	global_load_lds_dwordx4 v[190:191], off
	v_lshl_add_u64 v[190:191], v[12:13], 0, s[30:31]
	s_mov_b32 m0, s18
	v_mfma_f32_16x16x32_bf16 v[106:109], v[182:185], v[198:201], v[106:109]
	global_load_lds_dwordx4 v[190:191], off
	v_lshl_add_u64 v[190:191], v[14:15], 0, s[30:31]
	s_mov_b32 m0, s19
	v_mfma_f32_16x16x32_bf16 v[30:33], v[214:217], v[198:201], v[30:33]
	global_load_lds_dwordx4 v[190:191], off
	v_lshl_add_u64 v[190:191], v[16:17], 0, s[30:31]
	s_mov_b32 m0, s45
	s_nop 0
	global_load_lds_dwordx4 v[190:191], off
	ds_read_b128 v[182:185], v172
	ds_read_b128 v[190:193], v172 offset:2048
	ds_read_b128 v[194:197], v172 offset:4096
	ds_read_b128 v[202:205], v172 offset:6144
	ds_read_b128 v[206:209], v173
	ds_read_b128 v[210:213], v173 offset:2048
	ds_read_b128 v[218:221], v173 offset:4096
	ds_read_b128 v[222:225], v173 offset:6144
	s_waitcnt lgkmcnt(0)
	v_mfma_f32_16x16x32_bf16 v[50:53], v[206:209], v[182:185], v[50:53]
	v_mfma_f32_16x16x32_bf16 v[58:61], v[206:209], v[190:193], v[58:61]
	v_mfma_f32_16x16x32_bf16 v[66:69], v[206:209], v[194:197], v[66:69]
	v_mfma_f32_16x16x32_bf16 v[34:37], v[206:209], v[202:205], v[34:37]
	ds_read_b128 v[198:201], v173 offset:8192
	ds_read_b128 v[206:209], v173 offset:10240
	v_mfma_f32_16x16x32_bf16 v[54:57], v[210:213], v[182:185], v[54:57]
	v_mfma_f32_16x16x32_bf16 v[62:65], v[210:213], v[190:193], v[62:65]
	v_mfma_f32_16x16x32_bf16 v[70:73], v[210:213], v[194:197], v[70:73]
	v_mfma_f32_16x16x32_bf16 v[38:41], v[210:213], v[202:205], v[38:41]
	ds_read_b128 v[210:213], v173 offset:12288
	ds_read_b128 v[214:217], v173 offset:14336
	v_mfma_f32_16x16x32_bf16 v[82:85], v[218:221], v[182:185], v[82:85]
	v_mfma_f32_16x16x32_bf16 v[86:89], v[222:225], v[182:185], v[86:89]
	v_mfma_f32_16x16x32_bf16 v[90:93], v[218:221], v[190:193], v[90:93]
	v_mfma_f32_16x16x32_bf16 v[94:97], v[222:225], v[190:193], v[94:97]
	v_mfma_f32_16x16x32_bf16 v[98:101], v[218:221], v[194:197], v[98:101]
	v_mfma_f32_16x16x32_bf16 v[102:105], v[222:225], v[194:197], v[102:105]
	v_mfma_f32_16x16x32_bf16 v[42:45], v[218:221], v[202:205], v[42:45]
	v_mfma_f32_16x16x32_bf16 v[46:49], v[222:225], v[202:205], v[46:49]
	s_waitcnt lgkmcnt(0)
	v_mfma_f32_16x16x32_bf16 v[114:117], v[198:201], v[182:185], v[114:117]
	ds_read_b128 v[218:221], v174
	ds_read_b128 v[222:225], v174 offset:2048
	v_mfma_f32_16x16x32_bf16 v[122:125], v[198:201], v[190:193], v[122:125]
	v_mfma_f32_16x16x32_bf16 v[132:135], v[198:201], v[194:197], v[132:135]
	v_mfma_f32_16x16x32_bf16 v[74:77], v[198:201], v[202:205], v[74:77]
	ds_read_b128 v[198:201], v175
	ds_read_b128 v[226:229], v175 offset:2048
	ds_read_b128 v[230:233], v175 offset:4096
	ds_read_b128 v[234:237], v175 offset:6144
	v_mfma_f32_16x16x32_bf16 v[118:121], v[206:209], v[182:185], v[118:121]
	v_mfma_f32_16x16x32_bf16 v[126:129], v[206:209], v[190:193], v[126:129]
	v_mfma_f32_16x16x32_bf16 v[136:139], v[206:209], v[194:197], v[136:139]
	v_mfma_f32_16x16x32_bf16 v[78:81], v[206:209], v[202:205], v[78:81]
	v_mfma_f32_16x16x32_bf16 v[110:113], v[210:213], v[182:185], v[110:113]
	v_mfma_f32_16x16x32_bf16 v[18:21], v[214:217], v[182:185], v[18:21]
	v_mfma_f32_16x16x32_bf16 v[178:181], v[210:213], v[190:193], v[178:181]
	v_mfma_f32_16x16x32_bf16 v[22:25], v[214:217], v[190:193], v[22:25]
	v_mfma_f32_16x16x32_bf16 v[182:185], v[210:213], v[194:197], v[186:189]
	s_nop 2
	ds_read_b128 v[186:189], v174 offset:4096
	ds_read_b128 v[190:193], v174 offset:6144
	v_mfma_f32_16x16x32_bf16 v[26:29], v[214:217], v[194:197], v[26:29]
	v_mfma_f32_16x16x32_bf16 v[106:109], v[210:213], v[202:205], v[106:109]
	v_mfma_f32_16x16x32_bf16 v[30:33], v[214:217], v[202:205], v[30:33]
	ds_read_b128 v[194:197], v174 offset:8192
	ds_read_b128 v[202:205], v174 offset:10240
	s_waitcnt lgkmcnt(0)
	v_mfma_f32_16x16x32_bf16 v[50:53], v[218:221], v[198:201], v[50:53]
	v_mfma_f32_16x16x32_bf16 v[54:57], v[222:225], v[198:201], v[54:57]
	v_mfma_f32_16x16x32_bf16 v[58:61], v[218:221], v[226:229], v[58:61]
	v_mfma_f32_16x16x32_bf16 v[62:65], v[222:225], v[226:229], v[62:65]
	v_mfma_f32_16x16x32_bf16 v[66:69], v[218:221], v[230:233], v[66:69]
	v_mfma_f32_16x16x32_bf16 v[70:73], v[222:225], v[230:233], v[70:73]
	v_mfma_f32_16x16x32_bf16 v[34:37], v[218:221], v[234:237], v[34:37]
	v_mfma_f32_16x16x32_bf16 v[38:41], v[222:225], v[234:237], v[38:41]
	v_mfma_f32_16x16x32_bf16 v[82:85], v[186:189], v[198:201], v[82:85]
	v_mfma_f32_16x16x32_bf16 v[90:93], v[186:189], v[226:229], v[90:93]
	v_mfma_f32_16x16x32_bf16 v[98:101], v[186:189], v[230:233], v[98:101]
	v_mfma_f32_16x16x32_bf16 v[42:45], v[186:189], v[234:237], v[42:45]
	ds_read_b128 v[186:189], v174 offset:12288
	ds_read_b128 v[206:209], v174 offset:14336
	v_mfma_f32_16x16x32_bf16 v[86:89], v[190:193], v[198:201], v[86:89]
	v_mfma_f32_16x16x32_bf16 v[94:97], v[190:193], v[226:229], v[94:97]
	v_mfma_f32_16x16x32_bf16 v[102:105], v[190:193], v[230:233], v[102:105]
	v_mfma_f32_16x16x32_bf16 v[46:49], v[190:193], v[234:237], v[46:49]
	v_mfma_f32_16x16x32_bf16 v[114:117], v[194:197], v[198:201], v[114:117]
	v_mfma_f32_16x16x32_bf16 v[118:121], v[202:205], v[198:201], v[118:121]
	v_mfma_f32_16x16x32_bf16 v[122:125], v[194:197], v[226:229], v[122:125]
	v_mfma_f32_16x16x32_bf16 v[126:129], v[202:205], v[226:229], v[126:129]
	v_mfma_f32_16x16x32_bf16 v[132:135], v[194:197], v[230:233], v[132:135]
	v_mfma_f32_16x16x32_bf16 v[136:139], v[202:205], v[230:233], v[136:139]
	v_mfma_f32_16x16x32_bf16 v[74:77], v[194:197], v[234:237], v[74:77]
	v_mfma_f32_16x16x32_bf16 v[78:81], v[202:205], v[234:237], v[78:81]
	s_mov_b32 m0, s13
	s_waitcnt vmcnt(0)
	s_barrier
; template <bool SWAP, class Epi, bool THIN = false> ...
;     ...
;     for (int st = 0; st < ns; ++st) {
;       asm volatile("s_waitcnt vmcnt(0)" ::: "memory");
;       __builtin_amdgcn_s_barrier();
;       asm volatile("" ::: "memory");
;       if (st + 1 < ns) {
;         char* nb = smem + ((st + 1) & 1) * 65536;
;         const int ko = (st + 1) * 64;
; #pragma unroll
;         for (int i = 0; i < 4; ++i) { GLDS16(A + (size_t)(ap[i] + ko), nb + tid * 16 + i * 8192); GLDS16(Bt + (size_t)(bp[i] + ko), nb + 32768 + tid * 16 + i * 8192); }
;       }
;       const char* sa = smem + (st & 1) * 65536 + (wr * 64 + fr) * 128;
;       const char* sb = smem + (st & 1) * 65536 + 32768 + (wc * 128 + fr) * 128;
;       if constexpr (THIN) {
;         if (wc == 0) {
; #pragma unroll
;           for (int ks = 0; ks < 2; ++ks) {
;             bf16x8 af[4], bf[2];
; #pragma unroll
;             for (int m = 0; m < 4; ++m) af[m] = *(const bf16x8*)(sa + m * 2048 + (((ks * 4 + fq) ^ swz) << 4));
; #pragma unroll
;             for (int n = 0; n < 2; ++n) bf[n] = *(const bf16x8*)(sb + n * 2048 + (((ks * 4 + fq) ^ swz) << 4));
; #pragma unroll
;             for (int m = 0; m < 4; ++m)
; #pragma unroll
;               for (int n = 0; n < 2; ++n)
;                 acc[m][n] = SWAP ? __builtin_amdgcn_mfma_f32_16x16x32_bf16(bf[n], af[m], acc[m][n], 0, 0, 0)
;                                  : __builtin_amdgcn_mfma_f32_16x16x32_bf16(af[m], bf[n], acc[m][n], 0, 0, 0);
;           }
;         }
;       } else {
;       bf16x8 afA[4], afB[4], bfb[2][2];
; #pragma unroll
;       for (int m = 0; m < 4; ++m) afA[m] = *(const bf16x8*)(sa + m * 2048 + ((fq ^ swz) << 4));
; #pragma unroll
;       for (int n = 0; n < 2; ++n) bfb[0][n] = *(const bf16x8*)(sb + n * 2048 + ((fq ^ swz) << 4));
; #pragma unroll
;       for (int gq = 0; gq < 8; ++gq) {
;         const int ks = gq >> 2, nh = gq & 3;
;         if (gq < 7) {
;           const int ks2 = (gq + 1) >> 2, nh2 = (gq + 1) & 3;
; #pragma unroll
;           for (int n = 0; n < 2; ++n) bfb[(gq + 1) & 1][n] = *(const bf16x8*)(sb + (nh2 * 2 + n) * 2048 + (((ks2 * 4 + fq) ^ swz) << 4));
;         }
;         if (gq == 3) {
; #pragma unroll
;           for (int m = 0; m < 4; ++m) afB[m] = *(const bf16x8*)(sa + m * 2048 + (((4 + fq) ^ swz) << 4));
;         }
;         __builtin_amdgcn_sched_barrier(0);
; #pragma unroll
	v_lshl_add_u64 v[190:191], v[2:3], 0, s[34:35]
	global_load_lds_dwordx4 v[190:191], off
	v_lshl_add_u64 v[190:191], v[4:5], 0, s[34:35]
	s_mov_b32 m0, s8
	s_waitcnt lgkmcnt(0)
	v_mfma_f32_16x16x32_bf16 v[110:113], v[186:189], v[198:201], v[110:113]
	global_load_lds_dwordx4 v[190:191], off
	v_lshl_add_u64 v[190:191], v[6:7], 0, s[34:35]
	s_mov_b32 m0, s7
	v_mfma_f32_16x16x32_bf16 v[18:21], v[206:209], v[198:201], v[18:21]
	global_load_lds_dwordx4 v[190:191], off
	v_lshl_add_u64 v[190:191], v[8:9], 0, s[34:35]
	s_mov_b32 m0, s6
	v_mfma_f32_16x16x32_bf16 v[178:181], v[186:189], v[226:229], v[178:181]
	global_load_lds_dwordx4 v[190:191], off
	v_lshl_add_u64 v[190:191], v[10:11], 0, s[34:35]
	s_mov_b32 m0, s9
	v_mfma_f32_16x16x32_bf16 v[182:185], v[186:189], v[230:233], v[182:185]
	global_load_lds_dwordx4 v[190:191], off
	v_lshl_add_u64 v[190:191], v[12:13], 0, s[34:35]
	s_mov_b32 m0, s10
	v_mfma_f32_16x16x32_bf16 v[106:109], v[186:189], v[234:237], v[106:109]
	global_load_lds_dwordx4 v[190:191], off
	v_lshl_add_u64 v[190:191], v[14:15], 0, s[34:35]
	s_mov_b32 m0, s11
	v_mfma_f32_16x16x32_bf16 v[22:25], v[206:209], v[226:229], v[22:25]
	global_load_lds_dwordx4 v[190:191], off
	v_lshl_add_u64 v[190:191], v[16:17], 0, s[34:35]
	s_mov_b32 m0, s12
	v_mfma_f32_16x16x32_bf16 v[26:29], v[206:209], v[230:233], v[26:29]
	global_load_lds_dwordx4 v[190:191], off
	ds_read_b128 v[186:189], v168
	ds_read_b128 v[190:193], v168 offset:2048
	ds_read_b128 v[194:197], v168 offset:4096
	ds_read_b128 v[198:201], v168 offset:6144
	ds_read_b128 v[202:205], v169 offset:32768
	ds_read_b128 v[210:213], v169 offset:34816
	ds_read_b128 v[214:217], v169 offset:36864
	ds_read_b128 v[218:221], v169 offset:38912
	v_mfma_f32_16x16x32_bf16 v[30:33], v[206:209], v[234:237], v[30:33]
	s_waitcnt lgkmcnt(0)
	v_mfma_f32_16x16x32_bf16 v[50:53], v[202:205], v[186:189], v[50:53]
	v_mfma_f32_16x16x32_bf16 v[58:61], v[202:205], v[190:193], v[58:61]
	v_mfma_f32_16x16x32_bf16 v[66:69], v[202:205], v[194:197], v[66:69]
	v_mfma_f32_16x16x32_bf16 v[34:37], v[202:205], v[198:201], v[34:37]
	ds_read_b128 v[202:205], v169 offset:40960
	ds_read_b128 v[206:209], v169 offset:43008
	v_mfma_f32_16x16x32_bf16 v[54:57], v[210:213], v[186:189], v[54:57]
	v_mfma_f32_16x16x32_bf16 v[62:65], v[210:213], v[190:193], v[62:65]
	v_mfma_f32_16x16x32_bf16 v[70:73], v[210:213], v[194:197], v[70:73]
	v_mfma_f32_16x16x32_bf16 v[38:41], v[210:213], v[198:201], v[38:41]
	v_mfma_f32_16x16x32_bf16 v[82:85], v[214:217], v[186:189], v[82:85]
	v_mfma_f32_16x16x32_bf16 v[90:93], v[214:217], v[190:193], v[90:93]
	v_mfma_f32_16x16x32_bf16 v[98:101], v[214:217], v[194:197], v[98:101]
	v_mfma_f32_16x16x32_bf16 v[42:45], v[214:217], v[198:201], v[42:45]
	ds_read_b128 v[210:213], v169 offset:45056
	ds_read_b128 v[214:217], v169 offset:47104
	v_mfma_f32_16x16x32_bf16 v[86:89], v[218:221], v[186:189], v[86:89]
	v_mfma_f32_16x16x32_bf16 v[94:97], v[218:221], v[190:193], v[94:97]
	v_mfma_f32_16x16x32_bf16 v[102:105], v[218:221], v[194:197], v[102:105]
	v_mfma_f32_16x16x32_bf16 v[46:49], v[218:221], v[198:201], v[46:49]
	s_waitcnt lgkmcnt(0)
	v_mfma_f32_16x16x32_bf16 v[114:117], v[202:205], v[186:189], v[114:117]
	ds_read_b128 v[218:221], v170 offset:32768
	ds_read_b128 v[222:225], v170 offset:34816
	v_mfma_f32_16x16x32_bf16 v[122:125], v[202:205], v[190:193], v[122:125]
	v_mfma_f32_16x16x32_bf16 v[132:135], v[202:205], v[194:197], v[132:135]
	v_mfma_f32_16x16x32_bf16 v[74:77], v[202:205], v[198:201], v[74:77]
	ds_read_b128 v[202:205], v171
	ds_read_b128 v[226:229], v171 offset:2048
	ds_read_b128 v[230:233], v171 offset:4096
	ds_read_b128 v[234:237], v171 offset:6144
	v_mfma_f32_16x16x32_bf16 v[118:121], v[206:209], v[186:189], v[118:121]
	v_mfma_f32_16x16x32_bf16 v[126:129], v[206:209], v[190:193], v[126:129]
	v_mfma_f32_16x16x32_bf16 v[136:139], v[206:209], v[194:197], v[136:139]
	v_mfma_f32_16x16x32_bf16 v[78:81], v[206:209], v[198:201], v[78:81]
	v_mfma_f32_16x16x32_bf16 v[110:113], v[210:213], v[186:189], v[110:113]
	v_mfma_f32_16x16x32_bf16 v[18:21], v[214:217], v[186:189], v[18:21]
	v_mfma_f32_16x16x32_bf16 v[178:181], v[210:213], v[190:193], v[178:181]
	v_mfma_f32_16x16x32_bf16 v[22:25], v[214:217], v[190:193], v[22:25]
	ds_read_b128 v[186:189], v170 offset:36864
	ds_read_b128 v[190:193], v170 offset:38912
	v_mfma_f32_16x16x32_bf16 v[26:29], v[214:217], v[194:197], v[26:29]
	v_mfma_f32_16x16x32_bf16 v[106:109], v[210:213], v[198:201], v[106:109]
	v_mfma_f32_16x16x32_bf16 v[30:33], v[214:217], v[198:201], v[30:33]
	v_mfma_f32_16x16x32_bf16 v[182:185], v[210:213], v[194:197], v[182:185]
	ds_read_b128 v[194:197], v170 offset:40960
	ds_read_b128 v[198:201], v170 offset:43008
	s_waitcnt lgkmcnt(0)
	v_mfma_f32_16x16x32_bf16 v[50:53], v[218:221], v[202:205], v[50:53]
	v_mfma_f32_16x16x32_bf16 v[54:57], v[222:225], v[202:205], v[54:57]
	v_mfma_f32_16x16x32_bf16 v[58:61], v[218:221], v[226:229], v[58:61]
	v_mfma_f32_16x16x32_bf16 v[62:65], v[222:225], v[226:229], v[62:65]
	v_mfma_f32_16x16x32_bf16 v[66:69], v[218:221], v[230:233], v[66:69]
	v_mfma_f32_16x16x32_bf16 v[70:73], v[222:225], v[230:233], v[70:73]
	v_mfma_f32_16x16x32_bf16 v[34:37], v[218:221], v[234:237], v[34:37]
	v_mfma_f32_16x16x32_bf16 v[38:41], v[222:225], v[234:237], v[38:41]
	v_mfma_f32_16x16x32_bf16 v[82:85], v[186:189], v[202:205], v[82:85]
	v_mfma_f32_16x16x32_bf16 v[90:93], v[186:189], v[226:229], v[90:93]
	v_mfma_f32_16x16x32_bf16 v[98:101], v[186:189], v[230:233], v[98:101]
	v_mfma_f32_16x16x32_bf16 v[42:45], v[186:189], v[234:237], v[42:45]
	ds_read_b128 v[186:189], v170 offset:45056
	ds_read_b128 v[206:209], v170 offset:47104
	v_mfma_f32_16x16x32_bf16 v[86:89], v[190:193], v[202:205], v[86:89]
	v_mfma_f32_16x16x32_bf16 v[94:97], v[190:193], v[226:229], v[94:97]
	v_mfma_f32_16x16x32_bf16 v[102:105], v[190:193], v[230:233], v[102:105]
	v_mfma_f32_16x16x32_bf16 v[46:49], v[190:193], v[234:237], v[46:49]
	v_mfma_f32_16x16x32_bf16 v[114:117], v[194:197], v[202:205], v[114:117]
	v_mfma_f32_16x16x32_bf16 v[118:121], v[198:201], v[202:205], v[118:121]
	v_mfma_f32_16x16x32_bf16 v[122:125], v[194:197], v[226:229], v[122:125]
	v_mfma_f32_16x16x32_bf16 v[126:129], v[198:201], v[226:229], v[126:129]
	v_mfma_f32_16x16x32_bf16 v[132:135], v[194:197], v[230:233], v[132:135]
	v_mfma_f32_16x16x32_bf16 v[136:139], v[198:201], v[230:233], v[136:139]
	v_mfma_f32_16x16x32_bf16 v[74:77], v[194:197], v[234:237], v[74:77]
	v_mfma_f32_16x16x32_bf16 v[78:81], v[198:201], v[234:237], v[78:81]
	s_mov_b32 m0, s44
	s_waitcnt vmcnt(0)
	s_barrier
; template <bool SWAP, class Epi, bool THIN = false> ...
;     ...
;     for (int st = 0; st < ns; ++st) {
;       asm volatile("s_waitcnt vmcnt(0)" ::: "memory");
;       __builtin_amdgcn_s_barrier();
;       asm volatile("" ::: "memory");
;       if (st + 1 < ns) {
;         char* nb = smem + ((st + 1) & 1) * 65536;
;         const int ko = (st + 1) * 64;
; #pragma unroll
;         for (int i = 0; i < 4; ++i) { GLDS16(A + (size_t)(ap[i] + ko), nb + tid * 16 + i * 8192); GLDS16(Bt + (size_t)(bp[i] + ko), nb + 32768 + tid * 16 + i * 8192); }
;       }
;       const char* sa = smem + (st & 1) * 65536 + (wr * 64 + fr) * 128;
;       const char* sb = smem + (st & 1) * 65536 + 32768 + (wc * 128 + fr) * 128;
;       if constexpr (THIN) {
;         if (wc == 0) {
; #pragma unroll
;           for (int ks = 0; ks < 2; ++ks) {
;             bf16x8 af[4], bf[2];
; #pragma unroll
;             for (int m = 0; m < 4; ++m) af[m] = *(const bf16x8*)(sa + m * 2048 + (((ks * 4 + fq) ^ swz) << 4));
; #pragma unroll
;             for (int n = 0; n < 2; ++n) bf[n] = *(const bf16x8*)(sb + n * 2048 + (((ks * 4 + fq) ^ swz) << 4));
; #pragma unroll
;             for (int m = 0; m < 4; ++m)
; #pragma unroll
;               for (int n = 0; n < 2; ++n)
;                 acc[m][n] = SWAP ? __builtin_amdgcn_mfma_f32_16x16x32_bf16(bf[n], af[m], acc[m][n], 0, 0, 0)
;                                  : __builtin_amdgcn_mfma_f32_16x16x32_bf16(af[m], bf[n], acc[m][n], 0, 0, 0);
;           }
;         }
;       } else {
;       bf16x8 afA[4], afB[4], bfb[2][2];
; #pragma unroll
;       for (int m = 0; m < 4; ++m) afA[m] = *(const bf16x8*)(sa + m * 2048 + ((fq ^ swz) << 4));
; #pragma unroll
;       for (int n = 0; n < 2; ++n) bfb[0][n] = *(const bf16x8*)(sb + n * 2048 + ((fq ^ swz) << 4));
; #pragma unroll
;       for (int gq = 0; gq < 8; ++gq) {
;         const int ks = gq >> 2, nh = gq & 3;
;         if (gq < 7) {
;           const int ks2 = (gq + 1) >> 2, nh2 = (gq + 1) & 3;
; #pragma unroll
;           for (int n = 0; n < 2; ++n) bfb[(gq + 1) & 1][n] = *(const bf16x8*)(sb + (nh2 * 2 + n) * 2048 + (((ks2 * 4 + fq) ^ swz) << 4));
;         }
;         if (gq == 3) {
; #pragma unroll
;           for (int m = 0; m < 4; ++m) afB[m] = *(const bf16x8*)(sa + m * 2048 + (((4 + fq) ^ swz) << 4));
;         }
;         __builtin_amdgcn_sched_barrier(0);
; #pragma unroll
	v_lshl_add_u64 v[190:191], v[2:3], 0, s[36:37]
	global_load_lds_dwordx4 v[190:191], off
	v_lshl_add_u64 v[190:191], v[4:5], 0, s[36:37]
	s_mov_b32 m0, s14
	s_waitcnt lgkmcnt(0)
	v_mfma_f32_16x16x32_bf16 v[110:113], v[186:189], v[202:205], v[110:113]
	global_load_lds_dwordx4 v[190:191], off
	v_lshl_add_u64 v[190:191], v[6:7], 0, s[36:37]
	s_mov_b32 m0, s15
	v_mfma_f32_16x16x32_bf16 v[18:21], v[206:209], v[202:205], v[18:21]
	global_load_lds_dwordx4 v[190:191], off
	v_lshl_add_u64 v[190:191], v[8:9], 0, s[36:37]
	s_mov_b32 m0, s16
	v_mfma_f32_16x16x32_bf16 v[178:181], v[186:189], v[226:229], v[178:181]
	global_load_lds_dwordx4 v[190:191], off
	v_lshl_add_u64 v[190:191], v[10:11], 0, s[36:37]
	s_mov_b32 m0, s17
	v_mfma_f32_16x16x32_bf16 v[182:185], v[186:189], v[230:233], v[182:185]
	global_load_lds_dwordx4 v[190:191], off
	v_lshl_add_u64 v[190:191], v[12:13], 0, s[36:37]
	s_mov_b32 m0, s18
	v_mfma_f32_16x16x32_bf16 v[106:109], v[186:189], v[234:237], v[106:109]
	global_load_lds_dwordx4 v[190:191], off
	v_lshl_add_u64 v[190:191], v[14:15], 0, s[36:37]
	s_mov_b32 m0, s19
	v_mfma_f32_16x16x32_bf16 v[22:25], v[206:209], v[226:229], v[22:25]
	global_load_lds_dwordx4 v[190:191], off
	v_lshl_add_u64 v[190:191], v[16:17], 0, s[36:37]
	s_mov_b32 m0, s45
	v_mfma_f32_16x16x32_bf16 v[26:29], v[206:209], v[230:233], v[26:29]
	global_load_lds_dwordx4 v[190:191], off
	ds_read_b128 v[186:189], v172
	ds_read_b128 v[190:193], v172 offset:2048
	ds_read_b128 v[194:197], v172 offset:4096
	ds_read_b128 v[198:201], v172 offset:6144
	ds_read_b128 v[202:205], v173
	ds_read_b128 v[210:213], v173 offset:2048
	ds_read_b128 v[214:217], v173 offset:4096
	ds_read_b128 v[218:221], v173 offset:6144
	v_mfma_f32_16x16x32_bf16 v[30:33], v[206:209], v[234:237], v[30:33]
	s_waitcnt lgkmcnt(0)
	v_mfma_f32_16x16x32_bf16 v[50:53], v[202:205], v[186:189], v[50:53]
	v_mfma_f32_16x16x32_bf16 v[58:61], v[202:205], v[190:193], v[58:61]
	v_mfma_f32_16x16x32_bf16 v[66:69], v[202:205], v[194:197], v[66:69]
	v_mfma_f32_16x16x32_bf16 v[34:37], v[202:205], v[198:201], v[34:37]
	ds_read_b128 v[202:205], v173 offset:8192
	ds_read_b128 v[206:209], v173 offset:10240
	v_mfma_f32_16x16x32_bf16 v[54:57], v[210:213], v[186:189], v[54:57]
	v_mfma_f32_16x16x32_bf16 v[62:65], v[210:213], v[190:193], v[62:65]
	v_mfma_f32_16x16x32_bf16 v[70:73], v[210:213], v[194:197], v[70:73]
	v_mfma_f32_16x16x32_bf16 v[38:41], v[210:213], v[198:201], v[38:41]
	v_mfma_f32_16x16x32_bf16 v[82:85], v[214:217], v[186:189], v[82:85]
	v_mfma_f32_16x16x32_bf16 v[90:93], v[214:217], v[190:193], v[90:93]
	v_mfma_f32_16x16x32_bf16 v[98:101], v[214:217], v[194:197], v[98:101]
	v_mfma_f32_16x16x32_bf16 v[42:45], v[214:217], v[198:201], v[42:45]
	ds_read_b128 v[210:213], v173 offset:12288
	ds_read_b128 v[214:217], v173 offset:14336
	v_mfma_f32_16x16x32_bf16 v[86:89], v[218:221], v[186:189], v[86:89]
	v_mfma_f32_16x16x32_bf16 v[94:97], v[218:221], v[190:193], v[94:97]
	v_mfma_f32_16x16x32_bf16 v[102:105], v[218:221], v[194:197], v[102:105]
	v_mfma_f32_16x16x32_bf16 v[46:49], v[218:221], v[198:201], v[46:49]
	s_waitcnt lgkmcnt(0)
	v_mfma_f32_16x16x32_bf16 v[114:117], v[202:205], v[186:189], v[114:117]
	ds_read_b128 v[218:221], v174
	ds_read_b128 v[222:225], v174 offset:2048
	v_mfma_f32_16x16x32_bf16 v[122:125], v[202:205], v[190:193], v[122:125]
	v_mfma_f32_16x16x32_bf16 v[132:135], v[202:205], v[194:197], v[132:135]
	v_mfma_f32_16x16x32_bf16 v[74:77], v[202:205], v[198:201], v[74:77]
	ds_read_b128 v[202:205], v175
	ds_read_b128 v[226:229], v175 offset:2048
	ds_read_b128 v[230:233], v175 offset:4096
	ds_read_b128 v[234:237], v175 offset:6144
	v_mfma_f32_16x16x32_bf16 v[118:121], v[206:209], v[186:189], v[118:121]
	v_mfma_f32_16x16x32_bf16 v[126:129], v[206:209], v[190:193], v[126:129]
	v_mfma_f32_16x16x32_bf16 v[136:139], v[206:209], v[194:197], v[136:139]
	v_mfma_f32_16x16x32_bf16 v[78:81], v[206:209], v[198:201], v[78:81]
	v_mfma_f32_16x16x32_bf16 v[110:113], v[210:213], v[186:189], v[110:113]
	v_mfma_f32_16x16x32_bf16 v[18:21], v[214:217], v[186:189], v[18:21]
	v_mfma_f32_16x16x32_bf16 v[178:181], v[210:213], v[190:193], v[178:181]
	v_mfma_f32_16x16x32_bf16 v[22:25], v[214:217], v[190:193], v[22:25]
	ds_read_b128 v[186:189], v174 offset:4096
	ds_read_b128 v[190:193], v174 offset:6144
	v_mfma_f32_16x16x32_bf16 v[26:29], v[214:217], v[194:197], v[26:29]
	v_mfma_f32_16x16x32_bf16 v[106:109], v[210:213], v[198:201], v[106:109]
	v_mfma_f32_16x16x32_bf16 v[30:33], v[214:217], v[198:201], v[30:33]
	v_mfma_f32_16x16x32_bf16 v[182:185], v[210:213], v[194:197], v[182:185]
	ds_read_b128 v[194:197], v174 offset:8192
	ds_read_b128 v[198:201], v174 offset:10240
	s_waitcnt lgkmcnt(0)
	v_mfma_f32_16x16x32_bf16 v[50:53], v[218:221], v[202:205], v[50:53]
	v_mfma_f32_16x16x32_bf16 v[54:57], v[222:225], v[202:205], v[54:57]
	v_mfma_f32_16x16x32_bf16 v[58:61], v[218:221], v[226:229], v[58:61]
	v_mfma_f32_16x16x32_bf16 v[62:65], v[222:225], v[226:229], v[62:65]
	v_mfma_f32_16x16x32_bf16 v[66:69], v[218:221], v[230:233], v[66:69]
	v_mfma_f32_16x16x32_bf16 v[70:73], v[222:225], v[230:233], v[70:73]
	v_mfma_f32_16x16x32_bf16 v[34:37], v[218:221], v[234:237], v[34:37]
	v_mfma_f32_16x16x32_bf16 v[38:41], v[222:225], v[234:237], v[38:41]
	v_mfma_f32_16x16x32_bf16 v[82:85], v[186:189], v[202:205], v[82:85]
	v_mfma_f32_16x16x32_bf16 v[90:93], v[186:189], v[226:229], v[90:93]
	v_mfma_f32_16x16x32_bf16 v[98:101], v[186:189], v[230:233], v[98:101]
	v_mfma_f32_16x16x32_bf16 v[42:45], v[186:189], v[234:237], v[42:45]
	ds_read_b128 v[186:189], v174 offset:12288
	ds_read_b128 v[206:209], v174 offset:14336
	v_mfma_f32_16x16x32_bf16 v[86:89], v[190:193], v[202:205], v[86:89]
	v_mfma_f32_16x16x32_bf16 v[94:97], v[190:193], v[226:229], v[94:97]
	v_mfma_f32_16x16x32_bf16 v[102:105], v[190:193], v[230:233], v[102:105]
	v_mfma_f32_16x16x32_bf16 v[46:49], v[190:193], v[234:237], v[46:49]
	v_mfma_f32_16x16x32_bf16 v[114:117], v[194:197], v[202:205], v[114:117]
	v_mfma_f32_16x16x32_bf16 v[118:121], v[198:201], v[202:205], v[118:121]
	v_mfma_f32_16x16x32_bf16 v[122:125], v[194:197], v[226:229], v[122:125]
	v_mfma_f32_16x16x32_bf16 v[126:129], v[198:201], v[226:229], v[126:129]
	v_mfma_f32_16x16x32_bf16 v[132:135], v[194:197], v[230:233], v[132:135]
	v_mfma_f32_16x16x32_bf16 v[136:139], v[198:201], v[230:233], v[136:139]
	v_mfma_f32_16x16x32_bf16 v[74:77], v[194:197], v[234:237], v[74:77]
	v_mfma_f32_16x16x32_bf16 v[78:81], v[198:201], v[234:237], v[78:81]
	s_mov_b32 m0, s13
	s_waitcnt vmcnt(0)
	s_barrier
; template <bool SWAP, class Epi, bool THIN = false> ...
;     ...
;     for (int st = 0; st < ns; ++st) {
;       asm volatile("s_waitcnt vmcnt(0)" ::: "memory");
;       __builtin_amdgcn_s_barrier();
;       asm volatile("" ::: "memory");
;       if (st + 1 < ns) {
;         char* nb = smem + ((st + 1) & 1) * 65536;
;         const int ko = (st + 1) * 64;
; #pragma unroll
;         for (int i = 0; i < 4; ++i) { GLDS16(A + (size_t)(ap[i] + ko), nb + tid * 16 + i * 8192); GLDS16(Bt + (size_t)(bp[i] + ko), nb + 32768 + tid * 16 + i * 8192); }
;       }
;       const char* sa = smem + (st & 1) * 65536 + (wr * 64 + fr) * 128;
;       const char* sb = smem + (st & 1) * 65536 + 32768 + (wc * 128 + fr) * 128;
;       if constexpr (THIN) {
;         if (wc == 0) {
; #pragma unroll
;           for (int ks = 0; ks < 2; ++ks) {
;             bf16x8 af[4], bf[2];
; #pragma unroll
;             for (int m = 0; m < 4; ++m) af[m] = *(const bf16x8*)(sa + m * 2048 + (((ks * 4 + fq) ^ swz) << 4));
; #pragma unroll
;             for (int n = 0; n < 2; ++n) bf[n] = *(const bf16x8*)(sb + n * 2048 + (((ks * 4 + fq) ^ swz) << 4));
; #pragma unroll
;             for (int m = 0; m < 4; ++m)
; #pragma unroll
;               for (int n = 0; n < 2; ++n)
;                 acc[m][n] = SWAP ? __builtin_amdgcn_mfma_f32_16x16x32_bf16(bf[n], af[m], acc[m][n], 0, 0, 0)
;                                  : __builtin_amdgcn_mfma_f32_16x16x32_bf16(af[m], bf[n], acc[m][n], 0, 0, 0);
;           }
;         }
;       } else {
;       bf16x8 afA[4], afB[4], bfb[2][2];
; #pragma unroll
;       for (int m = 0; m < 4; ++m) afA[m] = *(const bf16x8*)(sa + m * 2048 + ((fq ^ swz) << 4));
; #pragma unroll
;       for (int n = 0; n < 2; ++n) bfb[0][n] = *(const bf16x8*)(sb + n * 2048 + ((fq ^ swz) << 4));
; #pragma unroll
;       for (int gq = 0; gq < 8; ++gq) {
;         const int ks = gq >> 2, nh = gq & 3;
;         if (gq < 7) {
;           const int ks2 = (gq + 1) >> 2, nh2 = (gq + 1) & 3;
; #pragma unroll
;           for (int n = 0; n < 2; ++n) bfb[(gq + 1) & 1][n] = *(const bf16x8*)(sb + (nh2 * 2 + n) * 2048 + (((ks2 * 4 + fq) ^ swz) << 4));
;         }
;         if (gq == 3) {
; #pragma unroll
;           for (int m = 0; m < 4; ++m) afB[m] = *(const bf16x8*)(sa + m * 2048 + (((4 + fq) ^ swz) << 4));
;         }
;         __builtin_amdgcn_sched_barrier(0);
; #pragma unroll
	v_lshl_add_u64 v[190:191], v[2:3], 0, s[38:39]
	global_load_lds_dwordx4 v[190:191], off
	v_lshl_add_u64 v[190:191], v[4:5], 0, s[38:39]
	s_mov_b32 m0, s8
	s_waitcnt lgkmcnt(0)
	v_mfma_f32_16x16x32_bf16 v[110:113], v[186:189], v[202:205], v[110:113]
	global_load_lds_dwordx4 v[190:191], off
	v_lshl_add_u64 v[190:191], v[6:7], 0, s[38:39]
	s_mov_b32 m0, s7
	v_mfma_f32_16x16x32_bf16 v[18:21], v[206:209], v[202:205], v[18:21]
	global_load_lds_dwordx4 v[190:191], off
	v_lshl_add_u64 v[190:191], v[8:9], 0, s[38:39]
	s_mov_b32 m0, s6
	v_mfma_f32_16x16x32_bf16 v[178:181], v[186:189], v[226:229], v[178:181]
	global_load_lds_dwordx4 v[190:191], off
	v_lshl_add_u64 v[190:191], v[10:11], 0, s[38:39]
	s_mov_b32 m0, s9
	v_mfma_f32_16x16x32_bf16 v[182:185], v[186:189], v[230:233], v[182:185]
	global_load_lds_dwordx4 v[190:191], off
	v_lshl_add_u64 v[190:191], v[12:13], 0, s[38:39]
	s_mov_b32 m0, s10
	v_mfma_f32_16x16x32_bf16 v[106:109], v[186:189], v[234:237], v[106:109]
	global_load_lds_dwordx4 v[190:191], off
	v_lshl_add_u64 v[190:191], v[14:15], 0, s[38:39]
	s_mov_b32 m0, s11
	v_mfma_f32_16x16x32_bf16 v[22:25], v[206:209], v[226:229], v[22:25]
	global_load_lds_dwordx4 v[190:191], off
	v_lshl_add_u64 v[190:191], v[16:17], 0, s[38:39]
	s_mov_b32 m0, s12
	v_mfma_f32_16x16x32_bf16 v[26:29], v[206:209], v[230:233], v[26:29]
	global_load_lds_dwordx4 v[190:191], off
	ds_read_b128 v[186:189], v168
	ds_read_b128 v[190:193], v168 offset:2048
	ds_read_b128 v[194:197], v168 offset:4096
	ds_read_b128 v[198:201], v168 offset:6144
	ds_read_b128 v[202:205], v169 offset:32768
	ds_read_b128 v[210:213], v169 offset:34816
	ds_read_b128 v[214:217], v169 offset:36864
	ds_read_b128 v[218:221], v169 offset:38912
	v_mfma_f32_16x16x32_bf16 v[30:33], v[206:209], v[234:237], v[30:33]
	s_waitcnt lgkmcnt(0)
	v_mfma_f32_16x16x32_bf16 v[50:53], v[202:205], v[186:189], v[50:53]
	v_mfma_f32_16x16x32_bf16 v[58:61], v[202:205], v[190:193], v[58:61]
	v_mfma_f32_16x16x32_bf16 v[66:69], v[202:205], v[194:197], v[66:69]
	v_mfma_f32_16x16x32_bf16 v[34:37], v[202:205], v[198:201], v[34:37]
	ds_read_b128 v[202:205], v169 offset:40960
	ds_read_b128 v[206:209], v169 offset:43008
	v_mfma_f32_16x16x32_bf16 v[54:57], v[210:213], v[186:189], v[54:57]
	v_mfma_f32_16x16x32_bf16 v[62:65], v[210:213], v[190:193], v[62:65]
	v_mfma_f32_16x16x32_bf16 v[70:73], v[210:213], v[194:197], v[70:73]
	v_mfma_f32_16x16x32_bf16 v[38:41], v[210:213], v[198:201], v[38:41]
	v_mfma_f32_16x16x32_bf16 v[82:85], v[214:217], v[186:189], v[82:85]
	v_mfma_f32_16x16x32_bf16 v[90:93], v[214:217], v[190:193], v[90:93]
	v_mfma_f32_16x16x32_bf16 v[98:101], v[214:217], v[194:197], v[98:101]
	v_mfma_f32_16x16x32_bf16 v[42:45], v[214:217], v[198:201], v[42:45]
	ds_read_b128 v[210:213], v169 offset:45056
	ds_read_b128 v[214:217], v169 offset:47104
	v_mfma_f32_16x16x32_bf16 v[86:89], v[218:221], v[186:189], v[86:89]
	v_mfma_f32_16x16x32_bf16 v[94:97], v[218:221], v[190:193], v[94:97]
	v_mfma_f32_16x16x32_bf16 v[102:105], v[218:221], v[194:197], v[102:105]
	v_mfma_f32_16x16x32_bf16 v[46:49], v[218:221], v[198:201], v[46:49]
	s_waitcnt lgkmcnt(0)
	v_mfma_f32_16x16x32_bf16 v[114:117], v[202:205], v[186:189], v[114:117]
	ds_read_b128 v[218:221], v170 offset:32768
	ds_read_b128 v[222:225], v170 offset:34816
	v_mfma_f32_16x16x32_bf16 v[122:125], v[202:205], v[190:193], v[122:125]
	v_mfma_f32_16x16x32_bf16 v[132:135], v[202:205], v[194:197], v[132:135]
	v_mfma_f32_16x16x32_bf16 v[74:77], v[202:205], v[198:201], v[74:77]
	ds_read_b128 v[202:205], v171
	ds_read_b128 v[226:229], v171 offset:2048
	ds_read_b128 v[230:233], v171 offset:4096
	ds_read_b128 v[234:237], v171 offset:6144
	v_mfma_f32_16x16x32_bf16 v[118:121], v[206:209], v[186:189], v[118:121]
	v_mfma_f32_16x16x32_bf16 v[126:129], v[206:209], v[190:193], v[126:129]
	v_mfma_f32_16x16x32_bf16 v[136:139], v[206:209], v[194:197], v[136:139]
	v_mfma_f32_16x16x32_bf16 v[78:81], v[206:209], v[198:201], v[78:81]
	v_mfma_f32_16x16x32_bf16 v[110:113], v[210:213], v[186:189], v[110:113]
	v_mfma_f32_16x16x32_bf16 v[18:21], v[214:217], v[186:189], v[18:21]
	v_mfma_f32_16x16x32_bf16 v[178:181], v[210:213], v[190:193], v[178:181]
	v_mfma_f32_16x16x32_bf16 v[22:25], v[214:217], v[190:193], v[22:25]
	ds_read_b128 v[186:189], v170 offset:36864
	ds_read_b128 v[190:193], v170 offset:38912
	v_mfma_f32_16x16x32_bf16 v[26:29], v[214:217], v[194:197], v[26:29]
	v_mfma_f32_16x16x32_bf16 v[106:109], v[210:213], v[198:201], v[106:109]
	v_mfma_f32_16x16x32_bf16 v[30:33], v[214:217], v[198:201], v[30:33]
	v_mfma_f32_16x16x32_bf16 v[182:185], v[210:213], v[194:197], v[182:185]
	ds_read_b128 v[194:197], v170 offset:40960
	ds_read_b128 v[198:201], v170 offset:43008
	s_waitcnt lgkmcnt(0)
	v_mfma_f32_16x16x32_bf16 v[50:53], v[218:221], v[202:205], v[50:53]
	v_mfma_f32_16x16x32_bf16 v[54:57], v[222:225], v[202:205], v[54:57]
	v_mfma_f32_16x16x32_bf16 v[58:61], v[218:221], v[226:229], v[58:61]
	v_mfma_f32_16x16x32_bf16 v[62:65], v[222:225], v[226:229], v[62:65]
	v_mfma_f32_16x16x32_bf16 v[66:69], v[218:221], v[230:233], v[66:69]
	v_mfma_f32_16x16x32_bf16 v[70:73], v[222:225], v[230:233], v[70:73]
	v_mfma_f32_16x16x32_bf16 v[34:37], v[218:221], v[234:237], v[34:37]
	v_mfma_f32_16x16x32_bf16 v[38:41], v[222:225], v[234:237], v[38:41]
	v_mfma_f32_16x16x32_bf16 v[82:85], v[186:189], v[202:205], v[82:85]
	v_mfma_f32_16x16x32_bf16 v[90:93], v[186:189], v[226:229], v[90:93]
	v_mfma_f32_16x16x32_bf16 v[98:101], v[186:189], v[230:233], v[98:101]
	v_mfma_f32_16x16x32_bf16 v[42:45], v[186:189], v[234:237], v[42:45]
	ds_read_b128 v[186:189], v170 offset:45056
	ds_read_b128 v[206:209], v170 offset:47104
	v_mfma_f32_16x16x32_bf16 v[86:89], v[190:193], v[202:205], v[86:89]
	v_mfma_f32_16x16x32_bf16 v[94:97], v[190:193], v[226:229], v[94:97]
	v_mfma_f32_16x16x32_bf16 v[102:105], v[190:193], v[230:233], v[102:105]
	v_mfma_f32_16x16x32_bf16 v[46:49], v[190:193], v[234:237], v[46:49]
	v_mfma_f32_16x16x32_bf16 v[114:117], v[194:197], v[202:205], v[114:117]
	v_mfma_f32_16x16x32_bf16 v[118:121], v[198:201], v[202:205], v[118:121]
	v_mfma_f32_16x16x32_bf16 v[122:125], v[194:197], v[226:229], v[122:125]
	v_mfma_f32_16x16x32_bf16 v[126:129], v[198:201], v[226:229], v[126:129]
	v_mfma_f32_16x16x32_bf16 v[132:135], v[194:197], v[230:233], v[132:135]
	v_mfma_f32_16x16x32_bf16 v[136:139], v[198:201], v[230:233], v[136:139]
	v_mfma_f32_16x16x32_bf16 v[74:77], v[194:197], v[234:237], v[74:77]
	v_mfma_f32_16x16x32_bf16 v[78:81], v[198:201], v[234:237], v[78:81]
	v_readfirstlane_b32 s6, v142
	s_waitcnt vmcnt(0)
	s_barrier
; template <bool SWAP, class Epi, bool THIN = false> ...
;     ...
;     for (int st = 0; st < ns; ++st) {
;       asm volatile("s_waitcnt vmcnt(0)" ::: "memory");
;       __builtin_amdgcn_s_barrier();
;       asm volatile("" ::: "memory");
;       if (st + 1 < ns) {
;         char* nb = smem + ((st + 1) & 1) * 65536;
;         const int ko = (st + 1) * 64;
; #pragma unroll
;         for (int i = 0; i < 4; ++i) { GLDS16(A + (size_t)(ap[i] + ko), nb + tid * 16 + i * 8192); GLDS16(Bt + (size_t)(bp[i] + ko), nb + 32768 + tid * 16 + i * 8192); }
;       }
;       const char* sa = smem + (st & 1) * 65536 + (wr * 64 + fr) * 128;
;       const char* sb = smem + (st & 1) * 65536 + 32768 + (wc * 128 + fr) * 128;
;       if constexpr (THIN) {
;         if (wc == 0) {
; #pragma unroll
;           for (int ks = 0; ks < 2; ++ks) {
;             bf16x8 af[4], bf[2];
; #pragma unroll
;             for (int m = 0; m < 4; ++m) af[m] = *(const bf16x8*)(sa + m * 2048 + (((ks * 4 + fq) ^ swz) << 4));
; #pragma unroll
;             for (int n = 0; n < 2; ++n) bf[n] = *(const bf16x8*)(sb + n * 2048 + (((ks * 4 + fq) ^ swz) << 4));
; #pragma unroll
;             for (int m = 0; m < 4; ++m)
; #pragma unroll
;               for (int n = 0; n < 2; ++n)
;                 acc[m][n] = SWAP ? __builtin_amdgcn_mfma_f32_16x16x32_bf16(bf[n], af[m], acc[m][n], 0, 0, 0)
;                                  : __builtin_amdgcn_mfma_f32_16x16x32_bf16(af[m], bf[n], acc[m][n], 0, 0, 0);
;           }
;         }
;       } else {
;       bf16x8 afA[4], afB[4], bfb[2][2];
; #pragma unroll
;       for (int m = 0; m < 4; ++m) afA[m] = *(const bf16x8*)(sa + m * 2048 + ((fq ^ swz) << 4));
; #pragma unroll
;       for (int n = 0; n < 2; ++n) bfb[0][n] = *(const bf16x8*)(sb + n * 2048 + ((fq ^ swz) << 4));
; #pragma unroll
;       for (int gq = 0; gq < 8; ++gq) {
;         const int ks = gq >> 2, nh = gq & 3;
;         if (gq < 7) {
;           const int ks2 = (gq + 1) >> 2, nh2 = (gq + 1) & 3;
; #pragma unroll
;           for (int n = 0; n < 2; ++n) bfb[(gq + 1) & 1][n] = *(const bf16x8*)(sb + (nh2 * 2 + n) * 2048 + (((ks2 * 4 + fq) ^ swz) << 4));
;         }
;         if (gq == 3) {
; #pragma unroll
;           for (int m = 0; m < 4; ++m) afB[m] = *(const bf16x8*)(sa + m * 2048 + (((4 + fq) ^ swz) << 4));
;         }
;         __builtin_amdgcn_sched_barrier(0);
; #pragma unroll
	v_lshl_add_u64 v[190:191], v[2:3], 0, s[40:41]
	s_mov_b32 m0, s6
	v_readfirstlane_b32 s6, v153
	global_load_lds_dwordx4 v[190:191], off
	v_lshl_add_u64 v[190:191], v[4:5], 0, s[40:41]
	s_mov_b32 m0, s6
	v_readfirstlane_b32 s6, v154
	global_load_lds_dwordx4 v[190:191], off
	v_lshl_add_u64 v[190:191], v[6:7], 0, s[40:41]
	s_mov_b32 m0, s6
	v_readfirstlane_b32 s6, v155
	global_load_lds_dwordx4 v[190:191], off
	v_lshl_add_u64 v[190:191], v[8:9], 0, s[40:41]
	s_mov_b32 m0, s6
	v_readfirstlane_b32 s6, v156
	global_load_lds_dwordx4 v[190:191], off
	v_lshl_add_u64 v[190:191], v[10:11], 0, s[40:41]
	s_mov_b32 m0, s6
	v_readfirstlane_b32 s6, v157
	global_load_lds_dwordx4 v[190:191], off
	v_lshl_add_u64 v[190:191], v[12:13], 0, s[40:41]
	s_mov_b32 m0, s6
	v_readfirstlane_b32 s6, v158
	global_load_lds_dwordx4 v[190:191], off
	v_lshl_add_u64 v[190:191], v[14:15], 0, s[40:41]
	s_mov_b32 m0, s6
	v_readfirstlane_b32 s6, v159
	global_load_lds_dwordx4 v[190:191], off
	v_lshl_add_u64 v[190:191], v[16:17], 0, s[40:41]
	s_mov_b32 m0, s6
	s_waitcnt lgkmcnt(0)
	v_mfma_f32_16x16x32_bf16 v[110:113], v[186:189], v[202:205], v[110:113]
	global_load_lds_dwordx4 v[190:191], off
	v_mfma_f32_16x16x32_bf16 v[18:21], v[206:209], v[202:205], v[18:21]
	v_mfma_f32_16x16x32_bf16 v[178:181], v[186:189], v[226:229], v[178:181]
	v_mfma_f32_16x16x32_bf16 v[182:185], v[186:189], v[230:233], v[182:185]
	v_mfma_f32_16x16x32_bf16 v[106:109], v[186:189], v[234:237], v[106:109]
	ds_read_b128 v[186:189], v172
	ds_read_b128 v[190:193], v172 offset:2048
	ds_read_b128 v[194:197], v172 offset:4096
	ds_read_b128 v[198:201], v172 offset:6144
	ds_read_b128 v[202:205], v173
	ds_read_b128 v[210:213], v173 offset:2048
	ds_read_b128 v[214:217], v173 offset:4096
	ds_read_b128 v[218:221], v173 offset:6144
	v_mfma_f32_16x16x32_bf16 v[22:25], v[206:209], v[226:229], v[22:25]
	v_mfma_f32_16x16x32_bf16 v[26:29], v[206:209], v[230:233], v[26:29]
	v_mfma_f32_16x16x32_bf16 v[30:33], v[206:209], v[234:237], v[30:33]
	s_waitcnt lgkmcnt(0)
	v_mfma_f32_16x16x32_bf16 v[50:53], v[202:205], v[186:189], v[50:53]
	v_mfma_f32_16x16x32_bf16 v[58:61], v[202:205], v[190:193], v[58:61]
	v_mfma_f32_16x16x32_bf16 v[66:69], v[202:205], v[194:197], v[66:69]
	v_mfma_f32_16x16x32_bf16 v[34:37], v[202:205], v[198:201], v[34:37]
	ds_read_b128 v[202:205], v173 offset:8192
	ds_read_b128 v[206:209], v173 offset:10240
	v_mfma_f32_16x16x32_bf16 v[54:57], v[210:213], v[186:189], v[54:57]
	v_mfma_f32_16x16x32_bf16 v[62:65], v[210:213], v[190:193], v[62:65]
	v_mfma_f32_16x16x32_bf16 v[70:73], v[210:213], v[194:197], v[70:73]
	v_mfma_f32_16x16x32_bf16 v[38:41], v[210:213], v[198:201], v[38:41]
	v_mfma_f32_16x16x32_bf16 v[82:85], v[214:217], v[186:189], v[82:85]
	v_mfma_f32_16x16x32_bf16 v[90:93], v[214:217], v[190:193], v[90:93]
	v_mfma_f32_16x16x32_bf16 v[98:101], v[214:217], v[194:197], v[98:101]
	v_mfma_f32_16x16x32_bf16 v[42:45], v[214:217], v[198:201], v[42:45]
	ds_read_b128 v[210:213], v173 offset:12288
	ds_read_b128 v[214:217], v173 offset:14336
	v_mfma_f32_16x16x32_bf16 v[86:89], v[218:221], v[186:189], v[86:89]
	v_mfma_f32_16x16x32_bf16 v[94:97], v[218:221], v[190:193], v[94:97]
	v_mfma_f32_16x16x32_bf16 v[102:105], v[218:221], v[194:197], v[102:105]
	v_mfma_f32_16x16x32_bf16 v[46:49], v[218:221], v[198:201], v[46:49]
	s_waitcnt lgkmcnt(0)
	v_mfma_f32_16x16x32_bf16 v[114:117], v[202:205], v[186:189], v[114:117]
	ds_read_b128 v[218:221], v174
	ds_read_b128 v[222:225], v174 offset:2048
	v_mfma_f32_16x16x32_bf16 v[122:125], v[202:205], v[190:193], v[122:125]
	v_mfma_f32_16x16x32_bf16 v[132:135], v[202:205], v[194:197], v[132:135]
	v_mfma_f32_16x16x32_bf16 v[74:77], v[202:205], v[198:201], v[74:77]
	ds_read_b128 v[202:205], v175
	ds_read_b128 v[226:229], v175 offset:2048
	ds_read_b128 v[230:233], v175 offset:4096
	ds_read_b128 v[234:237], v175 offset:6144
	v_mfma_f32_16x16x32_bf16 v[118:121], v[206:209], v[186:189], v[118:121]
	v_mfma_f32_16x16x32_bf16 v[126:129], v[206:209], v[190:193], v[126:129]
	v_mfma_f32_16x16x32_bf16 v[136:139], v[206:209], v[194:197], v[136:139]
	v_mfma_f32_16x16x32_bf16 v[78:81], v[206:209], v[198:201], v[78:81]
	v_mfma_f32_16x16x32_bf16 v[110:113], v[210:213], v[186:189], v[110:113]
	v_mfma_f32_16x16x32_bf16 v[18:21], v[214:217], v[186:189], v[18:21]
	v_mfma_f32_16x16x32_bf16 v[178:181], v[210:213], v[190:193], v[178:181]
	v_mfma_f32_16x16x32_bf16 v[22:25], v[214:217], v[190:193], v[22:25]
	ds_read_b128 v[186:189], v174 offset:4096
	ds_read_b128 v[190:193], v174 offset:6144
	v_mfma_f32_16x16x32_bf16 v[26:29], v[214:217], v[194:197], v[26:29]
	v_mfma_f32_16x16x32_bf16 v[106:109], v[210:213], v[198:201], v[106:109]
	v_mfma_f32_16x16x32_bf16 v[30:33], v[214:217], v[198:201], v[30:33]
	v_mfma_f32_16x16x32_bf16 v[182:185], v[210:213], v[194:197], v[182:185]
	ds_read_b128 v[194:197], v174 offset:8192
	ds_read_b128 v[198:201], v174 offset:10240
	s_waitcnt lgkmcnt(0)
	v_mfma_f32_16x16x32_bf16 v[50:53], v[218:221], v[202:205], v[50:53]
	v_mfma_f32_16x16x32_bf16 v[54:57], v[222:225], v[202:205], v[54:57]
	v_mfma_f32_16x16x32_bf16 v[58:61], v[218:221], v[226:229], v[58:61]
	v_mfma_f32_16x16x32_bf16 v[62:65], v[222:225], v[226:229], v[62:65]
	v_mfma_f32_16x16x32_bf16 v[66:69], v[218:221], v[230:233], v[66:69]
	v_mfma_f32_16x16x32_bf16 v[70:73], v[222:225], v[230:233], v[70:73]
	v_mfma_f32_16x16x32_bf16 v[34:37], v[218:221], v[234:237], v[34:37]
	v_mfma_f32_16x16x32_bf16 v[38:41], v[222:225], v[234:237], v[38:41]
	v_mfma_f32_16x16x32_bf16 v[82:85], v[186:189], v[202:205], v[82:85]
	v_mfma_f32_16x16x32_bf16 v[90:93], v[186:189], v[226:229], v[90:93]
	v_mfma_f32_16x16x32_bf16 v[98:101], v[186:189], v[230:233], v[98:101]
	v_mfma_f32_16x16x32_bf16 v[42:45], v[186:189], v[234:237], v[42:45]
	ds_read_b128 v[186:189], v174 offset:12288
	ds_read_b128 v[206:209], v174 offset:14336
	v_mfma_f32_16x16x32_bf16 v[86:89], v[190:193], v[202:205], v[86:89]
	v_mfma_f32_16x16x32_bf16 v[94:97], v[190:193], v[226:229], v[94:97]
	v_mfma_f32_16x16x32_bf16 v[102:105], v[190:193], v[230:233], v[102:105]
	v_mfma_f32_16x16x32_bf16 v[46:49], v[190:193], v[234:237], v[46:49]
	v_mfma_f32_16x16x32_bf16 v[114:117], v[194:197], v[202:205], v[114:117]
	v_mfma_f32_16x16x32_bf16 v[118:121], v[198:201], v[202:205], v[118:121]
	v_mfma_f32_16x16x32_bf16 v[122:125], v[194:197], v[226:229], v[122:125]
	v_mfma_f32_16x16x32_bf16 v[126:129], v[198:201], v[226:229], v[126:129]
	v_mfma_f32_16x16x32_bf16 v[132:135], v[194:197], v[230:233], v[132:135]
	v_mfma_f32_16x16x32_bf16 v[136:139], v[198:201], v[230:233], v[136:139]
	v_mfma_f32_16x16x32_bf16 v[74:77], v[194:197], v[234:237], v[74:77]
	v_mfma_f32_16x16x32_bf16 v[78:81], v[198:201], v[234:237], v[78:81]
	v_readfirstlane_b32 s6, v160
	s_waitcnt vmcnt(0)
	s_barrier
; template <bool SWAP, class Epi, bool THIN = false> ...
;     ...
;     for (int st = 0; st < ns; ++st) {
;       asm volatile("s_waitcnt vmcnt(0)" ::: "memory");
;       __builtin_amdgcn_s_barrier();
;       asm volatile("" ::: "memory");
;       if (st + 1 < ns) {
;         char* nb = smem + ((st + 1) & 1) * 65536;
;         const int ko = (st + 1) * 64;
; #pragma unroll
;         for (int i = 0; i < 4; ++i) { GLDS16(A + (size_t)(ap[i] + ko), nb + tid * 16 + i * 8192); GLDS16(Bt + (size_t)(bp[i] + ko), nb + 32768 + tid * 16 + i * 8192); }
;       }
;       const char* sa = smem + (st & 1) * 65536 + (wr * 64 + fr) * 128;
;       const char* sb = smem + (st & 1) * 65536 + 32768 + (wc * 128 + fr) * 128;
;       if constexpr (THIN) {
;         if (wc == 0) {
; #pragma unroll
;           for (int ks = 0; ks < 2; ++ks) {
;             bf16x8 af[4], bf[2];
; #pragma unroll
;             for (int m = 0; m < 4; ++m) af[m] = *(const bf16x8*)(sa + m * 2048 + (((ks * 4 + fq) ^ swz) << 4));
; #pragma unroll
;             for (int n = 0; n < 2; ++n) bf[n] = *(const bf16x8*)(sb + n * 2048 + (((ks * 4 + fq) ^ swz) << 4));
; #pragma unroll
;             for (int m = 0; m < 4; ++m)
; #pragma unroll
;               for (int n = 0; n < 2; ++n)
;                 acc[m][n] = SWAP ? __builtin_amdgcn_mfma_f32_16x16x32_bf16(bf[n], af[m], acc[m][n], 0, 0, 0)
;                                  : __builtin_amdgcn_mfma_f32_16x16x32_bf16(af[m], bf[n], acc[m][n], 0, 0, 0);
;           }
;         }
;       } else {
;       bf16x8 afA[4], afB[4], bfb[2][2];
; #pragma unroll
;       for (int m = 0; m < 4; ++m) afA[m] = *(const bf16x8*)(sa + m * 2048 + ((fq ^ swz) << 4));
; #pragma unroll
;       for (int n = 0; n < 2; ++n) bfb[0][n] = *(const bf16x8*)(sb + n * 2048 + ((fq ^ swz) << 4));
; #pragma unroll
;       for (int gq = 0; gq < 8; ++gq) {
;         const int ks = gq >> 2, nh = gq & 3;
;         if (gq < 7) {
;           const int ks2 = (gq + 1) >> 2, nh2 = (gq + 1) & 3;
; #pragma unroll
;           for (int n = 0; n < 2; ++n) bfb[(gq + 1) & 1][n] = *(const bf16x8*)(sb + (nh2 * 2 + n) * 2048 + (((ks2 * 4 + fq) ^ swz) << 4));
;         }
;         if (gq == 3) {
; #pragma unroll
;           for (int m = 0; m < 4; ++m) afB[m] = *(const bf16x8*)(sa + m * 2048 + (((4 + fq) ^ swz) << 4));
;         }
;         __builtin_amdgcn_sched_barrier(0);
; #pragma unroll
	v_lshl_add_u64 v[2:3], v[2:3], 0, s[42:43]
	s_mov_b32 m0, s6
	v_readfirstlane_b32 s6, v161
	global_load_lds_dwordx4 v[2:3], off
	v_lshl_add_u64 v[190:191], v[4:5], 0, s[42:43]
	s_mov_b32 m0, s6
	v_readfirstlane_b32 s6, v162
	global_load_lds_dwordx4 v[190:191], off
	v_lshl_add_u64 v[6:7], v[6:7], 0, s[42:43]
	s_mov_b32 m0, s6
	v_readfirstlane_b32 s6, v163
	global_load_lds_dwordx4 v[6:7], off
	v_lshl_add_u64 v[6:7], v[8:9], 0, s[42:43]
	s_mov_b32 m0, s6
	v_readfirstlane_b32 s6, v164
	global_load_lds_dwordx4 v[6:7], off
	v_lshl_add_u64 v[6:7], v[10:11], 0, s[42:43]
	s_mov_b32 m0, s6
	v_readfirstlane_b32 s6, v165
	global_load_lds_dwordx4 v[6:7], off
	v_lshl_add_u64 v[6:7], v[12:13], 0, s[42:43]
	s_mov_b32 m0, s6
	v_readfirstlane_b32 s6, v166
	global_load_lds_dwordx4 v[6:7], off
	v_lshl_add_u64 v[6:7], v[14:15], 0, s[42:43]
	s_mov_b32 m0, s6
	v_readfirstlane_b32 s6, v167
	global_load_lds_dwordx4 v[6:7], off
	v_lshl_add_u64 v[6:7], v[16:17], 0, s[42:43]
	s_mov_b32 m0, s6
	s_waitcnt lgkmcnt(0)
	v_mfma_f32_16x16x32_bf16 v[110:113], v[186:189], v[202:205], v[110:113]
	global_load_lds_dwordx4 v[6:7], off
	v_mfma_f32_16x16x32_bf16 v[178:181], v[186:189], v[226:229], v[178:181]
	v_mfma_f32_16x16x32_bf16 v[2:5], v[186:189], v[230:233], v[182:185]
	v_mfma_f32_16x16x32_bf16 v[6:9], v[186:189], v[234:237], v[106:109]
	ds_read_b128 v[10:13], v168
	ds_read_b128 v[14:17], v168 offset:2048
	s_nop 0
	ds_read_b128 v[106:109], v168 offset:4096
	ds_read_b128 v[182:185], v168 offset:6144
	ds_read_b128 v[186:189], v169 offset:32768
	ds_read_b128 v[190:193], v169 offset:34816
	ds_read_b128 v[194:197], v169 offset:36864
	ds_read_b128 v[198:201], v169 offset:38912
	v_mfma_f32_16x16x32_bf16 v[18:21], v[206:209], v[202:205], v[18:21]
	v_mfma_f32_16x16x32_bf16 v[22:25], v[206:209], v[226:229], v[22:25]
	v_mfma_f32_16x16x32_bf16 v[26:29], v[206:209], v[230:233], v[26:29]
	v_mfma_f32_16x16x32_bf16 v[30:33], v[206:209], v[234:237], v[30:33]
	s_waitcnt lgkmcnt(0)
	v_mfma_f32_16x16x32_bf16 v[50:53], v[186:189], v[10:13], v[50:53]
	v_mfma_f32_16x16x32_bf16 v[58:61], v[186:189], v[14:17], v[58:61]
	v_mfma_f32_16x16x32_bf16 v[66:69], v[186:189], v[106:109], v[66:69]
	v_mfma_f32_16x16x32_bf16 v[34:37], v[186:189], v[182:185], v[34:37]
	ds_read_b128 v[186:189], v169 offset:40960
	ds_read_b128 v[202:205], v169 offset:43008
	v_mfma_f32_16x16x32_bf16 v[54:57], v[190:193], v[10:13], v[54:57]
	v_mfma_f32_16x16x32_bf16 v[62:65], v[190:193], v[14:17], v[62:65]
	v_mfma_f32_16x16x32_bf16 v[70:73], v[190:193], v[106:109], v[70:73]
	v_mfma_f32_16x16x32_bf16 v[38:41], v[190:193], v[182:185], v[38:41]
	v_mfma_f32_16x16x32_bf16 v[82:85], v[194:197], v[10:13], v[82:85]
	v_mfma_f32_16x16x32_bf16 v[90:93], v[194:197], v[14:17], v[90:93]
	v_mfma_f32_16x16x32_bf16 v[98:101], v[194:197], v[106:109], v[98:101]
	v_mfma_f32_16x16x32_bf16 v[42:45], v[194:197], v[182:185], v[42:45]
	ds_read_b128 v[190:193], v169 offset:45056
	ds_read_b128 v[194:197], v169 offset:47104
	v_mfma_f32_16x16x32_bf16 v[86:89], v[198:201], v[10:13], v[86:89]
	v_mfma_f32_16x16x32_bf16 v[94:97], v[198:201], v[14:17], v[94:97]
	v_mfma_f32_16x16x32_bf16 v[102:105], v[198:201], v[106:109], v[102:105]
	v_mfma_f32_16x16x32_bf16 v[46:49], v[198:201], v[182:185], v[46:49]
	s_waitcnt lgkmcnt(0)
	v_mfma_f32_16x16x32_bf16 v[114:117], v[186:189], v[10:13], v[114:117]
	ds_read_b128 v[198:201], v170 offset:32768
	ds_read_b128 v[206:209], v170 offset:34816
	v_mfma_f32_16x16x32_bf16 v[122:125], v[186:189], v[14:17], v[122:125]
	v_mfma_f32_16x16x32_bf16 v[132:135], v[186:189], v[106:109], v[132:135]
	v_mfma_f32_16x16x32_bf16 v[74:77], v[186:189], v[182:185], v[74:77]
	ds_read_b128 v[186:189], v171
	ds_read_b128 v[210:213], v171 offset:2048
	ds_read_b128 v[214:217], v171 offset:4096
	ds_read_b128 v[218:221], v171 offset:6144
	v_mfma_f32_16x16x32_bf16 v[118:121], v[202:205], v[10:13], v[118:121]
	v_mfma_f32_16x16x32_bf16 v[126:129], v[202:205], v[14:17], v[126:129]
	v_mfma_f32_16x16x32_bf16 v[136:139], v[202:205], v[106:109], v[136:139]
	v_mfma_f32_16x16x32_bf16 v[78:81], v[202:205], v[182:185], v[78:81]
	v_mfma_f32_16x16x32_bf16 v[110:113], v[190:193], v[10:13], v[110:113]
	v_mfma_f32_16x16x32_bf16 v[10:13], v[194:197], v[10:13], v[18:21]
	v_mfma_f32_16x16x32_bf16 v[18:21], v[190:193], v[14:17], v[178:181]
	v_mfma_f32_16x16x32_bf16 v[14:17], v[194:197], v[14:17], v[22:25]
	v_mfma_f32_16x16x32_bf16 v[2:5], v[190:193], v[106:109], v[2:5]
	v_mfma_f32_16x16x32_bf16 v[22:25], v[194:197], v[106:109], v[26:29]
	s_nop 2
	ds_read_b128 v[26:29], v170 offset:36864
	ds_read_b128 v[106:109], v170 offset:38912
	v_mfma_f32_16x16x32_bf16 v[6:9], v[190:193], v[182:185], v[6:9]
	v_mfma_f32_16x16x32_bf16 v[30:33], v[194:197], v[182:185], v[30:33]
	ds_read_b128 v[178:181], v170 offset:40960
	ds_read_b128 v[182:185], v170 offset:43008
	s_waitcnt lgkmcnt(0)
	v_mfma_f32_16x16x32_bf16 v[50:53], v[198:201], v[186:189], v[50:53]
	v_mfma_f32_16x16x32_bf16 v[54:57], v[206:209], v[186:189], v[54:57]
	v_mfma_f32_16x16x32_bf16 v[58:61], v[198:201], v[210:213], v[58:61]
	v_mfma_f32_16x16x32_bf16 v[62:65], v[206:209], v[210:213], v[62:65]
	v_mfma_f32_16x16x32_bf16 v[66:69], v[198:201], v[214:217], v[66:69]
	v_mfma_f32_16x16x32_bf16 v[70:73], v[206:209], v[214:217], v[70:73]
	v_mfma_f32_16x16x32_bf16 v[34:37], v[198:201], v[218:221], v[34:37]
	v_mfma_f32_16x16x32_bf16 v[38:41], v[206:209], v[218:221], v[38:41]
	v_mfma_f32_16x16x32_bf16 v[82:85], v[26:29], v[186:189], v[82:85]
	v_mfma_f32_16x16x32_bf16 v[90:93], v[26:29], v[210:213], v[90:93]
	v_mfma_f32_16x16x32_bf16 v[98:101], v[26:29], v[214:217], v[98:101]
	v_mfma_f32_16x16x32_bf16 v[26:29], v[26:29], v[218:221], v[42:45]
	s_nop 2
	ds_read_b128 v[42:45], v170 offset:45056
	ds_read_b128 v[190:193], v170 offset:47104
	v_mfma_f32_16x16x32_bf16 v[86:89], v[106:109], v[186:189], v[86:89]
	v_mfma_f32_16x16x32_bf16 v[94:97], v[106:109], v[210:213], v[94:97]
	v_mfma_f32_16x16x32_bf16 v[102:105], v[106:109], v[214:217], v[102:105]
	v_mfma_f32_16x16x32_bf16 v[46:49], v[106:109], v[218:221], v[46:49]
	v_mfma_f32_16x16x32_bf16 v[106:109], v[178:181], v[186:189], v[114:117]
	v_mfma_f32_16x16x32_bf16 v[114:117], v[182:185], v[186:189], v[118:121]
	v_mfma_f32_16x16x32_bf16 v[118:121], v[178:181], v[210:213], v[122:125]
	v_mfma_f32_16x16x32_bf16 v[122:125], v[182:185], v[210:213], v[126:129]
	v_mfma_f32_16x16x32_bf16 v[126:129], v[178:181], v[214:217], v[132:135]
	v_mfma_f32_16x16x32_bf16 v[132:135], v[182:185], v[214:217], v[136:139]
	v_mfma_f32_16x16x32_bf16 v[74:77], v[178:181], v[218:221], v[74:77]
	v_mfma_f32_16x16x32_bf16 v[78:81], v[182:185], v[218:221], v[78:81]
	s_waitcnt vmcnt(0)
	s_barrier
; template <bool SWAP, class Epi, bool THIN = false> ...
;     ...
;       bf16x8 afA[4], afB[4], bfb[2][2];
; #pragma unroll
;       for (int m = 0; m < 4; ++m) afA[m] = *(const bf16x8*)(sa + m * 2048 + ((fq ^ swz) << 4));
; #pragma unroll
;       for (int n = 0; n < 2; ++n) bfb[0][n] = *(const bf16x8*)(sb + n * 2048 + ((fq ^ swz) << 4));
; #pragma unroll
;       for (int gq = 0; gq < 8; ++gq) {
;         const int ks = gq >> 2, nh = gq & 3;
;         if (gq < 7) {
;           const int ks2 = (gq + 1) >> 2, nh2 = (gq + 1) & 3;
; #pragma unroll
;           for (int n = 0; n < 2; ++n) bfb[(gq + 1) & 1][n] = *(const bf16x8*)(sb + (nh2 * 2 + n) * 2048 + (((ks2 * 4 + fq) ^ swz) << 4));
;         }
;         if (gq == 3) {
; #pragma unroll
;           for (int m = 0; m < 4; ++m) afB[m] = *(const bf16x8*)(sa + m * 2048 + (((4 + fq) ^ swz) << 4));
;         }
;         __builtin_amdgcn_sched_barrier(0);
; #pragma unroll
;         for (int m = 0; m < 4; ++m)
; #pragma unroll
;           for (int n = 0; n < 2; ++n) {
;             const bf16x8 av = ks ? afB[m] : afA[m];
;             acc[m][nh * 2 + n] = SWAP ? __builtin_amdgcn_mfma_f32_16x16x32_bf16(bfb[gq & 1][n], av, acc[m][nh * 2 + n], 0, 0, 0)
;                                       : __builtin_amdgcn_mfma_f32_16x16x32_bf16(av, bfb[gq & 1][n], acc[m][nh * 2 + n], 0, 0, 0);
;           }
;       }
;       }
;     }
;     __syncthreads();
	s_waitcnt lgkmcnt(0)
	v_mfma_f32_16x16x32_bf16 v[110:113], v[42:45], v[186:189], v[110:113]
	v_mfma_f32_16x16x32_bf16 v[10:13], v[190:193], v[186:189], v[10:13]
	ds_read_b128 v[136:139], v172
	ds_read_b128 v[178:181], v172 offset:2048
	ds_read_b128 v[182:185], v172 offset:4096
	ds_read_b128 v[186:189], v172 offset:6144
	v_mfma_f32_16x16x32_bf16 v[18:21], v[42:45], v[210:213], v[18:21]
	v_mfma_f32_16x16x32_bf16 v[2:5], v[42:45], v[214:217], v[2:5]
	v_mfma_f32_16x16x32_bf16 v[6:9], v[42:45], v[218:221], v[6:9]
	ds_read_b128 v[42:45], v173
	ds_read_b128 v[194:197], v173 offset:2048
	ds_read_b128 v[198:201], v173 offset:4096
	ds_read_b128 v[202:205], v173 offset:6144
	v_mfma_f32_16x16x32_bf16 v[14:17], v[190:193], v[210:213], v[14:17]
	v_mfma_f32_16x16x32_bf16 v[22:25], v[190:193], v[214:217], v[22:25]
	v_mfma_f32_16x16x32_bf16 v[30:33], v[190:193], v[218:221], v[30:33]
	s_waitcnt lgkmcnt(0)
	v_mfma_f32_16x16x32_bf16 v[50:53], v[42:45], v[136:139], v[50:53]
	v_mfma_f32_16x16x32_bf16 v[58:61], v[42:45], v[178:181], v[58:61]
	v_mfma_f32_16x16x32_bf16 v[66:69], v[42:45], v[182:185], v[66:69]
	v_mfma_f32_16x16x32_bf16 v[34:37], v[42:45], v[186:189], v[34:37]
	ds_read_b128 v[42:45], v173 offset:8192
	ds_read_b128 v[190:193], v173 offset:10240
	v_mfma_f32_16x16x32_bf16 v[54:57], v[194:197], v[136:139], v[54:57]
	v_mfma_f32_16x16x32_bf16 v[62:65], v[194:197], v[178:181], v[62:65]
	v_mfma_f32_16x16x32_bf16 v[70:73], v[194:197], v[182:185], v[70:73]
	v_mfma_f32_16x16x32_bf16 v[38:41], v[194:197], v[186:189], v[38:41]
	v_mfma_f32_16x16x32_bf16 v[82:85], v[198:201], v[136:139], v[82:85]
	v_mfma_f32_16x16x32_bf16 v[194:197], v[198:201], v[178:181], v[90:93]
	v_mfma_f32_16x16x32_bf16 v[98:101], v[198:201], v[182:185], v[98:101]
	v_mfma_f32_16x16x32_bf16 v[198:201], v[198:201], v[186:189], v[26:29]
	s_nop 2
	ds_read_b128 v[26:29], v173 offset:12288
	ds_read_b128 v[90:93], v173 offset:14336
	v_mfma_f32_16x16x32_bf16 v[86:89], v[202:205], v[136:139], v[86:89]
	v_mfma_f32_16x16x32_bf16 v[102:105], v[202:205], v[182:185], v[102:105]
	v_mfma_f32_16x16x32_bf16 v[46:49], v[202:205], v[186:189], v[46:49]
	v_mfma_f32_16x16x32_bf16 v[206:209], v[202:205], v[178:181], v[94:97]
	s_waitcnt lgkmcnt(0)
	v_mfma_f32_16x16x32_bf16 v[202:205], v[190:193], v[136:139], v[114:117]
	v_mfma_f32_16x16x32_bf16 v[210:213], v[42:45], v[178:181], v[118:121]
	s_nop 1
	ds_read_b128 v[114:117], v174
	ds_read_b128 v[118:121], v174 offset:2048
	ds_read_b128 v[226:229], v175
	ds_read_b128 v[230:233], v175 offset:2048
	ds_read_b128 v[234:237], v175 offset:4096
	ds_read_b128 v[238:241], v175 offset:6144
	v_mfma_f32_16x16x32_bf16 v[106:109], v[42:45], v[136:139], v[106:109]
	v_mfma_f32_16x16x32_bf16 v[132:135], v[190:193], v[182:185], v[132:135]
	v_mfma_f32_16x16x32_bf16 v[214:217], v[190:193], v[178:181], v[122:125]
	v_mfma_f32_16x16x32_bf16 v[218:221], v[42:45], v[182:185], v[126:129]
	v_mfma_f32_16x16x32_bf16 v[222:225], v[42:45], v[186:189], v[74:77]
	v_mfma_f32_16x16x32_bf16 v[190:193], v[190:193], v[186:189], v[78:81]
	v_mfma_f32_16x16x32_bf16 v[242:245], v[26:29], v[136:139], v[110:113]
	v_mfma_f32_16x16x32_bf16 v[136:139], v[90:93], v[136:139], v[10:13]
	v_mfma_f32_16x16x32_bf16 v[246:249], v[26:29], v[178:181], v[18:21]
	v_mfma_f32_16x16x32_bf16 v[178:181], v[90:93], v[178:181], v[14:17]
	s_nop 0
	ds_read_b128 v[10:13], v174 offset:4096
	s_nop 0
	ds_read_b128 v[14:17], v174 offset:6144
	v_mfma_f32_16x16x32_bf16 v[2:5], v[26:29], v[182:185], v[2:5]
	v_mfma_f32_16x16x32_bf16 v[6:9], v[26:29], v[186:189], v[6:9]
	v_mfma_f32_16x16x32_bf16 v[182:185], v[90:93], v[182:185], v[22:25]
	v_mfma_f32_16x16x32_bf16 v[186:189], v[90:93], v[186:189], v[30:33]
	s_waitcnt lgkmcnt(0)
	v_mfma_f32_16x16x32_bf16 v[90:93], v[118:121], v[230:233], v[62:65]
	v_mfma_f32_16x16x32_bf16 v[62:65], v[114:117], v[234:237], v[66:69]
	v_mfma_f32_16x16x32_bf16 v[30:33], v[114:117], v[238:241], v[34:37]
	s_nop 2
	ds_read_b128 v[34:37], v174 offset:8192
	ds_read_b128 v[66:69], v174 offset:10240
	v_mfma_f32_16x16x32_bf16 v[126:129], v[114:117], v[226:229], v[50:53]
	v_mfma_f32_16x16x32_bf16 v[122:125], v[118:121], v[226:229], v[54:57]
	v_mfma_f32_16x16x32_bf16 v[94:97], v[114:117], v[230:233], v[58:61]
	v_mfma_f32_16x16x32_bf16 v[58:61], v[118:121], v[234:237], v[70:73]
	v_mfma_f32_16x16x32_bf16 v[26:29], v[118:121], v[238:241], v[38:41]
	v_mfma_f32_16x16x32_bf16 v[114:117], v[14:17], v[226:229], v[86:89]
	v_mfma_f32_16x16x32_bf16 v[86:89], v[10:13], v[230:233], v[194:197]
	v_mfma_f32_16x16x32_bf16 v[22:25], v[10:13], v[238:241], v[198:201]
	s_nop 1
	ds_read_b128 v[194:197], v174 offset:12288
	ds_read_b128 v[198:201], v174 offset:14336
	v_mfma_f32_16x16x32_bf16 v[118:121], v[10:13], v[226:229], v[82:85]
	v_mfma_f32_16x16x32_bf16 v[82:85], v[14:17], v[230:233], v[206:209]
	v_mfma_f32_16x16x32_bf16 v[54:57], v[10:13], v[234:237], v[98:101]
	v_mfma_f32_16x16x32_bf16 v[50:53], v[14:17], v[234:237], v[102:105]
	v_mfma_f32_16x16x32_bf16 v[18:21], v[14:17], v[238:241], v[46:49]
	s_waitcnt lgkmcnt(0)
	v_mfma_f32_16x16x32_bf16 v[110:113], v[34:37], v[226:229], v[106:109]
	v_mfma_f32_16x16x32_bf16 v[106:109], v[66:69], v[226:229], v[202:205]
	v_mfma_f32_16x16x32_bf16 v[78:81], v[34:37], v[230:233], v[210:213]
	v_mfma_f32_16x16x32_bf16 v[74:77], v[66:69], v[230:233], v[214:217]
	v_mfma_f32_16x16x32_bf16 v[46:49], v[34:37], v[234:237], v[218:221]
	v_mfma_f32_16x16x32_bf16 v[42:45], v[66:69], v[234:237], v[132:135]
	v_mfma_f32_16x16x32_bf16 v[14:17], v[34:37], v[238:241], v[222:225]
	v_mfma_f32_16x16x32_bf16 v[10:13], v[66:69], v[238:241], v[190:193]
	v_mov_b32_e32 v130, v1
	s_waitcnt vmcnt(0)
	s_barrier
; __device__ __forceinline__ unsigned pack2(float a, float b) { unsigned r; asm("v_cvt_pk_bf16_f32 %0, %1, %2" : "=v"(r) : "v"(a), "v"(b)); return r; }
;   __device__ __forceinline__ void c4(int g, int rig, int col, f32x4 v) const {
;     const size_t row = (size_t)g * ostride + rig;
;     float s = 1.f;
;     if (NP > 0) {
;       float t = 0.f;
; #pragma unroll
;       for (int q = 0; q < NP; ++q) t += part[(size_t)q * pstride + row];
;       s = rsqrtf(t * inv_n + 1e-6f);
;     }
;     uint2 u; u.x = pack2(v[0] * s, v[1] * s); u.y = pack2(v[2] * s, v[3] * s);
;     *(uint2*)(out + row * ld + col) = u;
;   }
; template <bool SWAP, class Epi, bool THIN = false> ...
;     ...
;     if constexpr (Epi::KIND == 0) {
; #pragma unroll
;       for (int m = 0; m < 4; ++m) {
;         const int rig = rig0 + rw + m * 16 + fr_e;
;         if constexpr (Epi::ROWSUM) {
;           float ss = 0.f;
; #pragma unroll
;           for (int n = 0; n < 8; ++n) {
;             const int col = nt * 256 + wc_e * 128 + n * 16 + fq_e * 4;
;             if (col < N) ss += epi.c4(g, rig, col, acc[m][n]);
;           }
;           ss += __shfl_xor(ss, 16); ss += __shfl_xor(ss, 32);
;           if (fq_e == 0) epi.rowsum(g, rig, nt * 2 + wc_e, ss);
;         } else {
; #pragma unroll
;           for (int n = 0; n < 8; ++n) {
;             const int col = nt * 256 + wc_e * 128 + n * 16 + fq_e * 4;
;             if (col < N) epi.c4(g, rig, col, acc[m][n]);
;           }
;         }
	v_mfma_f32_16x16x32_bf16 v[38:41], v[194:197], v[234:237], v[2:5]
	v_ashrrev_i32_e32 v34, 8, v130
	v_add_u32_e32 v34, s5, v34
	v_ashrrev_i32_e32 v35, 31, v34
	v_lshrrev_b32_e32 v35, 28, v35
	v_add_u32_e32 v35, v34, v35
	v_ashrrev_i32_e32 v134, 4, v35
	v_lshlrev_b32_e32 v35, 11, v134
	v_lshlrev_b32_e32 v34, 7, v34
	v_lshrrev_b32_e32 v3, 1, v130
	v_and_b32_e32 v132, 15, v130
	v_sub_u32_e32 v2, v34, v35
	v_and_b32_e32 v3, 64, v3
	v_mfma_f32_16x16x32_bf16 v[98:101], v[198:201], v[226:229], v[136:139]
	v_ashrrev_i32_e32 v135, 31, v134
	s_nop 1
	v_or3_b32 v136, v2, v3, v132
	v_lshlrev_b32_e32 v2, 1, v130
	v_lshrrev_b32_e32 v3, 2, v130
	v_and_b32_e32 v2, 0x80, v2
	v_and_b32_e32 v3, 12, v3
	v_mfma_f32_16x16x32_bf16 v[102:105], v[194:197], v[226:229], v[242:245]
	v_or3_b32 v132, v3, v2, s4
	v_ashrrev_i32_e32 v137, 31, v136
	v_lshlrev_b64 v[138:139], 11, v[134:135]
	v_mfma_f32_16x16x32_bf16 v[70:73], v[194:197], v[230:233], v[246:249]
	v_cmp_gt_i32_e64 s[4:5], s50, v132
	v_ashrrev_i32_e32 v133, 31, v132
	v_lshl_add_u64 v[134:135], v[138:139], 0, v[136:137]
	v_mfma_f32_16x16x32_bf16 v[66:69], v[198:201], v[230:233], v[178:181]
	v_mfma_f32_16x16x32_bf16 v[34:37], v[198:201], v[234:237], v[182:185]
	v_mfma_f32_16x16x32_bf16 v[6:9], v[194:197], v[238:241], v[6:9]
	v_mfma_f32_16x16x32_bf16 v[2:5], v[198:201], v[238:241], v[186:189]
	v_lshl_add_u64 v[178:179], v[134:135], 2, s[22:23]
	v_add_co_u32_e32 v180, vcc, 0x10000, v178
	s_nop 1
	v_bfe_u32 v252, v1, 4, 1
	v_mul_u32_u24_e32 v252, 24, v252
	v_mov_b32_e32 v253, 0
	v_addc_co_u32_e32 v181, vcc, 0, v179, vcc
	v_add_co_u32_e32 v182, vcc, 0x20000, v178
	s_nop 1
	v_addc_co_u32_e32 v183, vcc, 0, v179, vcc
	v_add_co_u32_e32 v184, vcc, 0x30000, v178
	s_nop 1
	v_addc_co_u32_e32 v185, vcc, 0, v179, vcc
	global_load_dword v130, v[178:179], off
	global_load_dword v137, v[180:181], off
	global_load_dword v177, v[182:183], off
	s_nop 0
	global_load_dword v180, v[184:185], off
	v_mov_b64_e32 v[178:179], s[20:21]
	v_mad_u64_u32 v[178:179], s[8:9], v134, s56, v[178:179]
	v_mad_i32_i24 v179, v135, s56, v179
	s_waitcnt vmcnt(3)
	v_add_f32_e32 v130, 0, v130
	s_waitcnt vmcnt(2)
	v_add_f32_e32 v130, v130, v137
	s_waitcnt vmcnt(1)
	v_add_f32_e32 v130, v130, v177
	s_waitcnt vmcnt(0)
	v_add_f32_e32 v130, v130, v180
	v_fmamk_f32 v130, v130, 0x3b000000, v176
	v_mul_f32_e32 v137, 0x4b800000, v130
	v_cmp_gt_f32_e32 vcc, s51, v130
	s_nop 1
	v_cndmask_b32_e32 v130, v130, v137, vcc
	v_rsq_f32_e32 v130, v130
	s_nop 0
	v_mul_f32_e32 v137, 0x45800000, v130
	v_cndmask_b32_e32 v130, v130, v137, vcc
	v_mov_b32_e32 v251, v130
	v_mul_f32_e32 v126, v126, v130
	v_mul_f32_e32 v127, v127, v130
	v_mul_f32_e32 v128, v128, v130
	v_mul_f32_e32 v129, v129, v130
	v_cvt_pk_bf16_f32 v126, v126, v127
	v_cvt_pk_bf16_f32 v127, v128, v129
	v_or_b32_e32 v254, 16, v132
	v_mov_b64_e32 v[254:255], s[20:21]
	v_mad_u64_u32 v[254:255], s[10:11], v134, s56, v[254:255]
	v_mad_i32_i24 v255, v135, s56, v255
	v_mul_f32_e32 v122, v122, v251
	v_mul_f32_e32 v123, v123, v251
	v_mul_f32_e32 v124, v124, v251
	v_mul_f32_e32 v125, v125, v251
	v_cvt_pk_bf16_f32 v128, v122, v123
	v_cvt_pk_bf16_f32 v129, v124, v125
	v_lshl_add_u64 v[124:125], v[132:133], 1, v[254:255]
	s_nop 1
	v_permlane16_swap_b32 v126, v128
	v_permlane16_swap_b32 v127, v129
	v_lshl_add_u64 v[254:255], v[124:125], 0, v[252:253]
	s_nop 0
	global_store_dwordx4 v[254:255], v[126:129], off
	s_nop 1
	v_or_b32_e32 v122, 32, v132
	v_mov_b64_e32 v[122:123], s[20:21]
	v_mad_u64_u32 v[122:123], s[12:13], v134, s56, v[122:123]
	v_mad_i32_i24 v123, v135, s56, v123
	v_mul_f32_e32 v118, v118, v251
	v_mul_f32_e32 v119, v119, v251
	v_mul_f32_e32 v120, v120, v251
	v_mul_f32_e32 v121, v121, v251
	v_cvt_pk_bf16_f32 v118, v118, v119
	v_cvt_pk_bf16_f32 v119, v120, v121
	v_or_b32_e32 v254, 48, v132
	v_mov_b64_e32 v[254:255], s[20:21]
	v_mad_u64_u32 v[254:255], s[14:15], v134, s56, v[254:255]
	v_mad_i32_i24 v255, v135, s56, v255
	v_mul_f32_e32 v114, v114, v251
	v_mul_f32_e32 v115, v115, v251
	v_mul_f32_e32 v116, v116, v251
	v_mul_f32_e32 v117, v117, v251
	v_cvt_pk_bf16_f32 v120, v114, v115
	v_cvt_pk_bf16_f32 v121, v116, v117
	v_lshl_add_u64 v[116:117], v[132:133], 1, v[254:255]
	s_nop 1
	v_permlane16_swap_b32 v118, v120
	v_permlane16_swap_b32 v119, v121
	v_lshl_add_u64 v[254:255], v[116:117], 0, v[252:253]
	s_nop 0
	global_store_dwordx4 v[254:255], v[118:121], off offset:64
	s_nop 1
	v_or_b32_e32 v114, 64, v132
	v_mov_b64_e32 v[114:115], s[20:21]
	v_mad_u64_u32 v[114:115], s[16:17], v134, s56, v[114:115]
	v_mad_i32_i24 v115, v135, s56, v115
	v_mul_f32_e32 v110, v110, v251
	v_mul_f32_e32 v111, v111, v251
	v_mul_f32_e32 v112, v112, v251
	v_mul_f32_e32 v113, v113, v251
	v_cvt_pk_bf16_f32 v110, v110, v111
	v_cvt_pk_bf16_f32 v111, v112, v113
	v_or_b32_e32 v254, 0x50, v132
	v_mov_b64_e32 v[254:255], s[20:21]
	v_mad_u64_u32 v[254:255], s[18:19], v134, s56, v[254:255]
	v_mad_i32_i24 v255, v135, s56, v255
	v_mul_f32_e32 v106, v106, v251
	v_mul_f32_e32 v107, v107, v251
	v_mul_f32_e32 v108, v108, v251
	v_mul_f32_e32 v109, v109, v251
	v_cvt_pk_bf16_f32 v112, v106, v107
	v_cvt_pk_bf16_f32 v113, v108, v109
	v_lshl_add_u64 v[108:109], v[132:133], 1, v[254:255]
	s_nop 1
	v_permlane16_swap_b32 v110, v112
	v_permlane16_swap_b32 v111, v113
	v_lshl_add_u64 v[254:255], v[108:109], 0, v[252:253]
	s_nop 0
	global_store_dwordx4 v[254:255], v[110:113], off offset:128
	s_nop 1
	v_or_b32_e32 v106, 0x60, v132
	v_mov_b64_e32 v[106:107], s[20:21]
	v_mad_u64_u32 v[106:107], s[44:45], v134, s56, v[106:107]
	v_mad_i32_i24 v107, v135, s56, v107
	v_mul_f32_e32 v102, v102, v251
	v_mul_f32_e32 v103, v103, v251
	v_mul_f32_e32 v104, v104, v251
	v_mul_f32_e32 v105, v105, v251
; __device__ __forceinline__ unsigned pack2(float a, float b) { unsigned r; asm("v_cvt_pk_bf16_f32 %0, %1, %2" : "=v"(r) : "v"(a), "v"(b)); return r; }
;   __device__ __forceinline__ void c4(int g, int rig, int col, f32x4 v) const {
;     const size_t row = (size_t)g * ostride + rig;
;     float s = 1.f;
;     if (NP > 0) {
;       float t = 0.f;
; #pragma unroll
;       for (int q = 0; q < NP; ++q) t += part[(size_t)q * pstride + row];
;       s = rsqrtf(t * inv_n + 1e-6f);
;     }
;     uint2 u; u.x = pack2(v[0] * s, v[1] * s); u.y = pack2(v[2] * s, v[3] * s);
;     *(uint2*)(out + row * ld + col) = u;
;   }
; template <bool SWAP, class Epi, bool THIN = false> ...
;     ...
;     if constexpr (Epi::KIND == 0) {
; #pragma unroll
;       for (int m = 0; m < 4; ++m) {
;         const int rig = rig0 + rw + m * 16 + fr_e;
;         if constexpr (Epi::ROWSUM) {
;           float ss = 0.f;
; #pragma unroll
;           for (int n = 0; n < 8; ++n) {
;             const int col = nt * 256 + wc_e * 128 + n * 16 + fq_e * 4;
;             if (col < N) ss += epi.c4(g, rig, col, acc[m][n]);
;           }
;           ss += __shfl_xor(ss, 16); ss += __shfl_xor(ss, 32);
;           if (fq_e == 0) epi.rowsum(g, rig, nt * 2 + wc_e, ss);
;         } else {
; #pragma unroll
;           for (int n = 0; n < 8; ++n) {
;             const int col = nt * 256 + wc_e * 128 + n * 16 + fq_e * 4;
;             if (col < N) epi.c4(g, rig, col, acc[m][n]);
;           }
;         }
	v_cvt_pk_bf16_f32 v102, v102, v103
	v_cvt_pk_bf16_f32 v103, v104, v105
	v_or_b32_e32 v254, 0x70, v132
	v_mov_b64_e32 v[254:255], s[20:21]
	v_mad_u64_u32 v[254:255], s[58:59], v134, s56, v[254:255]
	v_mad_i32_i24 v255, v135, s56, v255
	v_mul_f32_e32 v98, v98, v251
	v_mul_f32_e32 v99, v99, v251
	v_mul_f32_e32 v100, v100, v251
	v_mul_f32_e32 v101, v101, v251
	v_cvt_pk_bf16_f32 v104, v98, v99
	v_cvt_pk_bf16_f32 v105, v100, v101
	v_lshl_add_u64 v[100:101], v[132:133], 1, v[254:255]
	s_nop 1
	v_permlane16_swap_b32 v102, v104
	v_permlane16_swap_b32 v103, v105
	v_lshl_add_u64 v[254:255], v[100:101], 0, v[252:253]
	s_nop 0
	global_store_dwordx4 v[254:255], v[102:105], off offset:192
	s_nop 1
	v_or_b32_e32 v98, 16, v136
	v_ashrrev_i32_e32 v99, 31, v98
	v_lshl_add_u64 v[98:99], v[138:139], 0, v[98:99]
	v_lshl_add_u64 v[100:101], v[134:135], 2, s[22:23]
	v_add_co_u32_e32 v102, vcc, 0x10000, v100
	s_nop 1
	v_addc_co_u32_e32 v103, vcc, 0, v101, vcc
	v_add_co_u32_e32 v104, vcc, 0x20000, v100
	s_nop 1
	v_addc_co_u32_e32 v105, vcc, 0, v101, vcc
	v_add_co_u32_e32 v106, vcc, 0x30000, v100
	s_nop 1
	v_addc_co_u32_e32 v107, vcc, 0, v101, vcc
	global_load_dword v108, v[100:101], off offset:64
	s_nop 0
	global_load_dword v102, v[102:103], off offset:64
	s_nop 0
	global_load_dword v103, v[104:105], off offset:64
	s_nop 0
	global_load_dword v104, v[106:107], off offset:64
	v_mov_b64_e32 v[100:101], s[20:21]
	v_mad_u64_u32 v[100:101], s[58:59], v98, s56, v[100:101]
	v_mad_i32_i24 v101, v99, s56, v101
	s_waitcnt vmcnt(3)
	v_add_f32_e32 v105, 0, v108
	s_waitcnt vmcnt(2)
	v_add_f32_e32 v102, v105, v102
	s_waitcnt vmcnt(1)
	v_add_f32_e32 v102, v102, v103
	s_waitcnt vmcnt(0)
	v_add_f32_e32 v102, v102, v104
	v_fmamk_f32 v102, v102, 0x3b000000, v176
	v_mul_f32_e32 v103, 0x4b800000, v102
	v_cmp_gt_f32_e32 vcc, s51, v102
	s_nop 1
	v_cndmask_b32_e32 v102, v102, v103, vcc
	v_rsq_f32_e32 v102, v102
	s_nop 0
	v_mul_f32_e32 v103, 0x45800000, v102
	v_cndmask_b32_e32 v102, v102, v103, vcc
	v_mov_b32_e32 v251, v102
	v_mul_f32_e32 v94, v94, v102
	v_mul_f32_e32 v95, v95, v102
	v_mul_f32_e32 v96, v96, v102
	v_mul_f32_e32 v97, v97, v102
	v_cvt_pk_bf16_f32 v94, v94, v95
	v_cvt_pk_bf16_f32 v95, v96, v97
	v_mov_b64_e32 v[254:255], s[20:21]
	v_mad_u64_u32 v[254:255], s[58:59], v98, s56, v[254:255]
	v_mad_i32_i24 v255, v99, s56, v255
	v_mul_f32_e32 v90, v90, v251
	v_mul_f32_e32 v91, v91, v251
	v_mul_f32_e32 v92, v92, v251
	v_mul_f32_e32 v93, v93, v251
	v_cvt_pk_bf16_f32 v96, v90, v91
	v_cvt_pk_bf16_f32 v97, v92, v93
	v_lshl_add_u64 v[92:93], v[132:133], 1, v[254:255]
	s_nop 1
	v_permlane16_swap_b32 v94, v96
	v_permlane16_swap_b32 v95, v97
	v_lshl_add_u64 v[254:255], v[92:93], 0, v[252:253]
	s_nop 0
	global_store_dwordx4 v[254:255], v[94:97], off
	s_nop 1
	v_mov_b64_e32 v[90:91], s[20:21]
	v_mad_u64_u32 v[90:91], s[58:59], v98, s56, v[90:91]
	v_mad_i32_i24 v91, v99, s56, v91
	v_mul_f32_e32 v86, v86, v251
	v_mul_f32_e32 v87, v87, v251
	v_mul_f32_e32 v88, v88, v251
	v_mul_f32_e32 v89, v89, v251
	v_cvt_pk_bf16_f32 v86, v86, v87
	v_cvt_pk_bf16_f32 v87, v88, v89
	v_mov_b64_e32 v[254:255], s[20:21]
	v_mad_u64_u32 v[254:255], s[58:59], v98, s56, v[254:255]
	v_mad_i32_i24 v255, v99, s56, v255
	v_mul_f32_e32 v82, v82, v251
	v_mul_f32_e32 v83, v83, v251
	v_mul_f32_e32 v84, v84, v251
	v_mul_f32_e32 v85, v85, v251
	v_cvt_pk_bf16_f32 v88, v82, v83
	v_cvt_pk_bf16_f32 v89, v84, v85
	v_lshl_add_u64 v[84:85], v[132:133], 1, v[254:255]
	s_nop 1
	v_permlane16_swap_b32 v86, v88
	v_permlane16_swap_b32 v87, v89
	v_lshl_add_u64 v[254:255], v[84:85], 0, v[252:253]
	s_nop 0
	global_store_dwordx4 v[254:255], v[86:89], off offset:64
	s_nop 1
	v_mov_b64_e32 v[82:83], s[20:21]
	v_mad_u64_u32 v[82:83], s[58:59], v98, s56, v[82:83]
	v_mad_i32_i24 v83, v99, s56, v83
	v_mul_f32_e32 v78, v78, v251
	v_mul_f32_e32 v79, v79, v251
	v_mul_f32_e32 v80, v80, v251
	v_mul_f32_e32 v81, v81, v251
	v_cvt_pk_bf16_f32 v78, v78, v79
	v_cvt_pk_bf16_f32 v79, v80, v81
	v_mov_b64_e32 v[254:255], s[20:21]
	v_mad_u64_u32 v[254:255], s[58:59], v98, s56, v[254:255]
	v_mad_i32_i24 v255, v99, s56, v255
	v_mul_f32_e32 v74, v74, v251
	v_mul_f32_e32 v75, v75, v251
	v_mul_f32_e32 v76, v76, v251
	v_mul_f32_e32 v77, v77, v251
	v_cvt_pk_bf16_f32 v80, v74, v75
	v_cvt_pk_bf16_f32 v81, v76, v77
	v_lshl_add_u64 v[76:77], v[132:133], 1, v[254:255]
	s_nop 1
	v_permlane16_swap_b32 v78, v80
	v_permlane16_swap_b32 v79, v81
	v_lshl_add_u64 v[254:255], v[76:77], 0, v[252:253]
	s_nop 0
	global_store_dwordx4 v[254:255], v[78:81], off offset:128
	s_nop 1
	v_mov_b64_e32 v[74:75], s[20:21]
	v_mad_u64_u32 v[74:75], s[58:59], v98, s56, v[74:75]
	v_mad_i32_i24 v75, v99, s56, v75
	v_mul_f32_e32 v70, v70, v251
	v_mul_f32_e32 v71, v71, v251
	v_mul_f32_e32 v72, v72, v251
	v_mul_f32_e32 v73, v73, v251
	v_cvt_pk_bf16_f32 v70, v70, v71
	v_cvt_pk_bf16_f32 v71, v72, v73
	v_mov_b64_e32 v[254:255], s[20:21]
	v_mad_u64_u32 v[254:255], s[58:59], v98, s56, v[254:255]
	v_mad_i32_i24 v255, v99, s56, v255
	v_mul_f32_e32 v66, v66, v251
	v_mul_f32_e32 v67, v67, v251
	v_mul_f32_e32 v68, v68, v251
	v_mul_f32_e32 v69, v69, v251
	v_cvt_pk_bf16_f32 v72, v66, v67
	v_cvt_pk_bf16_f32 v73, v68, v69
	v_lshl_add_u64 v[68:69], v[132:133], 1, v[254:255]
	s_nop 1
	v_permlane16_swap_b32 v70, v72
	v_permlane16_swap_b32 v71, v73
	v_lshl_add_u64 v[254:255], v[68:69], 0, v[252:253]
	s_nop 0
	global_store_dwordx4 v[254:255], v[70:73], off offset:192
	s_nop 1
	v_or_b32_e32 v66, 32, v136
	v_ashrrev_i32_e32 v67, 31, v66
	v_lshl_add_u64 v[66:67], v[138:139], 0, v[66:67]
	v_lshl_add_u64 v[68:69], v[134:135], 2, s[22:23]
	v_add_co_u32_e32 v70, vcc, 0x10000, v68
	s_nop 1
	v_addc_co_u32_e32 v71, vcc, 0, v69, vcc
	v_add_co_u32_e32 v72, vcc, 0x20000, v68
	s_nop 1
	v_addc_co_u32_e32 v73, vcc, 0, v69, vcc
	v_add_co_u32_e32 v74, vcc, 0x30000, v68
	s_nop 1
	v_addc_co_u32_e32 v75, vcc, 0, v69, vcc
	global_load_dword v76, v[68:69], off offset:128
	s_nop 0
	global_load_dword v70, v[70:71], off offset:128
	s_nop 0
	global_load_dword v71, v[72:73], off offset:128
	s_nop 0
	global_load_dword v72, v[74:75], off offset:128
	v_mov_b64_e32 v[68:69], s[20:21]
	v_mad_u64_u32 v[68:69], s[58:59], v66, s56, v[68:69]
	v_mad_i32_i24 v69, v67, s56, v69
	s_waitcnt vmcnt(3)
; __device__ __forceinline__ unsigned pack2(float a, float b) { unsigned r; asm("v_cvt_pk_bf16_f32 %0, %1, %2" : "=v"(r) : "v"(a), "v"(b)); return r; }
;   __device__ __forceinline__ void c4(int g, int rig, int col, f32x4 v) const {
;     const size_t row = (size_t)g * ostride + rig;
;     float s = 1.f;
;     if (NP > 0) {
;       float t = 0.f;
; #pragma unroll
;       for (int q = 0; q < NP; ++q) t += part[(size_t)q * pstride + row];
;       s = rsqrtf(t * inv_n + 1e-6f);
;     }
;     uint2 u; u.x = pack2(v[0] * s, v[1] * s); u.y = pack2(v[2] * s, v[3] * s);
;     *(uint2*)(out + row * ld + col) = u;
;   }
; template <bool SWAP, class Epi, bool THIN = false> ...
;     ...
; #pragma unroll
;           for (int n = 0; n < 8; ++n) {
;             const int col = nt * 256 + wc_e * 128 + n * 16 + fq_e * 4;
;             if (col < N) epi.c4(g, rig, col, acc[m][n]);
;           }
;         }
	v_add_f32_e32 v73, 0, v76
	s_waitcnt vmcnt(2)
	v_add_f32_e32 v70, v73, v70
	s_waitcnt vmcnt(1)
	v_add_f32_e32 v70, v70, v71
	s_waitcnt vmcnt(0)
	v_add_f32_e32 v70, v70, v72
	v_fmamk_f32 v70, v70, 0x3b000000, v176
	v_mul_f32_e32 v71, 0x4b800000, v70
	v_cmp_gt_f32_e32 vcc, s51, v70
	s_nop 1
	v_cndmask_b32_e32 v70, v70, v71, vcc
	v_rsq_f32_e32 v70, v70
	s_nop 0
	v_mul_f32_e32 v71, 0x45800000, v70
	v_cndmask_b32_e32 v70, v70, v71, vcc
	v_mov_b32_e32 v251, v70
	v_mul_f32_e32 v62, v62, v70
	v_mul_f32_e32 v63, v63, v70
	v_mul_f32_e32 v64, v64, v70
	v_mul_f32_e32 v65, v65, v70
	v_cvt_pk_bf16_f32 v62, v62, v63
	v_cvt_pk_bf16_f32 v63, v64, v65
	v_mov_b64_e32 v[254:255], s[20:21]
	v_mad_u64_u32 v[254:255], s[58:59], v66, s56, v[254:255]
	v_mad_i32_i24 v255, v67, s56, v255
	v_mul_f32_e32 v58, v58, v251
	v_mul_f32_e32 v59, v59, v251
	v_mul_f32_e32 v60, v60, v251
	v_mul_f32_e32 v61, v61, v251
	v_cvt_pk_bf16_f32 v64, v58, v59
	v_cvt_pk_bf16_f32 v65, v60, v61
	v_lshl_add_u64 v[60:61], v[132:133], 1, v[254:255]
	s_nop 1
	v_permlane16_swap_b32 v62, v64
	v_permlane16_swap_b32 v63, v65
	v_lshl_add_u64 v[254:255], v[60:61], 0, v[252:253]
	s_nop 0
	global_store_dwordx4 v[254:255], v[62:65], off
	s_nop 1
	v_mov_b64_e32 v[58:59], s[20:21]
	v_mad_u64_u32 v[58:59], s[58:59], v66, s56, v[58:59]
	v_mad_i32_i24 v59, v67, s56, v59
	v_mul_f32_e32 v54, v54, v251
	v_mul_f32_e32 v55, v55, v251
	v_mul_f32_e32 v56, v56, v251
	v_mul_f32_e32 v57, v57, v251
	v_cvt_pk_bf16_f32 v54, v54, v55
	v_cvt_pk_bf16_f32 v55, v56, v57
	v_mov_b64_e32 v[254:255], s[20:21]
	v_mad_u64_u32 v[254:255], s[58:59], v66, s56, v[254:255]
	v_mad_i32_i24 v255, v67, s56, v255
	v_mul_f32_e32 v50, v50, v251
	v_mul_f32_e32 v51, v51, v251
	v_mul_f32_e32 v52, v52, v251
	v_mul_f32_e32 v53, v53, v251
	v_cvt_pk_bf16_f32 v56, v50, v51
	v_cvt_pk_bf16_f32 v57, v52, v53
	v_lshl_add_u64 v[52:53], v[132:133], 1, v[254:255]
	s_nop 1
	v_permlane16_swap_b32 v54, v56
	v_permlane16_swap_b32 v55, v57
	v_lshl_add_u64 v[254:255], v[52:53], 0, v[252:253]
	s_nop 0
	global_store_dwordx4 v[254:255], v[54:57], off offset:64
	s_nop 1
	v_mov_b64_e32 v[50:51], s[20:21]
	v_mad_u64_u32 v[50:51], s[58:59], v66, s56, v[50:51]
	v_mad_i32_i24 v51, v67, s56, v51
	v_mul_f32_e32 v46, v46, v251
	v_mul_f32_e32 v47, v47, v251
	v_mul_f32_e32 v48, v48, v251
	v_mul_f32_e32 v49, v49, v251
	v_cvt_pk_bf16_f32 v46, v46, v47
	v_cvt_pk_bf16_f32 v47, v48, v49
	v_mov_b64_e32 v[254:255], s[20:21]
	v_mad_u64_u32 v[254:255], s[58:59], v66, s56, v[254:255]
	v_mad_i32_i24 v255, v67, s56, v255
	v_mul_f32_e32 v42, v42, v251
	v_mul_f32_e32 v43, v43, v251
	v_mul_f32_e32 v44, v44, v251
	v_mul_f32_e32 v45, v45, v251
	v_cvt_pk_bf16_f32 v48, v42, v43
	v_cvt_pk_bf16_f32 v49, v44, v45
	v_lshl_add_u64 v[44:45], v[132:133], 1, v[254:255]
	s_nop 1
	v_permlane16_swap_b32 v46, v48
	v_permlane16_swap_b32 v47, v49
	v_lshl_add_u64 v[254:255], v[44:45], 0, v[252:253]
	s_nop 0
	global_store_dwordx4 v[254:255], v[46:49], off offset:128
	s_nop 1
	v_mov_b64_e32 v[42:43], s[20:21]
	v_mad_u64_u32 v[42:43], s[58:59], v66, s56, v[42:43]
	v_mad_i32_i24 v43, v67, s56, v43
	v_mul_f32_e32 v38, v38, v251
	v_mul_f32_e32 v39, v39, v251
	v_mul_f32_e32 v40, v40, v251
	v_mul_f32_e32 v41, v41, v251
	v_cvt_pk_bf16_f32 v38, v38, v39
	v_cvt_pk_bf16_f32 v39, v40, v41
	v_mov_b64_e32 v[254:255], s[20:21]
	v_mad_u64_u32 v[254:255], s[58:59], v66, s56, v[254:255]
	v_mad_i32_i24 v255, v67, s56, v255
	v_mul_f32_e32 v34, v34, v251
	v_mul_f32_e32 v35, v35, v251
	v_mul_f32_e32 v36, v36, v251
	v_mul_f32_e32 v37, v37, v251
	v_cvt_pk_bf16_f32 v40, v34, v35
	v_cvt_pk_bf16_f32 v41, v36, v37
	v_lshl_add_u64 v[36:37], v[132:133], 1, v[254:255]
	s_nop 1
	v_permlane16_swap_b32 v38, v40
	v_permlane16_swap_b32 v39, v41
	v_lshl_add_u64 v[254:255], v[36:37], 0, v[252:253]
	s_nop 0
	global_store_dwordx4 v[254:255], v[38:41], off offset:192
	s_nop 1
	v_or_b32_e32 v34, 48, v136
	v_ashrrev_i32_e32 v35, 31, v34
	v_lshl_add_u64 v[34:35], v[138:139], 0, v[34:35]
	v_lshl_add_u64 v[36:37], v[134:135], 2, s[22:23]
	v_add_co_u32_e32 v38, vcc, 0x10000, v36
	s_nop 1
	v_addc_co_u32_e32 v39, vcc, 0, v37, vcc
	v_add_co_u32_e32 v40, vcc, 0x20000, v36
	s_nop 1
	v_addc_co_u32_e32 v41, vcc, 0, v37, vcc
	v_add_co_u32_e32 v42, vcc, 0x30000, v36
	s_nop 1
	v_addc_co_u32_e32 v43, vcc, 0, v37, vcc
	global_load_dword v44, v[36:37], off offset:192
	s_nop 0
	global_load_dword v38, v[38:39], off offset:192
	s_nop 0
	global_load_dword v39, v[40:41], off offset:192
	s_nop 0
	global_load_dword v40, v[42:43], off offset:192
	v_mov_b64_e32 v[36:37], s[20:21]
	v_mad_u64_u32 v[36:37], s[4:5], v34, s56, v[36:37]
	v_mad_i32_i24 v37, v35, s56, v37
	s_waitcnt vmcnt(3)
; __device__ __forceinline__ unsigned pack2(float a, float b) { unsigned r; asm("v_cvt_pk_bf16_f32 %0, %1, %2" : "=v"(r) : "v"(a), "v"(b)); return r; }
;   __device__ __forceinline__ void c4(int g, int rig, int col, f32x4 v) const {
;     const size_t row = (size_t)g * ostride + rig;
;     float s = 1.f;
;     if (NP > 0) {
;       float t = 0.f;
; #pragma unroll
;       for (int q = 0; q < NP; ++q) t += part[(size_t)q * pstride + row];
;       s = rsqrtf(t * inv_n + 1e-6f);
;     }
;     uint2 u; u.x = pack2(v[0] * s, v[1] * s); u.y = pack2(v[2] * s, v[3] * s);
;     *(uint2*)(out + row * ld + col) = u;
;   }
; template <bool SWAP, class Epi, bool THIN = false> ...
;     ...
; #pragma unroll
;           for (int n = 0; n < 8; ++n) {
;             const int col = nt * 256 + wc_e * 128 + n * 16 + fq_e * 4;
;             if (col < N) epi.c4(g, rig, col, acc[m][n]);
;           }
;         }
	v_add_f32_e32 v41, 0, v44
	s_waitcnt vmcnt(2)
	v_add_f32_e32 v38, v41, v38
	s_waitcnt vmcnt(1)
	v_add_f32_e32 v38, v38, v39
	s_waitcnt vmcnt(0)
	v_add_f32_e32 v38, v38, v40
	v_fmamk_f32 v38, v38, 0x3b000000, v176
	v_mul_f32_e32 v39, 0x4b800000, v38
	v_cmp_gt_f32_e32 vcc, s51, v38
	s_nop 1
	v_cndmask_b32_e32 v38, v38, v39, vcc
	v_rsq_f32_e32 v38, v38
	s_nop 0
	v_mul_f32_e32 v39, 0x45800000, v38
	v_cndmask_b32_e32 v38, v38, v39, vcc
	v_mov_b32_e32 v251, v38
	v_mul_f32_e32 v30, v30, v38
	v_mul_f32_e32 v31, v31, v38
	v_mul_f32_e32 v32, v32, v38
	v_mul_f32_e32 v33, v33, v38
	v_cvt_pk_bf16_f32 v30, v30, v31
	v_cvt_pk_bf16_f32 v31, v32, v33
	v_mov_b64_e32 v[254:255], s[20:21]
	v_mad_u64_u32 v[254:255], s[6:7], v34, s56, v[254:255]
	v_mad_i32_i24 v255, v35, s56, v255
	v_mul_f32_e32 v26, v26, v251
	v_mul_f32_e32 v27, v27, v251
	v_mul_f32_e32 v28, v28, v251
	v_mul_f32_e32 v29, v29, v251
	v_cvt_pk_bf16_f32 v32, v26, v27
	v_cvt_pk_bf16_f32 v33, v28, v29
	v_lshl_add_u64 v[28:29], v[132:133], 1, v[254:255]
	s_nop 1
	v_permlane16_swap_b32 v30, v32
	v_permlane16_swap_b32 v31, v33
	v_lshl_add_u64 v[254:255], v[28:29], 0, v[252:253]
	s_nop 0
	global_store_dwordx4 v[254:255], v[30:33], off
	s_nop 1
	v_mov_b64_e32 v[26:27], s[20:21]
	v_mad_u64_u32 v[26:27], s[6:7], v34, s56, v[26:27]
	v_mad_i32_i24 v27, v35, s56, v27
	v_mul_f32_e32 v22, v22, v251
	v_mul_f32_e32 v23, v23, v251
	v_mul_f32_e32 v24, v24, v251
	v_mul_f32_e32 v25, v25, v251
	v_cvt_pk_bf16_f32 v22, v22, v23
	v_cvt_pk_bf16_f32 v23, v24, v25
	v_mov_b64_e32 v[254:255], s[20:21]
	v_mad_u64_u32 v[254:255], s[6:7], v34, s56, v[254:255]
	v_mad_i32_i24 v255, v35, s56, v255
	v_mul_f32_e32 v18, v18, v251
	v_mul_f32_e32 v19, v19, v251
	v_mul_f32_e32 v20, v20, v251
	v_mul_f32_e32 v21, v21, v251
	v_cvt_pk_bf16_f32 v24, v18, v19
	v_cvt_pk_bf16_f32 v25, v20, v21
	v_lshl_add_u64 v[20:21], v[132:133], 1, v[254:255]
	s_nop 1
	v_permlane16_swap_b32 v22, v24
	v_permlane16_swap_b32 v23, v25
	v_lshl_add_u64 v[254:255], v[20:21], 0, v[252:253]
	s_nop 0
	global_store_dwordx4 v[254:255], v[22:25], off offset:64
	s_nop 1
	v_mov_b64_e32 v[18:19], s[20:21]
	v_mad_u64_u32 v[18:19], s[6:7], v34, s56, v[18:19]
	v_mad_i32_i24 v19, v35, s56, v19
	v_mul_f32_e32 v14, v14, v251
	v_mul_f32_e32 v15, v15, v251
	v_mul_f32_e32 v16, v16, v251
	v_mul_f32_e32 v17, v17, v251
	v_cvt_pk_bf16_f32 v14, v14, v15
	v_cvt_pk_bf16_f32 v15, v16, v17
	v_mov_b64_e32 v[254:255], s[20:21]
	v_mad_u64_u32 v[254:255], s[6:7], v34, s56, v[254:255]
	v_mad_i32_i24 v255, v35, s56, v255
	v_mul_f32_e32 v10, v10, v251
	v_mul_f32_e32 v11, v11, v251
	v_mul_f32_e32 v12, v12, v251
	v_mul_f32_e32 v13, v13, v251
	v_cvt_pk_bf16_f32 v16, v10, v11
	v_cvt_pk_bf16_f32 v17, v12, v13
	v_lshl_add_u64 v[12:13], v[132:133], 1, v[254:255]
	s_nop 1
	v_permlane16_swap_b32 v14, v16
	v_permlane16_swap_b32 v15, v17
	v_lshl_add_u64 v[254:255], v[12:13], 0, v[252:253]
	s_nop 0
	global_store_dwordx4 v[254:255], v[14:17], off offset:128
	s_nop 1
	v_mov_b64_e32 v[10:11], s[20:21]
	v_mad_u64_u32 v[10:11], s[6:7], v34, s56, v[10:11]
	v_mad_i32_i24 v11, v35, s56, v11
	v_mul_f32_e32 v6, v6, v251
	v_mul_f32_e32 v7, v7, v251
	v_mul_f32_e32 v8, v8, v251
	v_mul_f32_e32 v9, v9, v251
	v_cvt_pk_bf16_f32 v6, v6, v7
	v_cvt_pk_bf16_f32 v7, v8, v9
	v_mov_b64_e32 v[254:255], s[20:21]
	v_mad_u64_u32 v[254:255], s[6:7], v34, s56, v[254:255]
	v_mad_i32_i24 v255, v35, s56, v255
	v_mul_f32_e32 v2, v2, v251
	v_mul_f32_e32 v3, v3, v251
	v_mul_f32_e32 v4, v4, v251
	v_mul_f32_e32 v5, v5, v251
	v_cvt_pk_bf16_f32 v8, v2, v3
	v_cvt_pk_bf16_f32 v9, v4, v5
	v_lshl_add_u64 v[4:5], v[132:133], 1, v[254:255]
	s_nop 1
	v_permlane16_swap_b32 v6, v8
	v_permlane16_swap_b32 v7, v9
	v_lshl_add_u64 v[254:255], v[4:5], 0, v[252:253]
	s_nop 0
	global_store_dwordx4 v[254:255], v[6:9], off offset:192
	s_nop 1
	s_branch .LBB0_1748

; #define GLDS16(gp, lp) __builtin_amdgcn_global_load_lds((const unsigned*)(gp), (__attribute__((address_space(3))) unsigned*)(lp), 16, 0, 0)
; template <bool SWAP, class Epi, bool THIN = false> ...
;     ...
;     if (w < full * 8 * NT) { const int sr = w / (8 * NT), rem = w - sr * 8 * NT; nt = rem >> 3; mt = sr * 8 + (rem & 7); }
;     else { const int w2 = w - full * 8 * NT, rl = MT - full * 8; nt = w2 / rl; mt = full * 8 + (w2 - nt * rl); }
;     unsigned ap[4], bp[4];
; #pragma unroll
;     for (int i = 0; i < 4; ++i) {
;       const int r = (tid >> 3) + 64 * i;
;       const int cs = tid & 7;
;       const int c = ((cs ^ ((r >> 1) & 7)) << 3);
;       const int sub = 2 * mt + (r >> 7);
;       const int g = sub / tpg, ti = sub - g * tpg;
;       int rig = ti * step - halo + (r & 127); rig = rig < 0 ? 0 : (rig > grows - 1 ? grows - 1 : rig);
;       ap[i] = (unsigned)((g * a_gstride + a_goff + rig) * lda + c);
;       int br = nt * 256 + r; br = br > N - 1 ? N - 1 : br;
;       bp[i] = (unsigned)(br * K + c);
;     }
;     const bool have_next = false;
;     f32x4 acc[4][8];
; #pragma unroll
;     for (int m = 0; m < 4; ++m)
; #pragma unroll
;       for (int n = 0; n < 8; ++n) acc[m][n] = (f32x4){0.f, 0.f, 0.f, 0.f};
;     if (!pre_issued) {
; #pragma unroll
;       for (int i = 0; i < 4; ++i) { GLDS16(A + (size_t)ap[i], smem + tid * 16 + i * 8192); GLDS16(Bt + (size_t)bp[i], smem + 32768 + tid * 16 + i * 8192); }
;     }
;     pre_issued = have_next;
;     for (int st = 0; st < ns; ++st) {
;       asm volatile("s_waitcnt vmcnt(0)" ::: "memory");
;       __builtin_amdgcn_s_barrier();
;       asm volatile("" ::: "memory");
;       if (st + 1 < ns) {
;         char* nb = smem + ((st + 1) & 1) * 65536;
;         const int ko = (st + 1) * 64;
; #pragma unroll
;         for (int i = 0; i < 4; ++i) { GLDS16(A + (size_t)(ap[i] + ko), nb + tid * 16 + i * 8192); GLDS16(Bt + (size_t)(bp[i] + ko), nb + 32768 + tid * 16 + i * 8192); }
;     ...
;       bf16x8 afA[4], afB[4], bfb[2][2];
; #pragma unroll
;       for (int m = 0; m < 4; ++m) afA[m] = *(const bf16x8*)(sa + m * 2048 + ((fq ^ swz) << 4));
; #pragma unroll
;       for (int n = 0; n < 2; ++n) bfb[0][n] = *(const bf16x8*)(sb + n * 2048 + ((fq ^ swz) << 4));
.LBB0_1818:
	s_add_i32 s4, s33, 0xfffffe80
	s_ashr_i32 s5, s4, 31
	s_lshr_b32 s5, s5, 27
	s_add_i32 s4, s4, s5
	s_ashr_i32 s4, s4, 5
	s_lshl_b32 s5, s4, 4
	s_and_b32 s6, s38, 14
	s_or_b32 s5, s5, s6
	v_add_u32_e32 v2, s5, v139
	v_mul_hi_i32 v3, v2, s42
	v_lshrrev_b32_e32 v4, 31, v3
	v_ashrrev_i32_e32 v3, 2, v3
	v_add_u32_e32 v4, v3, v4
	v_mad_u64_u32 v[2:3], s[6:7], v4, s43, v[2:3]
	v_lshl_or_b32 v3, v2, 7, v140
	v_min_i32_e32 v3, 0x8ff, v3
	v_cmp_lt_i32_e32 vcc, -1, v2
	s_lshl_b32 s4, s4, 10
	s_sub_i32 s4, s40, s4
	v_cndmask_b32_e32 v2, 0, v3, vcc
	v_mad_u64_u32 v[2:3], s[6:7], v4, s44, v[2:3]
	s_and_b32 s4, s4, 0xffffff00
	v_mad_u64_u32 v[2:3], s[6:7], v2, s45, v[130:131]
	v_add_u32_e32 v3, s4, v131
	v_min_i32_e32 v3, 0x3ff, v3
	v_add_u32_e32 v4, s5, v142
	v_lshl_or_b32 v132, v3, 8, v130
	v_mul_hi_i32 v3, v4, s42
	v_lshrrev_b32_e32 v5, 31, v3
	v_ashrrev_i32_e32 v3, 2, v3
	v_add_u32_e32 v3, v3, v5
	v_mad_u64_u32 v[4:5], s[6:7], v3, s43, v[4:5]
	v_lshl_or_b32 v5, v4, 7, v143
	v_min_i32_e32 v5, 0x8ff, v5
	v_cmp_lt_i32_e32 vcc, -1, v4
	v_add_u32_e32 v6, s5, v145
	v_add_u32_e32 v8, s5, v147
	v_cndmask_b32_e32 v4, 0, v5, vcc
	v_mad_u64_u32 v[4:5], s[6:7], v3, s44, v[4:5]
	v_add_u32_e32 v3, s4, v141
	v_min_i32_e32 v3, 0x3ff, v3
	v_mad_u64_u32 v[4:5], s[6:7], v4, s45, v[130:131]
	v_lshl_or_b32 v12, v3, 8, v130
	v_mul_hi_i32 v3, v6, s42
	v_lshrrev_b32_e32 v5, 31, v3
	v_ashrrev_i32_e32 v3, 2, v3
	v_add_u32_e32 v3, v3, v5
	v_mad_u64_u32 v[6:7], s[6:7], v3, s43, v[6:7]
	v_lshl_or_b32 v5, v6, 7, v140
	v_min_i32_e32 v5, 0x8ff, v5
	v_cmp_lt_i32_e32 vcc, -1, v6
	v_readfirstlane_b32 s37, v138
	s_mov_b32 m0, s37
	v_cndmask_b32_e32 v6, 0, v5, vcc
	v_mad_u64_u32 v[6:7], s[6:7], v3, s44, v[6:7]
	v_add_u32_e32 v3, s4, v144
	v_min_i32_e32 v3, 0x3ff, v3
	v_lshl_or_b32 v14, v3, 8, v130
	v_mul_hi_i32 v3, v8, s42
	v_lshrrev_b32_e32 v5, 31, v3
	v_ashrrev_i32_e32 v3, 2, v3
	v_add_u32_e32 v3, v3, v5
	v_mad_u64_u32 v[8:9], s[6:7], v3, s43, v[8:9]
	v_lshl_or_b32 v5, v8, 7, v148
	v_min_i32_e32 v5, 0x8ff, v5
	v_cmp_lt_i32_e32 vcc, -1, v8
	v_readfirstlane_b32 s15, v149
	v_readfirstlane_b32 s14, v150
	v_cndmask_b32_e32 v8, 0, v5, vcc
	v_mad_u64_u32 v[8:9], s[6:7], v3, s44, v[8:9]
	v_add_u32_e32 v3, s4, v146
	v_min_i32_e32 v3, 0x3ff, v3
	v_lshl_or_b32 v16, v3, 8, v130
	v_mov_b32_e32 v3, v133
	v_lshl_add_u64 v[10:11], v[2:3], 1, s[28:29]
	global_load_lds_dwordx4 v[10:11], off
	v_lshl_add_u64 v[10:11], v[132:133], 1, s[20:21]
	s_mov_b32 m0, s15
	v_mov_b32_e32 v5, v133
	v_mad_u64_u32 v[6:7], s[6:7], v6, s45, v[130:131]
	global_load_lds_dwordx4 v[10:11], off
	v_lshl_add_u64 v[18:19], v[4:5], 1, s[28:29]
	s_mov_b32 m0, s14
	v_mov_b32_e32 v13, v133
	v_readfirstlane_b32 s17, v151
	global_load_lds_dwordx4 v[18:19], off
	v_lshl_add_u64 v[12:13], v[12:13], 1, s[20:21]
	s_mov_b32 m0, s17
	v_mov_b32_e32 v7, v133
	v_readfirstlane_b32 s16, v152
	v_mad_u64_u32 v[8:9], s[6:7], v8, s45, v[130:131]
	global_load_lds_dwordx4 v[12:13], off
	v_lshl_add_u64 v[18:19], v[6:7], 1, s[28:29]
	s_mov_b32 m0, s16
	v_mov_b32_e32 v15, v133
	v_readfirstlane_b32 s19, v153
	global_load_lds_dwordx4 v[18:19], off
	v_lshl_add_u64 v[14:15], v[14:15], 1, s[20:21]
	s_mov_b32 m0, s19
	v_mov_b32_e32 v9, v133
	v_readfirstlane_b32 s18, v154
	global_load_lds_dwordx4 v[14:15], off
	v_lshl_add_u64 v[18:19], v[8:9], 1, s[28:29]
	s_mov_b32 m0, s18
	v_mov_b32_e32 v17, v133
	v_readfirstlane_b32 s36, v155
	global_load_lds_dwordx4 v[18:19], off
	v_lshl_add_u64 v[16:17], v[16:17], 1, s[20:21]
	s_mov_b32 m0, s36
	v_add_u32_e32 v132, 64, v2
	global_load_lds_dwordx4 v[16:17], off
	v_readfirstlane_b32 s13, v156
	s_waitcnt vmcnt(0)
	s_barrier
	v_lshl_add_u64 v[18:19], v[132:133], 1, s[28:29]
	s_mov_b32 m0, s13
	v_readfirstlane_b32 s8, v157
	global_load_lds_dwordx4 v[18:19], off
	v_lshl_add_u64 v[18:19], v[10:11], 0, s[24:25]
	s_mov_b32 m0, s8
	v_add_u32_e32 v132, 64, v4
	v_readfirstlane_b32 s7, v158
	global_load_lds_dwordx4 v[18:19], off
	v_lshl_add_u64 v[18:19], v[132:133], 1, s[28:29]
	s_mov_b32 m0, s7
	v_readfirstlane_b32 s6, v159
	global_load_lds_dwordx4 v[18:19], off
	v_lshl_add_u64 v[18:19], v[12:13], 0, s[24:25]
	s_mov_b32 m0, s6
	v_add_u32_e32 v132, 64, v6
	v_readfirstlane_b32 s9, v160
	global_load_lds_dwordx4 v[18:19], off
	v_lshl_add_u64 v[18:19], v[132:133], 1, s[28:29]
	s_mov_b32 m0, s9
	v_readfirstlane_b32 s10, v161
	global_load_lds_dwordx4 v[18:19], off
	v_lshl_add_u64 v[18:19], v[14:15], 0, s[24:25]
	s_mov_b32 m0, s10
	v_add_u32_e32 v132, 64, v8
	v_readfirstlane_b32 s11, v162
	global_load_lds_dwordx4 v[18:19], off
	v_lshl_add_u64 v[18:19], v[132:133], 1, s[28:29]
	s_mov_b32 m0, s11
	v_readfirstlane_b32 s12, v163
	global_load_lds_dwordx4 v[18:19], off
	v_lshl_add_u64 v[18:19], v[16:17], 0, s[24:25]
	s_mov_b32 m0, s12
	s_nop 0
	global_load_lds_dwordx4 v[18:19], off
	ds_read_b128 v[18:21], v164
	ds_read_b128 v[22:25], v164 offset:2048
	ds_read_b128 v[26:29], v164 offset:4096
	ds_read_b128 v[30:33], v164 offset:6144
	ds_read_b128 v[34:37], v165 offset:32768
	ds_read_b128 v[38:41], v165 offset:34816
	ds_read_b128 v[42:45], v165 offset:36864
	ds_read_b128 v[46:49], v165 offset:38912
	ds_read_b128 v[74:77], v165 offset:40960
	ds_read_b128 v[78:81], v165 offset:43008
	s_waitcnt lgkmcnt(0)
; template <bool SWAP, class Epi, bool THIN = false> ...
;     ...
;       bf16x8 afA[4], afB[4], bfb[2][2];
; #pragma unroll
;       for (int m = 0; m < 4; ++m) afA[m] = *(const bf16x8*)(sa + m * 2048 + ((fq ^ swz) << 4));
; #pragma unroll
;       for (int n = 0; n < 2; ++n) bfb[0][n] = *(const bf16x8*)(sb + n * 2048 + ((fq ^ swz) << 4));
; #pragma unroll
;       for (int gq = 0; gq < 8; ++gq) {
;         const int ks = gq >> 2, nh = gq & 3;
;         if (gq < 7) {
;           const int ks2 = (gq + 1) >> 2, nh2 = (gq + 1) & 3;
; #pragma unroll
;           for (int n = 0; n < 2; ++n) bfb[(gq + 1) & 1][n] = *(const bf16x8*)(sb + (nh2 * 2 + n) * 2048 + (((ks2 * 4 + fq) ^ swz) << 4));
;         }
;         if (gq == 3) {
; #pragma unroll
;           for (int m = 0; m < 4; ++m) afB[m] = *(const bf16x8*)(sa + m * 2048 + (((4 + fq) ^ swz) << 4));
;         }
;         __builtin_amdgcn_sched_barrier(0);
; #pragma unroll
;         for (int m = 0; m < 4; ++m)
; #pragma unroll
;           for (int n = 0; n < 2; ++n) {
;             const bf16x8 av = ks ? afB[m] : afA[m];
;             acc[m][nh * 2 + n] = SWAP ? __builtin_amdgcn_mfma_f32_16x16x32_bf16(bfb[gq & 1][n], av, acc[m][nh * 2 + n], 0, 0, 0)
;                                       : __builtin_amdgcn_mfma_f32_16x16x32_bf16(av, bfb[gq & 1][n], acc[m][nh * 2 + n], 0, 0, 0);
;           }
;       }
	v_mfma_f32_16x16x32_bf16 v[50:53], v[34:37], v[18:21], 0
	v_mfma_f32_16x16x32_bf16 v[54:57], v[38:41], v[18:21], 0
	v_mfma_f32_16x16x32_bf16 v[58:61], v[34:37], v[22:25], 0
	v_mfma_f32_16x16x32_bf16 v[62:65], v[38:41], v[22:25], 0
	v_mfma_f32_16x16x32_bf16 v[66:69], v[34:37], v[26:29], 0
	v_mfma_f32_16x16x32_bf16 v[70:73], v[38:41], v[26:29], 0
	v_mfma_f32_16x16x32_bf16 v[34:37], v[34:37], v[30:33], 0
	v_mfma_f32_16x16x32_bf16 v[38:41], v[38:41], v[30:33], 0
	ds_read_b128 v[106:109], v165 offset:45056
	ds_read_b128 v[110:113], v165 offset:47104
	v_mfma_f32_16x16x32_bf16 v[82:85], v[42:45], v[18:21], 0
	v_mfma_f32_16x16x32_bf16 v[86:89], v[46:49], v[18:21], 0
	v_mfma_f32_16x16x32_bf16 v[90:93], v[42:45], v[22:25], 0
	v_mfma_f32_16x16x32_bf16 v[94:97], v[46:49], v[22:25], 0
	v_mfma_f32_16x16x32_bf16 v[98:101], v[42:45], v[26:29], 0
	v_mfma_f32_16x16x32_bf16 v[102:105], v[46:49], v[26:29], 0
	v_mfma_f32_16x16x32_bf16 v[42:45], v[42:45], v[30:33], 0
	v_mfma_f32_16x16x32_bf16 v[46:49], v[46:49], v[30:33], 0
	ds_read_b128 v[178:181], v166 offset:32768
	ds_read_b128 v[182:185], v166 offset:34816
	ds_read_b128 v[186:189], v167
	ds_read_b128 v[190:193], v167 offset:2048
	ds_read_b128 v[194:197], v167 offset:4096
	ds_read_b128 v[198:201], v167 offset:6144
	v_mfma_f32_16x16x32_bf16 v[114:117], v[74:77], v[18:21], 0
	v_mfma_f32_16x16x32_bf16 v[118:121], v[78:81], v[18:21], 0
	v_mfma_f32_16x16x32_bf16 v[122:125], v[74:77], v[22:25], 0
	v_mfma_f32_16x16x32_bf16 v[126:129], v[78:81], v[22:25], 0
	v_mfma_f32_16x16x32_bf16 v[134:137], v[74:77], v[26:29], 0
	v_mfma_f32_16x16x32_bf16 v[174:177], v[78:81], v[26:29], 0
	v_mfma_f32_16x16x32_bf16 v[74:77], v[74:77], v[30:33], 0
	v_mfma_f32_16x16x32_bf16 v[78:81], v[78:81], v[30:33], 0
	ds_read_b128 v[214:217], v166 offset:36864
	ds_read_b128 v[218:221], v166 offset:38912
	s_waitcnt lgkmcnt(0)
	v_mfma_f32_16x16x32_bf16 v[202:205], v[106:109], v[18:21], 0
	v_mfma_f32_16x16x32_bf16 v[18:21], v[110:113], v[18:21], 0
	v_mfma_f32_16x16x32_bf16 v[206:209], v[106:109], v[22:25], 0
	v_mfma_f32_16x16x32_bf16 v[22:25], v[110:113], v[22:25], 0
	v_mfma_f32_16x16x32_bf16 v[210:213], v[106:109], v[26:29], 0
	v_mfma_f32_16x16x32_bf16 v[26:29], v[110:113], v[26:29], 0
	v_mfma_f32_16x16x32_bf16 v[106:109], v[106:109], v[30:33], 0
	v_mfma_f32_16x16x32_bf16 v[30:33], v[110:113], v[30:33], 0
	v_mfma_f32_16x16x32_bf16 v[50:53], v[178:181], v[186:189], v[50:53]
	v_mfma_f32_16x16x32_bf16 v[58:61], v[178:181], v[190:193], v[58:61]
	v_mfma_f32_16x16x32_bf16 v[66:69], v[178:181], v[194:197], v[66:69]
	v_mfma_f32_16x16x32_bf16 v[34:37], v[178:181], v[198:201], v[34:37]
	ds_read_b128 v[110:113], v166 offset:40960
	ds_read_b128 v[178:181], v166 offset:43008
	v_mfma_f32_16x16x32_bf16 v[54:57], v[182:185], v[186:189], v[54:57]
	v_mfma_f32_16x16x32_bf16 v[62:65], v[182:185], v[190:193], v[62:65]
	v_mfma_f32_16x16x32_bf16 v[70:73], v[182:185], v[194:197], v[70:73]
	v_mfma_f32_16x16x32_bf16 v[38:41], v[182:185], v[198:201], v[38:41]
	v_mfma_f32_16x16x32_bf16 v[82:85], v[214:217], v[186:189], v[82:85]
	v_mfma_f32_16x16x32_bf16 v[90:93], v[214:217], v[190:193], v[90:93]
	v_mfma_f32_16x16x32_bf16 v[98:101], v[214:217], v[194:197], v[98:101]
	v_mfma_f32_16x16x32_bf16 v[42:45], v[214:217], v[198:201], v[42:45]
	ds_read_b128 v[182:185], v166 offset:45056
	ds_read_b128 v[214:217], v166 offset:47104
	v_mfma_f32_16x16x32_bf16 v[86:89], v[218:221], v[186:189], v[86:89]
	v_mfma_f32_16x16x32_bf16 v[94:97], v[218:221], v[190:193], v[94:97]
	v_mfma_f32_16x16x32_bf16 v[102:105], v[218:221], v[194:197], v[102:105]
	v_mfma_f32_16x16x32_bf16 v[46:49], v[218:221], v[198:201], v[46:49]
	s_waitcnt lgkmcnt(0)
	v_mfma_f32_16x16x32_bf16 v[114:117], v[110:113], v[186:189], v[114:117]
	v_mfma_f32_16x16x32_bf16 v[118:121], v[178:181], v[186:189], v[118:121]
	v_mfma_f32_16x16x32_bf16 v[122:125], v[110:113], v[190:193], v[122:125]
	v_mfma_f32_16x16x32_bf16 v[126:129], v[178:181], v[190:193], v[126:129]
	v_mfma_f32_16x16x32_bf16 v[134:137], v[110:113], v[194:197], v[134:137]
	v_mfma_f32_16x16x32_bf16 v[74:77], v[110:113], v[198:201], v[74:77]
	v_mfma_f32_16x16x32_bf16 v[78:81], v[178:181], v[198:201], v[78:81]
	v_mfma_f32_16x16x32_bf16 v[174:177], v[178:181], v[194:197], v[174:177]
	v_add_u32_e32 v132, 0x80, v2
	s_mov_b32 m0, s37
	v_mfma_f32_16x16x32_bf16 v[110:113], v[182:185], v[186:189], v[202:205]
	s_waitcnt vmcnt(0)
	s_barrier
; template <bool SWAP, class Epi, bool THIN = false> ...
;     ...
;     for (int st = 0; st < ns; ++st) {
;       asm volatile("s_waitcnt vmcnt(0)" ::: "memory");
;       __builtin_amdgcn_s_barrier();
;       asm volatile("" ::: "memory");
;       if (st + 1 < ns) {
;         char* nb = smem + ((st + 1) & 1) * 65536;
;         const int ko = (st + 1) * 64;
; #pragma unroll
;         for (int i = 0; i < 4; ++i) { GLDS16(A + (size_t)(ap[i] + ko), nb + tid * 16 + i * 8192); GLDS16(Bt + (size_t)(bp[i] + ko), nb + 32768 + tid * 16 + i * 8192); }
;       }
;       const char* sa = smem + (st & 1) * 65536 + (wr * 64 + fr) * 128;
;       const char* sb = smem + (st & 1) * 65536 + 32768 + (wc * 128 + fr) * 128;
;       if constexpr (THIN) {
;         if (wc == 0) {
; #pragma unroll
;           for (int ks = 0; ks < 2; ++ks) {
;             bf16x8 af[4], bf[2];
; #pragma unroll
;             for (int m = 0; m < 4; ++m) af[m] = *(const bf16x8*)(sa + m * 2048 + (((ks * 4 + fq) ^ swz) << 4));
; #pragma unroll
;             for (int n = 0; n < 2; ++n) bf[n] = *(const bf16x8*)(sb + n * 2048 + (((ks * 4 + fq) ^ swz) << 4));
; #pragma unroll
;             for (int m = 0; m < 4; ++m)
; #pragma unroll
;               for (int n = 0; n < 2; ++n)
;                 acc[m][n] = SWAP ? __builtin_amdgcn_mfma_f32_16x16x32_bf16(bf[n], af[m], acc[m][n], 0, 0, 0)
;                                  : __builtin_amdgcn_mfma_f32_16x16x32_bf16(af[m], bf[n], acc[m][n], 0, 0, 0);
;           }
;         }
;       } else {
;       bf16x8 afA[4], afB[4], bfb[2][2];
; #pragma unroll
;       for (int m = 0; m < 4; ++m) afA[m] = *(const bf16x8*)(sa + m * 2048 + ((fq ^ swz) << 4));
; #pragma unroll
;       for (int n = 0; n < 2; ++n) bfb[0][n] = *(const bf16x8*)(sb + n * 2048 + ((fq ^ swz) << 4));
; #pragma unroll
;       for (int gq = 0; gq < 8; ++gq) {
;         const int ks = gq >> 2, nh = gq & 3;
;         if (gq < 7) {
;           const int ks2 = (gq + 1) >> 2, nh2 = (gq + 1) & 3;
; #pragma unroll
;           for (int n = 0; n < 2; ++n) bfb[(gq + 1) & 1][n] = *(const bf16x8*)(sb + (nh2 * 2 + n) * 2048 + (((ks2 * 4 + fq) ^ swz) << 4));
;         }
;         if (gq == 3) {
; #pragma unroll
;           for (int m = 0; m < 4; ++m) afB[m] = *(const bf16x8*)(sa + m * 2048 + (((4 + fq) ^ swz) << 4));
;         }
;         __builtin_amdgcn_sched_barrier(0);
; #pragma unroll
	v_mfma_f32_16x16x32_bf16 v[18:21], v[214:217], v[186:189], v[18:21]
	v_lshl_add_u64 v[186:187], v[132:133], 1, s[28:29]
	global_load_lds_dwordx4 v[186:187], off
	v_lshl_add_u64 v[186:187], v[10:11], 0, s[30:31]
	s_mov_b32 m0, s15
	v_add_u32_e32 v132, 0x80, v4
	v_mfma_f32_16x16x32_bf16 v[178:181], v[182:185], v[190:193], v[206:209]
	global_load_lds_dwordx4 v[186:187], off
	s_mov_b32 m0, s14
	v_mfma_f32_16x16x32_bf16 v[22:25], v[214:217], v[190:193], v[22:25]
	v_lshl_add_u64 v[190:191], v[132:133], 1, s[28:29]
	global_load_lds_dwordx4 v[190:191], off
	v_lshl_add_u64 v[190:191], v[12:13], 0, s[30:31]
	s_mov_b32 m0, s17
	v_add_u32_e32 v132, 0x80, v6
	global_load_lds_dwordx4 v[190:191], off
	v_lshl_add_u64 v[190:191], v[132:133], 1, s[28:29]
	s_mov_b32 m0, s16
	v_add_u32_e32 v132, 0x80, v8
	global_load_lds_dwordx4 v[190:191], off
	v_lshl_add_u64 v[190:191], v[14:15], 0, s[30:31]
	s_mov_b32 m0, s19
	v_mfma_f32_16x16x32_bf16 v[186:189], v[182:185], v[194:197], v[210:213]
	global_load_lds_dwordx4 v[190:191], off
	v_lshl_add_u64 v[190:191], v[132:133], 1, s[28:29]
	s_mov_b32 m0, s18
	v_mfma_f32_16x16x32_bf16 v[26:29], v[214:217], v[194:197], v[26:29]
	global_load_lds_dwordx4 v[190:191], off
	v_lshl_add_u64 v[190:191], v[16:17], 0, s[30:31]
	s_mov_b32 m0, s36
	v_mfma_f32_16x16x32_bf16 v[106:109], v[182:185], v[198:201], v[106:109]
	global_load_lds_dwordx4 v[190:191], off
	ds_read_b128 v[182:185], v168
	ds_read_b128 v[190:193], v168 offset:2048
	ds_read_b128 v[194:197], v168 offset:4096
	ds_read_b128 v[202:205], v168 offset:6144
	ds_read_b128 v[206:209], v169
	ds_read_b128 v[210:213], v169 offset:2048
	ds_read_b128 v[218:221], v169 offset:4096
	ds_read_b128 v[222:225], v169 offset:6144
	v_mfma_f32_16x16x32_bf16 v[30:33], v[214:217], v[198:201], v[30:33]
	s_waitcnt lgkmcnt(0)
	v_mfma_f32_16x16x32_bf16 v[50:53], v[206:209], v[182:185], v[50:53]
	v_mfma_f32_16x16x32_bf16 v[58:61], v[206:209], v[190:193], v[58:61]
	v_mfma_f32_16x16x32_bf16 v[66:69], v[206:209], v[194:197], v[66:69]
	v_mfma_f32_16x16x32_bf16 v[34:37], v[206:209], v[202:205], v[34:37]
	ds_read_b128 v[198:201], v169 offset:8192
	ds_read_b128 v[206:209], v169 offset:10240
	v_mfma_f32_16x16x32_bf16 v[54:57], v[210:213], v[182:185], v[54:57]
	v_mfma_f32_16x16x32_bf16 v[62:65], v[210:213], v[190:193], v[62:65]
	v_mfma_f32_16x16x32_bf16 v[70:73], v[210:213], v[194:197], v[70:73]
	v_mfma_f32_16x16x32_bf16 v[38:41], v[210:213], v[202:205], v[38:41]
	ds_read_b128 v[210:213], v169 offset:12288
	ds_read_b128 v[214:217], v169 offset:14336
	v_mfma_f32_16x16x32_bf16 v[82:85], v[218:221], v[182:185], v[82:85]
	v_mfma_f32_16x16x32_bf16 v[86:89], v[222:225], v[182:185], v[86:89]
	v_mfma_f32_16x16x32_bf16 v[90:93], v[218:221], v[190:193], v[90:93]
	v_mfma_f32_16x16x32_bf16 v[94:97], v[222:225], v[190:193], v[94:97]
	v_mfma_f32_16x16x32_bf16 v[98:101], v[218:221], v[194:197], v[98:101]
	v_mfma_f32_16x16x32_bf16 v[102:105], v[222:225], v[194:197], v[102:105]
	v_mfma_f32_16x16x32_bf16 v[42:45], v[218:221], v[202:205], v[42:45]
	v_mfma_f32_16x16x32_bf16 v[46:49], v[222:225], v[202:205], v[46:49]
	s_waitcnt lgkmcnt(0)
	v_mfma_f32_16x16x32_bf16 v[114:117], v[198:201], v[182:185], v[114:117]
	ds_read_b128 v[218:221], v170
	ds_read_b128 v[222:225], v170 offset:2048
	v_mfma_f32_16x16x32_bf16 v[122:125], v[198:201], v[190:193], v[122:125]
	v_mfma_f32_16x16x32_bf16 v[134:137], v[198:201], v[194:197], v[134:137]
	v_mfma_f32_16x16x32_bf16 v[74:77], v[198:201], v[202:205], v[74:77]
	ds_read_b128 v[198:201], v171
	ds_read_b128 v[226:229], v171 offset:2048
	ds_read_b128 v[230:233], v171 offset:4096
	ds_read_b128 v[234:237], v171 offset:6144
	v_mfma_f32_16x16x32_bf16 v[118:121], v[206:209], v[182:185], v[118:121]
	v_mfma_f32_16x16x32_bf16 v[126:129], v[206:209], v[190:193], v[126:129]
	v_mfma_f32_16x16x32_bf16 v[78:81], v[206:209], v[202:205], v[78:81]
	v_mfma_f32_16x16x32_bf16 v[174:177], v[206:209], v[194:197], v[174:177]
	v_mfma_f32_16x16x32_bf16 v[110:113], v[210:213], v[182:185], v[110:113]
	v_mfma_f32_16x16x32_bf16 v[18:21], v[214:217], v[182:185], v[18:21]
	v_mfma_f32_16x16x32_bf16 v[178:181], v[210:213], v[190:193], v[178:181]
	v_mfma_f32_16x16x32_bf16 v[22:25], v[214:217], v[190:193], v[22:25]
	v_mfma_f32_16x16x32_bf16 v[182:185], v[210:213], v[194:197], v[186:189]
	s_nop 2
	ds_read_b128 v[186:189], v170 offset:4096
	ds_read_b128 v[190:193], v170 offset:6144
	v_mfma_f32_16x16x32_bf16 v[26:29], v[214:217], v[194:197], v[26:29]
	v_mfma_f32_16x16x32_bf16 v[106:109], v[210:213], v[202:205], v[106:109]
	v_mfma_f32_16x16x32_bf16 v[30:33], v[214:217], v[202:205], v[30:33]
	ds_read_b128 v[194:197], v170 offset:8192
	ds_read_b128 v[202:205], v170 offset:10240
	s_waitcnt lgkmcnt(0)
	v_mfma_f32_16x16x32_bf16 v[50:53], v[218:221], v[198:201], v[50:53]
	v_mfma_f32_16x16x32_bf16 v[54:57], v[222:225], v[198:201], v[54:57]
	v_mfma_f32_16x16x32_bf16 v[58:61], v[218:221], v[226:229], v[58:61]
	v_mfma_f32_16x16x32_bf16 v[62:65], v[222:225], v[226:229], v[62:65]
	v_mfma_f32_16x16x32_bf16 v[66:69], v[218:221], v[230:233], v[66:69]
	v_mfma_f32_16x16x32_bf16 v[70:73], v[222:225], v[230:233], v[70:73]
	v_mfma_f32_16x16x32_bf16 v[34:37], v[218:221], v[234:237], v[34:37]
	v_mfma_f32_16x16x32_bf16 v[38:41], v[222:225], v[234:237], v[38:41]
	v_mfma_f32_16x16x32_bf16 v[82:85], v[186:189], v[198:201], v[82:85]
	v_mfma_f32_16x16x32_bf16 v[90:93], v[186:189], v[226:229], v[90:93]
	v_mfma_f32_16x16x32_bf16 v[98:101], v[186:189], v[230:233], v[98:101]
	v_mfma_f32_16x16x32_bf16 v[42:45], v[186:189], v[234:237], v[42:45]
	ds_read_b128 v[186:189], v170 offset:12288
	ds_read_b128 v[206:209], v170 offset:14336
	v_mfma_f32_16x16x32_bf16 v[86:89], v[190:193], v[198:201], v[86:89]
	v_mfma_f32_16x16x32_bf16 v[94:97], v[190:193], v[226:229], v[94:97]
	v_mfma_f32_16x16x32_bf16 v[102:105], v[190:193], v[230:233], v[102:105]
	v_mfma_f32_16x16x32_bf16 v[46:49], v[190:193], v[234:237], v[46:49]
	v_mfma_f32_16x16x32_bf16 v[114:117], v[194:197], v[198:201], v[114:117]
	v_mfma_f32_16x16x32_bf16 v[118:121], v[202:205], v[198:201], v[118:121]
	v_mfma_f32_16x16x32_bf16 v[122:125], v[194:197], v[226:229], v[122:125]
	v_mfma_f32_16x16x32_bf16 v[126:129], v[202:205], v[226:229], v[126:129]
	v_mfma_f32_16x16x32_bf16 v[134:137], v[194:197], v[230:233], v[134:137]
	v_mfma_f32_16x16x32_bf16 v[74:77], v[194:197], v[234:237], v[74:77]
	v_mfma_f32_16x16x32_bf16 v[78:81], v[202:205], v[234:237], v[78:81]
	v_mfma_f32_16x16x32_bf16 v[174:177], v[202:205], v[230:233], v[174:177]
	v_add_u32_e32 v132, 0xc0, v2
	s_mov_b32 m0, s13
	s_waitcnt vmcnt(0)
	s_barrier
; template <bool SWAP, class Epi, bool THIN = false> ...
;     ...
;     for (int st = 0; st < ns; ++st) {
;       asm volatile("s_waitcnt vmcnt(0)" ::: "memory");
;       __builtin_amdgcn_s_barrier();
;       asm volatile("" ::: "memory");
;       if (st + 1 < ns) {
;         char* nb = smem + ((st + 1) & 1) * 65536;
;         const int ko = (st + 1) * 64;
; #pragma unroll
;         for (int i = 0; i < 4; ++i) { GLDS16(A + (size_t)(ap[i] + ko), nb + tid * 16 + i * 8192); GLDS16(Bt + (size_t)(bp[i] + ko), nb + 32768 + tid * 16 + i * 8192); }
;       }
;       const char* sa = smem + (st & 1) * 65536 + (wr * 64 + fr) * 128;
;       const char* sb = smem + (st & 1) * 65536 + 32768 + (wc * 128 + fr) * 128;
;       if constexpr (THIN) {
;         if (wc == 0) {
; #pragma unroll
;           for (int ks = 0; ks < 2; ++ks) {
;             bf16x8 af[4], bf[2];
; #pragma unroll
;             for (int m = 0; m < 4; ++m) af[m] = *(const bf16x8*)(sa + m * 2048 + (((ks * 4 + fq) ^ swz) << 4));
; #pragma unroll
;             for (int n = 0; n < 2; ++n) bf[n] = *(const bf16x8*)(sb + n * 2048 + (((ks * 4 + fq) ^ swz) << 4));
; #pragma unroll
;             for (int m = 0; m < 4; ++m)
; #pragma unroll
;               for (int n = 0; n < 2; ++n)
;                 acc[m][n] = SWAP ? __builtin_amdgcn_mfma_f32_16x16x32_bf16(bf[n], af[m], acc[m][n], 0, 0, 0)
;                                  : __builtin_amdgcn_mfma_f32_16x16x32_bf16(af[m], bf[n], acc[m][n], 0, 0, 0);
;           }
;         }
;       } else {
;       bf16x8 afA[4], afB[4], bfb[2][2];
; #pragma unroll
;       for (int m = 0; m < 4; ++m) afA[m] = *(const bf16x8*)(sa + m * 2048 + ((fq ^ swz) << 4));
; #pragma unroll
;       for (int n = 0; n < 2; ++n) bfb[0][n] = *(const bf16x8*)(sb + n * 2048 + ((fq ^ swz) << 4));
; #pragma unroll
;       for (int gq = 0; gq < 8; ++gq) {
;         const int ks = gq >> 2, nh = gq & 3;
;         if (gq < 7) {
;           const int ks2 = (gq + 1) >> 2, nh2 = (gq + 1) & 3;
; #pragma unroll
;           for (int n = 0; n < 2; ++n) bfb[(gq + 1) & 1][n] = *(const bf16x8*)(sb + (nh2 * 2 + n) * 2048 + (((ks2 * 4 + fq) ^ swz) << 4));
;         }
;         if (gq == 3) {
; #pragma unroll
;           for (int m = 0; m < 4; ++m) afB[m] = *(const bf16x8*)(sa + m * 2048 + (((4 + fq) ^ swz) << 4));
;         }
;         __builtin_amdgcn_sched_barrier(0);
; #pragma unroll
	v_lshl_add_u64 v[2:3], v[132:133], 1, s[28:29]
	global_load_lds_dwordx4 v[2:3], off
	v_lshl_add_u64 v[2:3], v[10:11], 0, s[34:35]
	s_mov_b32 m0, s8
	v_add_u32_e32 v132, 0xc0, v4
	global_load_lds_dwordx4 v[2:3], off
	v_lshl_add_u64 v[10:11], v[132:133], 1, s[28:29]
	s_mov_b32 m0, s7
	v_add_u32_e32 v132, 0xc0, v6
	global_load_lds_dwordx4 v[10:11], off
	v_lshl_add_u64 v[10:11], v[12:13], 0, s[34:35]
	s_mov_b32 m0, s6
	v_lshl_add_u64 v[6:7], v[132:133], 1, s[28:29]
	global_load_lds_dwordx4 v[10:11], off
	s_mov_b32 m0, s9
	v_add_u32_e32 v132, 0xc0, v8
	global_load_lds_dwordx4 v[6:7], off
	v_lshl_add_u64 v[6:7], v[14:15], 0, s[34:35]
	s_mov_b32 m0, s10
	s_waitcnt lgkmcnt(0)
	v_mfma_f32_16x16x32_bf16 v[110:113], v[186:189], v[198:201], v[110:113]
	global_load_lds_dwordx4 v[6:7], off
	v_lshl_add_u64 v[6:7], v[132:133], 1, s[28:29]
	s_mov_b32 m0, s11
	v_mfma_f32_16x16x32_bf16 v[18:21], v[206:209], v[198:201], v[18:21]
	global_load_lds_dwordx4 v[6:7], off
	v_lshl_add_u64 v[6:7], v[16:17], 0, s[34:35]
	s_mov_b32 m0, s12
	v_mfma_f32_16x16x32_bf16 v[178:181], v[186:189], v[226:229], v[178:181]
	global_load_lds_dwordx4 v[6:7], off
	v_mfma_f32_16x16x32_bf16 v[2:5], v[186:189], v[230:233], v[182:185]
	v_mfma_f32_16x16x32_bf16 v[6:9], v[186:189], v[234:237], v[106:109]
	ds_read_b128 v[10:13], v164
	ds_read_b128 v[14:17], v164 offset:2048
	s_nop 0
	ds_read_b128 v[106:109], v164 offset:4096
	ds_read_b128 v[182:185], v164 offset:6144
	ds_read_b128 v[186:189], v165 offset:32768
	ds_read_b128 v[190:193], v165 offset:34816
	ds_read_b128 v[194:197], v165 offset:36864
	ds_read_b128 v[198:201], v165 offset:38912
	v_mfma_f32_16x16x32_bf16 v[22:25], v[206:209], v[226:229], v[22:25]
	v_mfma_f32_16x16x32_bf16 v[26:29], v[206:209], v[230:233], v[26:29]
	v_mfma_f32_16x16x32_bf16 v[30:33], v[206:209], v[234:237], v[30:33]
	s_waitcnt lgkmcnt(0)
	v_mfma_f32_16x16x32_bf16 v[50:53], v[186:189], v[10:13], v[50:53]
	v_mfma_f32_16x16x32_bf16 v[58:61], v[186:189], v[14:17], v[58:61]
	v_mfma_f32_16x16x32_bf16 v[66:69], v[186:189], v[106:109], v[66:69]
	v_mfma_f32_16x16x32_bf16 v[34:37], v[186:189], v[182:185], v[34:37]
	ds_read_b128 v[186:189], v165 offset:40960
	ds_read_b128 v[202:205], v165 offset:43008
	v_mfma_f32_16x16x32_bf16 v[54:57], v[190:193], v[10:13], v[54:57]
	v_mfma_f32_16x16x32_bf16 v[62:65], v[190:193], v[14:17], v[62:65]
	v_mfma_f32_16x16x32_bf16 v[70:73], v[190:193], v[106:109], v[70:73]
	v_mfma_f32_16x16x32_bf16 v[38:41], v[190:193], v[182:185], v[38:41]
	v_mfma_f32_16x16x32_bf16 v[82:85], v[194:197], v[10:13], v[82:85]
	v_mfma_f32_16x16x32_bf16 v[90:93], v[194:197], v[14:17], v[90:93]
	v_mfma_f32_16x16x32_bf16 v[98:101], v[194:197], v[106:109], v[98:101]
	v_mfma_f32_16x16x32_bf16 v[42:45], v[194:197], v[182:185], v[42:45]
	ds_read_b128 v[190:193], v165 offset:45056
	ds_read_b128 v[194:197], v165 offset:47104
	v_mfma_f32_16x16x32_bf16 v[86:89], v[198:201], v[10:13], v[86:89]
	v_mfma_f32_16x16x32_bf16 v[94:97], v[198:201], v[14:17], v[94:97]
	v_mfma_f32_16x16x32_bf16 v[102:105], v[198:201], v[106:109], v[102:105]
	v_mfma_f32_16x16x32_bf16 v[46:49], v[198:201], v[182:185], v[46:49]
	s_waitcnt lgkmcnt(0)
	v_mfma_f32_16x16x32_bf16 v[114:117], v[186:189], v[10:13], v[114:117]
	ds_read_b128 v[198:201], v166 offset:32768
	ds_read_b128 v[206:209], v166 offset:34816
	v_mfma_f32_16x16x32_bf16 v[122:125], v[186:189], v[14:17], v[122:125]
	v_mfma_f32_16x16x32_bf16 v[134:137], v[186:189], v[106:109], v[134:137]
	v_mfma_f32_16x16x32_bf16 v[74:77], v[186:189], v[182:185], v[74:77]
	ds_read_b128 v[186:189], v167
	ds_read_b128 v[210:213], v167 offset:2048
	ds_read_b128 v[214:217], v167 offset:4096
	ds_read_b128 v[218:221], v167 offset:6144
	v_mfma_f32_16x16x32_bf16 v[118:121], v[202:205], v[10:13], v[118:121]
	v_mfma_f32_16x16x32_bf16 v[126:129], v[202:205], v[14:17], v[126:129]
	v_mfma_f32_16x16x32_bf16 v[78:81], v[202:205], v[182:185], v[78:81]
	v_mfma_f32_16x16x32_bf16 v[174:177], v[202:205], v[106:109], v[174:177]
	v_mfma_f32_16x16x32_bf16 v[110:113], v[190:193], v[10:13], v[110:113]
	v_mfma_f32_16x16x32_bf16 v[10:13], v[194:197], v[10:13], v[18:21]
	v_mfma_f32_16x16x32_bf16 v[18:21], v[190:193], v[14:17], v[178:181]
	v_mfma_f32_16x16x32_bf16 v[14:17], v[194:197], v[14:17], v[22:25]
	v_mfma_f32_16x16x32_bf16 v[2:5], v[190:193], v[106:109], v[2:5]
	v_mfma_f32_16x16x32_bf16 v[22:25], v[194:197], v[106:109], v[26:29]
	s_nop 2
	ds_read_b128 v[26:29], v166 offset:36864
	ds_read_b128 v[106:109], v166 offset:38912
	v_mfma_f32_16x16x32_bf16 v[6:9], v[190:193], v[182:185], v[6:9]
	v_mfma_f32_16x16x32_bf16 v[30:33], v[194:197], v[182:185], v[30:33]
	ds_read_b128 v[178:181], v166 offset:40960
	ds_read_b128 v[182:185], v166 offset:43008
	s_waitcnt lgkmcnt(0)
	v_mfma_f32_16x16x32_bf16 v[50:53], v[198:201], v[186:189], v[50:53]
	v_mfma_f32_16x16x32_bf16 v[54:57], v[206:209], v[186:189], v[54:57]
	v_mfma_f32_16x16x32_bf16 v[58:61], v[198:201], v[210:213], v[58:61]
	v_mfma_f32_16x16x32_bf16 v[62:65], v[206:209], v[210:213], v[62:65]
	v_mfma_f32_16x16x32_bf16 v[66:69], v[198:201], v[214:217], v[66:69]
	v_mfma_f32_16x16x32_bf16 v[70:73], v[206:209], v[214:217], v[70:73]
	v_mfma_f32_16x16x32_bf16 v[34:37], v[198:201], v[218:221], v[34:37]
	v_mfma_f32_16x16x32_bf16 v[38:41], v[206:209], v[218:221], v[38:41]
	v_mfma_f32_16x16x32_bf16 v[82:85], v[26:29], v[186:189], v[82:85]
	v_mfma_f32_16x16x32_bf16 v[90:93], v[26:29], v[210:213], v[90:93]
	v_mfma_f32_16x16x32_bf16 v[98:101], v[26:29], v[214:217], v[98:101]
	v_mfma_f32_16x16x32_bf16 v[26:29], v[26:29], v[218:221], v[42:45]
	s_nop 2
	ds_read_b128 v[42:45], v166 offset:45056
	ds_read_b128 v[190:193], v166 offset:47104
	v_mfma_f32_16x16x32_bf16 v[86:89], v[106:109], v[186:189], v[86:89]
	v_mfma_f32_16x16x32_bf16 v[94:97], v[106:109], v[210:213], v[94:97]
	v_mfma_f32_16x16x32_bf16 v[102:105], v[106:109], v[214:217], v[102:105]
	v_mfma_f32_16x16x32_bf16 v[46:49], v[106:109], v[218:221], v[46:49]
	v_mfma_f32_16x16x32_bf16 v[106:109], v[178:181], v[186:189], v[114:117]
	v_mfma_f32_16x16x32_bf16 v[114:117], v[182:185], v[186:189], v[118:121]
	v_mfma_f32_16x16x32_bf16 v[118:121], v[178:181], v[210:213], v[122:125]
	v_mfma_f32_16x16x32_bf16 v[122:125], v[182:185], v[210:213], v[126:129]
	v_mfma_f32_16x16x32_bf16 v[126:129], v[178:181], v[214:217], v[134:137]
	v_mfma_f32_16x16x32_bf16 v[134:137], v[182:185], v[214:217], v[174:177]
	v_mfma_f32_16x16x32_bf16 v[74:77], v[178:181], v[218:221], v[74:77]
	v_mfma_f32_16x16x32_bf16 v[78:81], v[182:185], v[218:221], v[78:81]
	s_waitcnt vmcnt(0)
	s_barrier
; template <bool SWAP, class Epi, bool THIN = false> ...
;     ...
;       bf16x8 afA[4], afB[4], bfb[2][2];
; #pragma unroll
;       for (int m = 0; m < 4; ++m) afA[m] = *(const bf16x8*)(sa + m * 2048 + ((fq ^ swz) << 4));
; #pragma unroll
;       for (int n = 0; n < 2; ++n) bfb[0][n] = *(const bf16x8*)(sb + n * 2048 + ((fq ^ swz) << 4));
; #pragma unroll
;       for (int gq = 0; gq < 8; ++gq) {
;         const int ks = gq >> 2, nh = gq & 3;
;         if (gq < 7) {
;           const int ks2 = (gq + 1) >> 2, nh2 = (gq + 1) & 3;
; #pragma unroll
;           for (int n = 0; n < 2; ++n) bfb[(gq + 1) & 1][n] = *(const bf16x8*)(sb + (nh2 * 2 + n) * 2048 + (((ks2 * 4 + fq) ^ swz) << 4));
;         }
;         if (gq == 3) {
; #pragma unroll
;           for (int m = 0; m < 4; ++m) afB[m] = *(const bf16x8*)(sa + m * 2048 + (((4 + fq) ^ swz) << 4));
;         }
;         __builtin_amdgcn_sched_barrier(0);
; #pragma unroll
;         for (int m = 0; m < 4; ++m)
; #pragma unroll
;           for (int n = 0; n < 2; ++n) {
;             const bf16x8 av = ks ? afB[m] : afA[m];
;             acc[m][nh * 2 + n] = SWAP ? __builtin_amdgcn_mfma_f32_16x16x32_bf16(bfb[gq & 1][n], av, acc[m][nh * 2 + n], 0, 0, 0)
;                                       : __builtin_amdgcn_mfma_f32_16x16x32_bf16(av, bfb[gq & 1][n], acc[m][nh * 2 + n], 0, 0, 0);
;           }
;       }
;       }
;     }
;     __syncthreads();
	s_waitcnt lgkmcnt(0)
	v_mfma_f32_16x16x32_bf16 v[110:113], v[42:45], v[186:189], v[110:113]
	v_mfma_f32_16x16x32_bf16 v[10:13], v[190:193], v[186:189], v[10:13]
	ds_read_b128 v[174:177], v168
	ds_read_b128 v[178:181], v168 offset:2048
	ds_read_b128 v[182:185], v168 offset:4096
	ds_read_b128 v[186:189], v168 offset:6144
	v_mfma_f32_16x16x32_bf16 v[18:21], v[42:45], v[210:213], v[18:21]
	v_mfma_f32_16x16x32_bf16 v[2:5], v[42:45], v[214:217], v[2:5]
	v_mfma_f32_16x16x32_bf16 v[6:9], v[42:45], v[218:221], v[6:9]
	ds_read_b128 v[42:45], v169
	ds_read_b128 v[194:197], v169 offset:2048
	ds_read_b128 v[198:201], v169 offset:4096
	ds_read_b128 v[202:205], v169 offset:6144
	v_mfma_f32_16x16x32_bf16 v[14:17], v[190:193], v[210:213], v[14:17]
	v_mfma_f32_16x16x32_bf16 v[22:25], v[190:193], v[214:217], v[22:25]
	v_mfma_f32_16x16x32_bf16 v[30:33], v[190:193], v[218:221], v[30:33]
	s_waitcnt lgkmcnt(0)
	v_mfma_f32_16x16x32_bf16 v[50:53], v[42:45], v[174:177], v[50:53]
	v_mfma_f32_16x16x32_bf16 v[58:61], v[42:45], v[178:181], v[58:61]
	v_mfma_f32_16x16x32_bf16 v[66:69], v[42:45], v[182:185], v[66:69]
	v_mfma_f32_16x16x32_bf16 v[34:37], v[42:45], v[186:189], v[34:37]
	ds_read_b128 v[42:45], v169 offset:8192
	ds_read_b128 v[190:193], v169 offset:10240
	v_mfma_f32_16x16x32_bf16 v[54:57], v[194:197], v[174:177], v[54:57]
	v_mfma_f32_16x16x32_bf16 v[62:65], v[194:197], v[178:181], v[62:65]
	v_mfma_f32_16x16x32_bf16 v[70:73], v[194:197], v[182:185], v[70:73]
	v_mfma_f32_16x16x32_bf16 v[38:41], v[194:197], v[186:189], v[38:41]
	v_mfma_f32_16x16x32_bf16 v[82:85], v[198:201], v[174:177], v[82:85]
	v_mfma_f32_16x16x32_bf16 v[194:197], v[198:201], v[178:181], v[90:93]
	v_mfma_f32_16x16x32_bf16 v[98:101], v[198:201], v[182:185], v[98:101]
	v_mfma_f32_16x16x32_bf16 v[198:201], v[198:201], v[186:189], v[26:29]
	s_nop 2
	ds_read_b128 v[26:29], v169 offset:12288
	ds_read_b128 v[90:93], v169 offset:14336
	v_mfma_f32_16x16x32_bf16 v[86:89], v[202:205], v[174:177], v[86:89]
	v_mfma_f32_16x16x32_bf16 v[102:105], v[202:205], v[182:185], v[102:105]
	v_mfma_f32_16x16x32_bf16 v[46:49], v[202:205], v[186:189], v[46:49]
	v_mfma_f32_16x16x32_bf16 v[206:209], v[202:205], v[178:181], v[94:97]
	s_waitcnt lgkmcnt(0)
	v_mfma_f32_16x16x32_bf16 v[202:205], v[190:193], v[174:177], v[114:117]
	v_mfma_f32_16x16x32_bf16 v[210:213], v[42:45], v[178:181], v[118:121]
	s_nop 1
	ds_read_b128 v[114:117], v170
	ds_read_b128 v[118:121], v170 offset:2048
	ds_read_b128 v[226:229], v171
	ds_read_b128 v[230:233], v171 offset:2048
	ds_read_b128 v[234:237], v171 offset:4096
	ds_read_b128 v[238:241], v171 offset:6144
	v_mfma_f32_16x16x32_bf16 v[106:109], v[42:45], v[174:177], v[106:109]
	v_mfma_f32_16x16x32_bf16 v[134:137], v[190:193], v[182:185], v[134:137]
	v_mfma_f32_16x16x32_bf16 v[214:217], v[190:193], v[178:181], v[122:125]
	v_mfma_f32_16x16x32_bf16 v[218:221], v[42:45], v[182:185], v[126:129]
	v_mfma_f32_16x16x32_bf16 v[222:225], v[42:45], v[186:189], v[74:77]
	v_mfma_f32_16x16x32_bf16 v[190:193], v[190:193], v[186:189], v[78:81]
	v_mfma_f32_16x16x32_bf16 v[242:245], v[26:29], v[174:177], v[110:113]
	v_mfma_f32_16x16x32_bf16 v[174:177], v[90:93], v[174:177], v[10:13]
	v_mfma_f32_16x16x32_bf16 v[246:249], v[26:29], v[178:181], v[18:21]
	v_mfma_f32_16x16x32_bf16 v[178:181], v[90:93], v[178:181], v[14:17]
	s_nop 0
	ds_read_b128 v[10:13], v170 offset:4096
	s_nop 0
	ds_read_b128 v[14:17], v170 offset:6144
	v_mfma_f32_16x16x32_bf16 v[2:5], v[26:29], v[182:185], v[2:5]
	v_mfma_f32_16x16x32_bf16 v[6:9], v[26:29], v[186:189], v[6:9]
	v_mfma_f32_16x16x32_bf16 v[182:185], v[90:93], v[182:185], v[22:25]
	v_mfma_f32_16x16x32_bf16 v[186:189], v[90:93], v[186:189], v[30:33]
	s_waitcnt lgkmcnt(0)
	v_mfma_f32_16x16x32_bf16 v[90:93], v[118:121], v[230:233], v[62:65]
	v_mfma_f32_16x16x32_bf16 v[62:65], v[114:117], v[234:237], v[66:69]
	v_mfma_f32_16x16x32_bf16 v[30:33], v[114:117], v[238:241], v[34:37]
	s_nop 2
	ds_read_b128 v[34:37], v170 offset:8192
	ds_read_b128 v[66:69], v170 offset:10240
	v_mfma_f32_16x16x32_bf16 v[126:129], v[114:117], v[226:229], v[50:53]
	v_mfma_f32_16x16x32_bf16 v[122:125], v[118:121], v[226:229], v[54:57]
	v_mfma_f32_16x16x32_bf16 v[94:97], v[114:117], v[230:233], v[58:61]
	v_mfma_f32_16x16x32_bf16 v[58:61], v[118:121], v[234:237], v[70:73]
	v_mfma_f32_16x16x32_bf16 v[26:29], v[118:121], v[238:241], v[38:41]
	v_mfma_f32_16x16x32_bf16 v[114:117], v[14:17], v[226:229], v[86:89]
	v_mfma_f32_16x16x32_bf16 v[86:89], v[10:13], v[230:233], v[194:197]
	v_mfma_f32_16x16x32_bf16 v[22:25], v[10:13], v[238:241], v[198:201]
	s_nop 1
	ds_read_b128 v[194:197], v170 offset:12288
	ds_read_b128 v[198:201], v170 offset:14336
	v_mfma_f32_16x16x32_bf16 v[118:121], v[10:13], v[226:229], v[82:85]
	v_mfma_f32_16x16x32_bf16 v[82:85], v[14:17], v[230:233], v[206:209]
	v_mfma_f32_16x16x32_bf16 v[54:57], v[10:13], v[234:237], v[98:101]
	v_mfma_f32_16x16x32_bf16 v[50:53], v[14:17], v[234:237], v[102:105]
	v_mfma_f32_16x16x32_bf16 v[18:21], v[14:17], v[238:241], v[46:49]
	s_waitcnt lgkmcnt(0)
	v_mfma_f32_16x16x32_bf16 v[110:113], v[34:37], v[226:229], v[106:109]
	v_mfma_f32_16x16x32_bf16 v[106:109], v[66:69], v[226:229], v[202:205]
	v_mfma_f32_16x16x32_bf16 v[78:81], v[34:37], v[230:233], v[210:213]
	v_mfma_f32_16x16x32_bf16 v[74:77], v[66:69], v[230:233], v[214:217]
	v_mfma_f32_16x16x32_bf16 v[46:49], v[34:37], v[234:237], v[218:221]
	v_mfma_f32_16x16x32_bf16 v[42:45], v[66:69], v[234:237], v[134:137]
	v_mfma_f32_16x16x32_bf16 v[14:17], v[34:37], v[238:241], v[222:225]
	v_mfma_f32_16x16x32_bf16 v[10:13], v[66:69], v[238:241], v[190:193]
	s_nop 0
	v_mov_b32_e32 v134, v1
	s_waitcnt vmcnt(0)
	s_barrier
; __device__ __forceinline__ int get_tid512() { int t = threadIdx.x; asm volatile("" : "+v"(t)); return t; }
; __device__ __forceinline__ unsigned pack2(float a, float b) { unsigned r; asm("v_cvt_pk_bf16_f32 %0, %1, %2" : "=v"(r) : "v"(a), "v"(b)); return r; }
;   __device__ __forceinline__ void c4(int g, int rig, int col, f32x4 v) const {
;     const size_t row = (size_t)g * ostride + rig;
;     float s = 1.f;
;     if (NP > 0) {
;       float t = 0.f;
; #pragma unroll
;       for (int q = 0; q < NP; ++q) t += part[(size_t)q * pstride + row];
;       s = rsqrtf(t * inv_n + 1e-6f);
;     }
;     uint2 u; u.x = pack2(v[0] * s, v[1] * s); u.y = pack2(v[2] * s, v[3] * s);
;     *(uint2*)(out + row * ld + col) = u;
;   }
; template <bool SWAP, class Epi, bool THIN = false> ...
;     ...
;     const int te = get_tid512();
;     const int fr_e = te & 15, fq_e = (te & 63) >> 4, wr_e = te >> 7, wc_e = (te >> 6) & 1;
;     const int sub = 2 * mt + (wr_e >> 1);
;     const int g = sub / tpg, ti = sub - g * tpg;
;     const int rig0 = ti * step - halo;
;     const int rw = (wr_e & 1) * 64;
;     if constexpr (Epi::KIND == 0) {
; #pragma unroll
;       for (int m = 0; m < 4; ++m) {
;         const int rig = rig0 + rw + m * 16 + fr_e;
;         if constexpr (Epi::ROWSUM) {
;           float ss = 0.f;
; #pragma unroll
;           for (int n = 0; n < 8; ++n) {
;             const int col = nt * 256 + wc_e * 128 + n * 16 + fq_e * 4;
;             if (col < N) ss += epi.c4(g, rig, col, acc[m][n]);
;           }
;           ss += __shfl_xor(ss, 16); ss += __shfl_xor(ss, 32);
;           if (fq_e == 0) epi.rowsum(g, rig, nt * 2 + wc_e, ss);
;         } else {
; #pragma unroll
;           for (int n = 0; n < 8; ++n) {
;             const int col = nt * 256 + wc_e * 128 + n * 16 + fq_e * 4;
;             if (col < N) epi.c4(g, rig, col, acc[m][n]);
;           }
;         }
	v_mfma_f32_16x16x32_bf16 v[38:41], v[194:197], v[234:237], v[2:5]
	v_ashrrev_i32_e32 v35, 8, v134
	v_add_u32_e32 v35, s5, v35
	v_mul_hi_i32 v36, v35, s42
	v_lshrrev_b32_e32 v37, 31, v36
	v_ashrrev_i32_e32 v36, 2, v36
	v_add_u32_e32 v132, v36, v37
	v_mul_lo_u32 v36, v132, s43
	v_lshrrev_b32_e32 v2, 1, v134
	v_and_b32_e32 v34, 15, v134
	v_add_lshl_u32 v35, v36, v35, 7
	v_and_b32_e32 v2, 64, v2
	v_or3_b32 v136, v35, v2, v34
	v_lshlrev_b32_e32 v2, 1, v134
	v_lshrrev_b32_e32 v3, 2, v134
	v_and_b32_e32 v2, 0x80, v2
	v_and_b32_e32 v3, 12, v3
	v_mfma_f32_16x16x32_bf16 v[102:105], v[194:197], v[226:229], v[242:245]
	v_or3_b32 v134, v3, v2, s4
	v_bfe_u32 v252, v1, 4, 1
	v_mul_u32_u24_e32 v252, 24, v252
	v_mov_b32_e32 v253, 0
	v_ashrrev_i32_e32 v137, 31, v136
	v_cmp_gt_i32_e64 s[10:11], s46, v134
	v_mfma_f32_16x16x32_bf16 v[98:101], v[198:201], v[226:229], v[174:177]
	v_ashrrev_i32_e32 v135, 31, v134
	v_mfma_f32_16x16x32_bf16 v[70:73], v[194:197], v[230:233], v[246:249]
	v_mfma_f32_16x16x32_bf16 v[66:69], v[198:201], v[230:233], v[178:181]
	v_mfma_f32_16x16x32_bf16 v[34:37], v[198:201], v[234:237], v[182:185]
	v_mfma_f32_16x16x32_bf16 v[6:9], v[194:197], v[238:241], v[6:9]
	v_mfma_f32_16x16x32_bf16 v[2:5], v[198:201], v[238:241], v[186:189]
	v_mad_i64_i32 v[174:175], s[6:7], v132, s44, v[136:137]
	v_lshl_add_u64 v[176:177], v[174:175], 2, s[26:27]
	v_add_co_u32_e32 v178, vcc, 0x12000, v176
	v_lshlrev_b64 v[174:175], 11, v[174:175]
	s_nop 0
	v_addc_co_u32_e32 v179, vcc, 0, v177, vcc
	global_load_dword v173, v[176:177], off
	s_nop 0
	global_load_dword v176, v[178:179], off
	v_lshl_add_u64 v[174:175], s[22:23], 0, v[174:175]
	s_waitcnt vmcnt(1)
	v_add_f32_e32 v173, 0, v173
	s_waitcnt vmcnt(0)
	v_add_f32_e32 v173, v173, v176
	v_fmamk_f32 v173, v173, 0x3b800000, v172
	v_mul_f32_e32 v176, 0x4b800000, v173
	v_cmp_gt_f32_e32 vcc, s47, v173
	s_nop 1
	v_cndmask_b32_e32 v173, v173, v176, vcc
	v_rsq_f32_e32 v173, v173
	s_nop 0
	v_mul_f32_e32 v176, 0x45800000, v173
	v_cndmask_b32_e32 v173, v173, v176, vcc
	v_mov_b32_e32 v251, v173
	v_mul_f32_e32 v126, v126, v173
	v_mul_f32_e32 v127, v127, v173
	v_mul_f32_e32 v128, v128, v173
	v_mul_f32_e32 v129, v129, v173
	v_cvt_pk_bf16_f32 v126, v126, v127
	v_cvt_pk_bf16_f32 v127, v128, v129
	v_or_b32_e32 v254, 16, v134
	v_mad_i64_i32 v[254:255], s[6:7], v132, s44, v[136:137]
	v_lshlrev_b64 v[254:255], 11, v[254:255]
	s_nop 0
	v_lshl_add_u64 v[254:255], s[22:23], 0, v[254:255]
	v_mul_f32_e32 v122, v122, v251
	v_mul_f32_e32 v123, v123, v251
	v_mul_f32_e32 v124, v124, v251
	v_mul_f32_e32 v125, v125, v251
	v_cvt_pk_bf16_f32 v128, v122, v123
	v_cvt_pk_bf16_f32 v129, v124, v125
	v_lshl_add_u64 v[124:125], v[134:135], 1, v[254:255]
	s_nop 1
	v_permlane16_swap_b32 v126, v128
	v_permlane16_swap_b32 v127, v129
	v_lshl_add_u64 v[254:255], v[124:125], 0, v[252:253]
	s_nop 0
	global_store_dwordx4 v[254:255], v[126:129], off
	s_nop 1
	v_or_b32_e32 v122, 32, v134
	v_mad_i64_i32 v[122:123], s[6:7], v132, s44, v[136:137]
	v_lshlrev_b64 v[122:123], 11, v[122:123]
	s_nop 0
	v_lshl_add_u64 v[122:123], s[22:23], 0, v[122:123]
	v_mul_f32_e32 v118, v118, v251
	v_mul_f32_e32 v119, v119, v251
	v_mul_f32_e32 v120, v120, v251
	v_mul_f32_e32 v121, v121, v251
	v_cvt_pk_bf16_f32 v118, v118, v119
	v_cvt_pk_bf16_f32 v119, v120, v121
	v_or_b32_e32 v254, 48, v134
	v_mad_i64_i32 v[254:255], s[6:7], v132, s44, v[136:137]
	v_lshlrev_b64 v[254:255], 11, v[254:255]
	s_nop 0
	v_lshl_add_u64 v[254:255], s[22:23], 0, v[254:255]
	v_mul_f32_e32 v114, v114, v251
	v_mul_f32_e32 v115, v115, v251
	v_mul_f32_e32 v116, v116, v251
	v_mul_f32_e32 v117, v117, v251
	v_cvt_pk_bf16_f32 v120, v114, v115
	v_cvt_pk_bf16_f32 v121, v116, v117
	v_lshl_add_u64 v[116:117], v[134:135], 1, v[254:255]
	s_nop 1
	v_permlane16_swap_b32 v118, v120
	v_permlane16_swap_b32 v119, v121
	v_lshl_add_u64 v[254:255], v[116:117], 0, v[252:253]
	s_nop 0
	global_store_dwordx4 v[254:255], v[118:121], off offset:64
	s_nop 1
	v_or_b32_e32 v114, 64, v134
	v_mad_i64_i32 v[114:115], s[6:7], v132, s44, v[136:137]
	v_lshlrev_b64 v[114:115], 11, v[114:115]
	s_nop 0
	v_lshl_add_u64 v[114:115], s[22:23], 0, v[114:115]
	v_mul_f32_e32 v110, v110, v251
	v_mul_f32_e32 v111, v111, v251
	v_mul_f32_e32 v112, v112, v251
	v_mul_f32_e32 v113, v113, v251
	v_cvt_pk_bf16_f32 v110, v110, v111
	v_cvt_pk_bf16_f32 v111, v112, v113
	v_or_b32_e32 v254, 0x50, v134
	v_mad_i64_i32 v[254:255], s[6:7], v132, s44, v[136:137]
	v_lshlrev_b64 v[254:255], 11, v[254:255]
	s_nop 0
	v_lshl_add_u64 v[254:255], s[22:23], 0, v[254:255]
	v_mul_f32_e32 v106, v106, v251
	v_mul_f32_e32 v107, v107, v251
	v_mul_f32_e32 v108, v108, v251
	v_mul_f32_e32 v109, v109, v251
	v_cvt_pk_bf16_f32 v112, v106, v107
	v_cvt_pk_bf16_f32 v113, v108, v109
	v_lshl_add_u64 v[108:109], v[134:135], 1, v[254:255]
	s_nop 1
	v_permlane16_swap_b32 v110, v112
	v_permlane16_swap_b32 v111, v113
	v_lshl_add_u64 v[254:255], v[108:109], 0, v[252:253]
	s_nop 0
	global_store_dwordx4 v[254:255], v[110:113], off offset:128
	s_nop 1
	v_or_b32_e32 v106, 0x60, v134
	v_mad_i64_i32 v[106:107], s[36:37], v132, s44, v[136:137]
	v_lshlrev_b64 v[106:107], 11, v[106:107]
	s_nop 0
	v_lshl_add_u64 v[106:107], s[22:23], 0, v[106:107]
	v_mul_f32_e32 v102, v102, v251
	v_mul_f32_e32 v103, v103, v251
	v_mul_f32_e32 v104, v104, v251
	v_mul_f32_e32 v105, v105, v251
	v_cvt_pk_bf16_f32 v102, v102, v103
	v_cvt_pk_bf16_f32 v103, v104, v105
	v_or_b32_e32 v254, 0x70, v134
	v_mad_i64_i32 v[254:255], s[48:49], v132, s44, v[136:137]
	v_lshlrev_b64 v[254:255], 11, v[254:255]
	s_nop 0
	v_lshl_add_u64 v[254:255], s[22:23], 0, v[254:255]
	v_mul_f32_e32 v98, v98, v251
	v_mul_f32_e32 v99, v99, v251
	v_mul_f32_e32 v100, v100, v251
	v_mul_f32_e32 v101, v101, v251
	v_cvt_pk_bf16_f32 v104, v98, v99
	v_cvt_pk_bf16_f32 v105, v100, v101
	v_lshl_add_u64 v[100:101], v[134:135], 1, v[254:255]
	s_nop 1
	v_permlane16_swap_b32 v102, v104
	v_permlane16_swap_b32 v103, v105
	v_lshl_add_u64 v[254:255], v[100:101], 0, v[252:253]
	s_nop 0
	global_store_dwordx4 v[254:255], v[102:105], off offset:192
	s_nop 1
	v_or_b32_e32 v98, 16, v136
	v_ashrrev_i32_e32 v99, 31, v98
	v_mad_i64_i32 v[100:101], s[48:49], v132, s44, v[136:137]
	v_lshl_add_u64 v[100:101], v[100:101], 2, s[26:27]
	v_add_co_u32_e32 v102, vcc, 0x12000, v100
	s_nop 1
	v_addc_co_u32_e32 v103, vcc, 0, v101, vcc
	global_load_dword v100, v[100:101], off offset:64
	s_nop 0
	global_load_dword v101, v[102:103], off offset:64
	s_waitcnt vmcnt(1)
; __device__ __forceinline__ unsigned pack2(float a, float b) { unsigned r; asm("v_cvt_pk_bf16_f32 %0, %1, %2" : "=v"(r) : "v"(a), "v"(b)); return r; }
;   __device__ __forceinline__ void c4(int g, int rig, int col, f32x4 v) const {
;     const size_t row = (size_t)g * ostride + rig;
;     float s = 1.f;
;     if (NP > 0) {
;       float t = 0.f;
; #pragma unroll
;       for (int q = 0; q < NP; ++q) t += part[(size_t)q * pstride + row];
;       s = rsqrtf(t * inv_n + 1e-6f);
;     }
;     uint2 u; u.x = pack2(v[0] * s, v[1] * s); u.y = pack2(v[2] * s, v[3] * s);
;     *(uint2*)(out + row * ld + col) = u;
;   }
; template <bool SWAP, class Epi, bool THIN = false> ...
;     ...
; #pragma unroll
;           for (int n = 0; n < 8; ++n) {
;             const int col = nt * 256 + wc_e * 128 + n * 16 + fq_e * 4;
;             if (col < N) epi.c4(g, rig, col, acc[m][n]);
;           }
;         }
	v_add_f32_e32 v100, 0, v100
	s_waitcnt vmcnt(0)
	v_add_f32_e32 v100, v100, v101
	v_fmamk_f32 v100, v100, 0x3b800000, v172
	v_mul_f32_e32 v101, 0x4b800000, v100
	v_cmp_gt_f32_e32 vcc, s47, v100
	s_nop 1
	v_cndmask_b32_e32 v100, v100, v101, vcc
	v_rsq_f32_e32 v102, v100
	v_mad_i64_i32 v[100:101], s[48:49], v132, s44, v[98:99]
	v_lshlrev_b64 v[100:101], 11, v[100:101]
	v_mul_f32_e32 v103, 0x45800000, v102
	v_cndmask_b32_e32 v102, v102, v103, vcc
	v_lshl_add_u64 v[100:101], s[22:23], 0, v[100:101]
	v_mov_b32_e32 v251, v102
	v_mul_f32_e32 v94, v94, v102
	v_mul_f32_e32 v95, v95, v102
	v_mul_f32_e32 v96, v96, v102
	v_mul_f32_e32 v97, v97, v102
	v_cvt_pk_bf16_f32 v94, v94, v95
	v_cvt_pk_bf16_f32 v95, v96, v97
	v_mad_i64_i32 v[254:255], s[48:49], v132, s44, v[98:99]
	v_lshlrev_b64 v[254:255], 11, v[254:255]
	v_lshl_add_u64 v[254:255], s[22:23], 0, v[254:255]
	v_mul_f32_e32 v90, v90, v251
	v_mul_f32_e32 v91, v91, v251
	v_mul_f32_e32 v92, v92, v251
	v_mul_f32_e32 v93, v93, v251
	v_cvt_pk_bf16_f32 v96, v90, v91
	v_cvt_pk_bf16_f32 v97, v92, v93
	v_lshl_add_u64 v[92:93], v[134:135], 1, v[254:255]
	s_nop 1
	v_permlane16_swap_b32 v94, v96
	v_permlane16_swap_b32 v95, v97
	v_lshl_add_u64 v[254:255], v[92:93], 0, v[252:253]
	s_nop 0
	global_store_dwordx4 v[254:255], v[94:97], off
	s_nop 1
	v_mad_i64_i32 v[90:91], s[48:49], v132, s44, v[98:99]
	v_lshlrev_b64 v[90:91], 11, v[90:91]
	v_lshl_add_u64 v[90:91], s[22:23], 0, v[90:91]
	v_mul_f32_e32 v86, v86, v251
	v_mul_f32_e32 v87, v87, v251
	v_mul_f32_e32 v88, v88, v251
	v_mul_f32_e32 v89, v89, v251
	v_cvt_pk_bf16_f32 v86, v86, v87
	v_cvt_pk_bf16_f32 v87, v88, v89
	v_mad_i64_i32 v[254:255], s[48:49], v132, s44, v[98:99]
	v_lshlrev_b64 v[254:255], 11, v[254:255]
	v_lshl_add_u64 v[254:255], s[22:23], 0, v[254:255]
	v_mul_f32_e32 v82, v82, v251
	v_mul_f32_e32 v83, v83, v251
	v_mul_f32_e32 v84, v84, v251
	v_mul_f32_e32 v85, v85, v251
	v_cvt_pk_bf16_f32 v88, v82, v83
	v_cvt_pk_bf16_f32 v89, v84, v85
	v_lshl_add_u64 v[84:85], v[134:135], 1, v[254:255]
	s_nop 1
	v_permlane16_swap_b32 v86, v88
	v_permlane16_swap_b32 v87, v89
	v_lshl_add_u64 v[254:255], v[84:85], 0, v[252:253]
	s_nop 0
	global_store_dwordx4 v[254:255], v[86:89], off offset:64
	s_nop 1
	v_mad_i64_i32 v[82:83], s[48:49], v132, s44, v[98:99]
	v_lshlrev_b64 v[82:83], 11, v[82:83]
	v_lshl_add_u64 v[82:83], s[22:23], 0, v[82:83]
	v_mul_f32_e32 v78, v78, v251
	v_mul_f32_e32 v79, v79, v251
	v_mul_f32_e32 v80, v80, v251
	v_mul_f32_e32 v81, v81, v251
	v_cvt_pk_bf16_f32 v78, v78, v79
	v_cvt_pk_bf16_f32 v79, v80, v81
	v_mad_i64_i32 v[254:255], s[48:49], v132, s44, v[98:99]
	v_lshlrev_b64 v[254:255], 11, v[254:255]
	v_lshl_add_u64 v[254:255], s[22:23], 0, v[254:255]
	v_mul_f32_e32 v74, v74, v251
	v_mul_f32_e32 v75, v75, v251
	v_mul_f32_e32 v76, v76, v251
	v_mul_f32_e32 v77, v77, v251
	v_cvt_pk_bf16_f32 v80, v74, v75
	v_cvt_pk_bf16_f32 v81, v76, v77
	v_lshl_add_u64 v[76:77], v[134:135], 1, v[254:255]
	s_nop 1
	v_permlane16_swap_b32 v78, v80
	v_permlane16_swap_b32 v79, v81
	v_lshl_add_u64 v[254:255], v[76:77], 0, v[252:253]
	s_nop 0
	global_store_dwordx4 v[254:255], v[78:81], off offset:128
	s_nop 1
	v_mad_i64_i32 v[74:75], s[48:49], v132, s44, v[98:99]
	v_lshlrev_b64 v[74:75], 11, v[74:75]
	v_lshl_add_u64 v[74:75], s[22:23], 0, v[74:75]
	v_mul_f32_e32 v70, v70, v251
	v_mul_f32_e32 v71, v71, v251
	v_mul_f32_e32 v72, v72, v251
	v_mul_f32_e32 v73, v73, v251
	v_cvt_pk_bf16_f32 v70, v70, v71
	v_cvt_pk_bf16_f32 v71, v72, v73
	v_mad_i64_i32 v[254:255], s[48:49], v132, s44, v[98:99]
	v_lshlrev_b64 v[254:255], 11, v[254:255]
	v_lshl_add_u64 v[254:255], s[22:23], 0, v[254:255]
	v_mul_f32_e32 v66, v66, v251
	v_mul_f32_e32 v67, v67, v251
	v_mul_f32_e32 v68, v68, v251
	v_mul_f32_e32 v69, v69, v251
	v_cvt_pk_bf16_f32 v72, v66, v67
	v_cvt_pk_bf16_f32 v73, v68, v69
	v_lshl_add_u64 v[68:69], v[134:135], 1, v[254:255]
	s_nop 1
	v_permlane16_swap_b32 v70, v72
	v_permlane16_swap_b32 v71, v73
	v_lshl_add_u64 v[254:255], v[68:69], 0, v[252:253]
	s_nop 0
	global_store_dwordx4 v[254:255], v[70:73], off offset:192
	s_nop 1
	v_or_b32_e32 v66, 32, v136
	v_ashrrev_i32_e32 v67, 31, v66
	v_mad_i64_i32 v[68:69], s[48:49], v132, s44, v[136:137]
	v_lshl_add_u64 v[68:69], v[68:69], 2, s[26:27]
	v_add_co_u32_e32 v70, vcc, 0x12000, v68
	s_nop 1
	v_addc_co_u32_e32 v71, vcc, 0, v69, vcc
	global_load_dword v68, v[68:69], off offset:128
	s_nop 0
	global_load_dword v69, v[70:71], off offset:128
	s_waitcnt vmcnt(1)
	v_add_f32_e32 v68, 0, v68
	s_waitcnt vmcnt(0)
; __device__ __forceinline__ unsigned pack2(float a, float b) { unsigned r; asm("v_cvt_pk_bf16_f32 %0, %1, %2" : "=v"(r) : "v"(a), "v"(b)); return r; }
;   __device__ __forceinline__ void c4(int g, int rig, int col, f32x4 v) const {
;     const size_t row = (size_t)g * ostride + rig;
;     float s = 1.f;
;     if (NP > 0) {
;       float t = 0.f;
; #pragma unroll
;       for (int q = 0; q < NP; ++q) t += part[(size_t)q * pstride + row];
;       s = rsqrtf(t * inv_n + 1e-6f);
;     }
;     uint2 u; u.x = pack2(v[0] * s, v[1] * s); u.y = pack2(v[2] * s, v[3] * s);
;     *(uint2*)(out + row * ld + col) = u;
;   }
; template <bool SWAP, class Epi, bool THIN = false> ...
;     ...
; #pragma unroll
;           for (int n = 0; n < 8; ++n) {
;             const int col = nt * 256 + wc_e * 128 + n * 16 + fq_e * 4;
;             if (col < N) epi.c4(g, rig, col, acc[m][n]);
;           }
;         }
	v_add_f32_e32 v68, v68, v69
	v_fmamk_f32 v68, v68, 0x3b800000, v172
	v_mul_f32_e32 v69, 0x4b800000, v68
	v_cmp_gt_f32_e32 vcc, s47, v68
	s_nop 1
	v_cndmask_b32_e32 v68, v68, v69, vcc
	v_rsq_f32_e32 v70, v68
	v_mad_i64_i32 v[68:69], s[48:49], v132, s44, v[66:67]
	v_lshlrev_b64 v[68:69], 11, v[68:69]
	v_mul_f32_e32 v71, 0x45800000, v70
	v_cndmask_b32_e32 v70, v70, v71, vcc
	v_lshl_add_u64 v[68:69], s[22:23], 0, v[68:69]
	v_mov_b32_e32 v251, v70
	v_mul_f32_e32 v62, v62, v70
	v_mul_f32_e32 v63, v63, v70
	v_mul_f32_e32 v64, v64, v70
	v_mul_f32_e32 v65, v65, v70
	v_cvt_pk_bf16_f32 v62, v62, v63
	v_cvt_pk_bf16_f32 v63, v64, v65
	v_mad_i64_i32 v[254:255], s[48:49], v132, s44, v[66:67]
	v_lshlrev_b64 v[254:255], 11, v[254:255]
	v_lshl_add_u64 v[254:255], s[22:23], 0, v[254:255]
	v_mul_f32_e32 v58, v58, v251
	v_mul_f32_e32 v59, v59, v251
	v_mul_f32_e32 v60, v60, v251
	v_mul_f32_e32 v61, v61, v251
	v_cvt_pk_bf16_f32 v64, v58, v59
	v_cvt_pk_bf16_f32 v65, v60, v61
	v_lshl_add_u64 v[60:61], v[134:135], 1, v[254:255]
	s_nop 1
	v_permlane16_swap_b32 v62, v64
	v_permlane16_swap_b32 v63, v65
	v_lshl_add_u64 v[254:255], v[60:61], 0, v[252:253]
	s_nop 0
	global_store_dwordx4 v[254:255], v[62:65], off
	s_nop 1
	v_mad_i64_i32 v[58:59], s[48:49], v132, s44, v[66:67]
	v_lshlrev_b64 v[58:59], 11, v[58:59]
	v_lshl_add_u64 v[58:59], s[22:23], 0, v[58:59]
	v_mul_f32_e32 v54, v54, v251
	v_mul_f32_e32 v55, v55, v251
	v_mul_f32_e32 v56, v56, v251
	v_mul_f32_e32 v57, v57, v251
	v_cvt_pk_bf16_f32 v54, v54, v55
	v_cvt_pk_bf16_f32 v55, v56, v57
	v_mad_i64_i32 v[254:255], s[48:49], v132, s44, v[66:67]
	v_lshlrev_b64 v[254:255], 11, v[254:255]
	v_lshl_add_u64 v[254:255], s[22:23], 0, v[254:255]
	v_mul_f32_e32 v50, v50, v251
	v_mul_f32_e32 v51, v51, v251
	v_mul_f32_e32 v52, v52, v251
	v_mul_f32_e32 v53, v53, v251
	v_cvt_pk_bf16_f32 v56, v50, v51
	v_cvt_pk_bf16_f32 v57, v52, v53
	v_lshl_add_u64 v[52:53], v[134:135], 1, v[254:255]
	s_nop 1
	v_permlane16_swap_b32 v54, v56
	v_permlane16_swap_b32 v55, v57
	v_lshl_add_u64 v[254:255], v[52:53], 0, v[252:253]
	s_nop 0
	global_store_dwordx4 v[254:255], v[54:57], off offset:64
	s_nop 1
	v_mad_i64_i32 v[50:51], s[48:49], v132, s44, v[66:67]
	v_lshlrev_b64 v[50:51], 11, v[50:51]
	v_lshl_add_u64 v[50:51], s[22:23], 0, v[50:51]
	v_mul_f32_e32 v46, v46, v251
	v_mul_f32_e32 v47, v47, v251
	v_mul_f32_e32 v48, v48, v251
	v_mul_f32_e32 v49, v49, v251
	v_cvt_pk_bf16_f32 v46, v46, v47
	v_cvt_pk_bf16_f32 v47, v48, v49
	v_mad_i64_i32 v[254:255], s[48:49], v132, s44, v[66:67]
	v_lshlrev_b64 v[254:255], 11, v[254:255]
	v_lshl_add_u64 v[254:255], s[22:23], 0, v[254:255]
	v_mul_f32_e32 v42, v42, v251
	v_mul_f32_e32 v43, v43, v251
	v_mul_f32_e32 v44, v44, v251
	v_mul_f32_e32 v45, v45, v251
	v_cvt_pk_bf16_f32 v48, v42, v43
	v_cvt_pk_bf16_f32 v49, v44, v45
	v_lshl_add_u64 v[44:45], v[134:135], 1, v[254:255]
	s_nop 1
	v_permlane16_swap_b32 v46, v48
	v_permlane16_swap_b32 v47, v49
	v_lshl_add_u64 v[254:255], v[44:45], 0, v[252:253]
	s_nop 0
	global_store_dwordx4 v[254:255], v[46:49], off offset:128
	s_nop 1
	v_mad_i64_i32 v[42:43], s[48:49], v132, s44, v[66:67]
	v_lshlrev_b64 v[42:43], 11, v[42:43]
	v_lshl_add_u64 v[42:43], s[22:23], 0, v[42:43]
	v_mul_f32_e32 v38, v38, v251
	v_mul_f32_e32 v39, v39, v251
	v_mul_f32_e32 v40, v40, v251
	v_mul_f32_e32 v41, v41, v251
	v_cvt_pk_bf16_f32 v38, v38, v39
	v_cvt_pk_bf16_f32 v39, v40, v41
	v_mad_i64_i32 v[254:255], s[48:49], v132, s44, v[66:67]
	v_lshlrev_b64 v[254:255], 11, v[254:255]
	v_lshl_add_u64 v[254:255], s[22:23], 0, v[254:255]
	v_mul_f32_e32 v34, v34, v251
	v_mul_f32_e32 v35, v35, v251
	v_mul_f32_e32 v36, v36, v251
	v_mul_f32_e32 v37, v37, v251
	v_cvt_pk_bf16_f32 v40, v34, v35
	v_cvt_pk_bf16_f32 v41, v36, v37
	v_lshl_add_u64 v[36:37], v[134:135], 1, v[254:255]
	s_nop 1
	v_permlane16_swap_b32 v38, v40
	v_permlane16_swap_b32 v39, v41
	v_lshl_add_u64 v[254:255], v[36:37], 0, v[252:253]
	s_nop 0
	global_store_dwordx4 v[254:255], v[38:41], off offset:192
	s_nop 1
	v_or_b32_e32 v34, 48, v136
	v_ashrrev_i32_e32 v35, 31, v34
	v_mad_i64_i32 v[36:37], s[10:11], v132, s44, v[136:137]
	v_lshl_add_u64 v[36:37], v[36:37], 2, s[26:27]
	v_add_co_u32_e32 v38, vcc, 0x12000, v36
	s_nop 1
	v_addc_co_u32_e32 v39, vcc, 0, v37, vcc
	global_load_dword v36, v[36:37], off offset:192
	s_nop 0
	global_load_dword v37, v[38:39], off offset:192
	s_waitcnt vmcnt(1)
; __device__ __forceinline__ unsigned pack2(float a, float b) { unsigned r; asm("v_cvt_pk_bf16_f32 %0, %1, %2" : "=v"(r) : "v"(a), "v"(b)); return r; }
;   __device__ __forceinline__ void c4(int g, int rig, int col, f32x4 v) const {
;     const size_t row = (size_t)g * ostride + rig;
;     float s = 1.f;
;     if (NP > 0) {
;       float t = 0.f;
; #pragma unroll
;       for (int q = 0; q < NP; ++q) t += part[(size_t)q * pstride + row];
;       s = rsqrtf(t * inv_n + 1e-6f);
;     }
;     uint2 u; u.x = pack2(v[0] * s, v[1] * s); u.y = pack2(v[2] * s, v[3] * s);
;     *(uint2*)(out + row * ld + col) = u;
;   }
; template <bool SWAP, class Epi, bool THIN = false> ...
;     ...
; #pragma unroll
;           for (int n = 0; n < 8; ++n) {
;             const int col = nt * 256 + wc_e * 128 + n * 16 + fq_e * 4;
;             if (col < N) epi.c4(g, rig, col, acc[m][n]);
;           }
;         }
	v_add_f32_e32 v36, 0, v36
	s_waitcnt vmcnt(0)
	v_add_f32_e32 v36, v36, v37
	v_fmamk_f32 v36, v36, 0x3b800000, v172
	v_mul_f32_e32 v37, 0x4b800000, v36
	v_cmp_gt_f32_e32 vcc, s47, v36
	s_nop 1
	v_cndmask_b32_e32 v36, v36, v37, vcc
	v_rsq_f32_e32 v38, v36
	v_mad_i64_i32 v[36:37], s[10:11], v132, s44, v[34:35]
	v_lshlrev_b64 v[36:37], 11, v[36:37]
	v_mul_f32_e32 v39, 0x45800000, v38
	v_cndmask_b32_e32 v38, v38, v39, vcc
	v_lshl_add_u64 v[36:37], s[22:23], 0, v[36:37]
	v_mov_b32_e32 v251, v38
	v_mul_f32_e32 v30, v30, v38
	v_mul_f32_e32 v31, v31, v38
	v_mul_f32_e32 v32, v32, v38
	v_mul_f32_e32 v33, v33, v38
	v_cvt_pk_bf16_f32 v30, v30, v31
	v_cvt_pk_bf16_f32 v31, v32, v33
	v_mad_i64_i32 v[254:255], s[12:13], v132, s44, v[34:35]
	v_lshlrev_b64 v[254:255], 11, v[254:255]
	v_lshl_add_u64 v[254:255], s[22:23], 0, v[254:255]
	v_mul_f32_e32 v26, v26, v251
	v_mul_f32_e32 v27, v27, v251
	v_mul_f32_e32 v28, v28, v251
	v_mul_f32_e32 v29, v29, v251
	v_cvt_pk_bf16_f32 v32, v26, v27
	v_cvt_pk_bf16_f32 v33, v28, v29
	v_lshl_add_u64 v[28:29], v[134:135], 1, v[254:255]
	s_nop 1
	v_permlane16_swap_b32 v30, v32
	v_permlane16_swap_b32 v31, v33
	v_lshl_add_u64 v[254:255], v[28:29], 0, v[252:253]
	s_nop 0
	global_store_dwordx4 v[254:255], v[30:33], off
	s_nop 1
	v_mad_i64_i32 v[26:27], s[12:13], v132, s44, v[34:35]
	v_lshlrev_b64 v[26:27], 11, v[26:27]
	v_lshl_add_u64 v[26:27], s[22:23], 0, v[26:27]
	v_mul_f32_e32 v22, v22, v251
	v_mul_f32_e32 v23, v23, v251
	v_mul_f32_e32 v24, v24, v251
	v_mul_f32_e32 v25, v25, v251
	v_cvt_pk_bf16_f32 v22, v22, v23
	v_cvt_pk_bf16_f32 v23, v24, v25
	v_mad_i64_i32 v[254:255], s[12:13], v132, s44, v[34:35]
	v_lshlrev_b64 v[254:255], 11, v[254:255]
	v_lshl_add_u64 v[254:255], s[22:23], 0, v[254:255]
	v_mul_f32_e32 v18, v18, v251
	v_mul_f32_e32 v19, v19, v251
	v_mul_f32_e32 v20, v20, v251
	v_mul_f32_e32 v21, v21, v251
	v_cvt_pk_bf16_f32 v24, v18, v19
	v_cvt_pk_bf16_f32 v25, v20, v21
	v_lshl_add_u64 v[20:21], v[134:135], 1, v[254:255]
	s_nop 1
	v_permlane16_swap_b32 v22, v24
	v_permlane16_swap_b32 v23, v25
	v_lshl_add_u64 v[254:255], v[20:21], 0, v[252:253]
	s_nop 0
	global_store_dwordx4 v[254:255], v[22:25], off offset:64
	s_nop 1
	v_mad_i64_i32 v[18:19], s[12:13], v132, s44, v[34:35]
	v_lshlrev_b64 v[18:19], 11, v[18:19]
	v_lshl_add_u64 v[18:19], s[22:23], 0, v[18:19]
	v_mul_f32_e32 v14, v14, v251
	v_mul_f32_e32 v15, v15, v251
	v_mul_f32_e32 v16, v16, v251
	v_mul_f32_e32 v17, v17, v251
	v_cvt_pk_bf16_f32 v14, v14, v15
	v_cvt_pk_bf16_f32 v15, v16, v17
	v_mad_i64_i32 v[254:255], s[8:9], v132, s44, v[34:35]
	v_lshlrev_b64 v[254:255], 11, v[254:255]
	v_lshl_add_u64 v[254:255], s[22:23], 0, v[254:255]
	v_mul_f32_e32 v10, v10, v251
	v_mul_f32_e32 v11, v11, v251
	v_mul_f32_e32 v12, v12, v251
	v_mul_f32_e32 v13, v13, v251
	v_cvt_pk_bf16_f32 v16, v10, v11
	v_cvt_pk_bf16_f32 v17, v12, v13
	v_lshl_add_u64 v[12:13], v[134:135], 1, v[254:255]
	s_nop 1
	v_permlane16_swap_b32 v14, v16
	v_permlane16_swap_b32 v15, v17
	v_lshl_add_u64 v[254:255], v[12:13], 0, v[252:253]
	s_nop 0
	global_store_dwordx4 v[254:255], v[14:17], off offset:128
	s_nop 1
	v_mad_i64_i32 v[10:11], s[6:7], v132, s44, v[34:35]
	v_lshlrev_b64 v[10:11], 11, v[10:11]
	v_lshl_add_u64 v[10:11], s[22:23], 0, v[10:11]
	v_mul_f32_e32 v6, v6, v251
	v_mul_f32_e32 v7, v7, v251
	v_mul_f32_e32 v8, v8, v251
	v_mul_f32_e32 v9, v9, v251
	v_cvt_pk_bf16_f32 v6, v6, v7
	v_cvt_pk_bf16_f32 v7, v8, v9
	v_mad_i64_i32 v[254:255], s[4:5], v132, s44, v[34:35]
	v_lshlrev_b64 v[254:255], 11, v[254:255]
	v_lshl_add_u64 v[254:255], s[22:23], 0, v[254:255]
	v_mul_f32_e32 v2, v2, v251
	v_mul_f32_e32 v3, v3, v251
	v_mul_f32_e32 v4, v4, v251
	v_mul_f32_e32 v5, v5, v251
	v_cvt_pk_bf16_f32 v8, v2, v3
	v_cvt_pk_bf16_f32 v9, v4, v5
	v_lshl_add_u64 v[4:5], v[134:135], 1, v[254:255]
	s_nop 1
	v_permlane16_swap_b32 v6, v8
	v_permlane16_swap_b32 v7, v9
	v_lshl_add_u64 v[254:255], v[4:5], 0, v[252:253]
	s_nop 0
	global_store_dwordx4 v[254:255], v[6:9], off offset:192
	s_nop 1
	s_branch .LBB0_1817

; __device__ __forceinline__ unsigned pack2(float a, float b) { unsigned r; asm("v_cvt_pk_bf16_f32 %0, %1, %2" : "=v"(r) : "v"(a), "v"(b)); return r; }
; __device__ __forceinline__ void phase_attn(CP& p, char* smem, int vid0, int grid) {
;     ...
;       float psum = 0.f;
;       bf16x8 pf[4];
; #pragma unroll
;       for (int t2 = 0; t2 < 2; ++t2)
; #pragma unroll
;         for (int hf = 0; hf < 2; ++hf) {
;           union { unsigned u[4]; bf16x8 v; } cvp;
; #pragma unroll
;           for (int i = 0; i < 4; ++i) {
;             const float p0 = __builtin_amdgcn_exp2f(s[t2][hf * 8 + 2 * i] * cs - mnew);
;             const float p1 = __builtin_amdgcn_exp2f(s[t2][hf * 8 + 2 * i + 1] * cs - mnew);
;             psum += p0 + p1;
;             cvp.u[i] = pack2(p0, p1);
;           }
;           pf[t2 * 2 + hf] = cvp.v;
;         }
;       lrun += psum;
; #pragma unroll
;       for (int dt = 0; dt < 2; ++dt)
; #pragma unroll
;         for (int s4 = 0; s4 < 4; ++s4) {
;           const bf16x8 vfr = *(const bf16x8*)(Vs + (32 * dt + r) * 72 + 16 * s4 + 8 * hh);
;           oacc[dt] = __builtin_amdgcn_mfma_f32_32x32x16_bf16(vfr, pf[s4], oacc[dt], 0, 0, 0);
;         }
.LBB0_2024:
	v_fma_f32 v3, v52, s25, -v147
	v_fma_f32 v52, v53, s25, -v147
	v_exp_f32_e32 v3, v3
	v_exp_f32_e32 v52, v52
	v_fma_f32 v36, v36, s25, -v147
	v_exp_f32_e32 v70, v36
	v_fma_f32 v36, v37, s25, -v147
	v_add_f32_e32 v53, v3, v52
	v_cvt_pk_bf16_f32 v52, v3, v52
	v_add_f32_e32 v3, 0, v53
	v_fma_f32 v53, v54, s25, -v147
	v_fma_f32 v54, v55, s25, -v147
	v_exp_f32_e32 v53, v53
	v_exp_f32_e32 v54, v54
	v_fma_f32 v55, v56, s25, -v147
	v_fma_f32 v56, v57, s25, -v147
	v_exp_f32_e32 v55, v55
	v_exp_f32_e32 v56, v56
	v_exp_f32_e32 v71, v36
	v_fma_f32 v36, v38, s25, -v147
	v_exp_f32_e32 v72, v36
	v_fma_f32 v36, v39, s25, -v147
	v_exp_f32_e32 v73, v36
	v_fma_f32 v36, v40, s25, -v147
	v_add_f32_e32 v57, v53, v54
	v_exp_f32_e32 v74, v36
	v_fma_f32 v36, v41, s25, -v147
	v_add_f32_e32 v3, v57, v3
	v_cvt_pk_bf16_f32 v53, v53, v54
	v_add_f32_e32 v54, v55, v56
	v_exp_f32_e32 v75, v36
	v_fma_f32 v36, v42, s25, -v147
	v_add_f32_e32 v3, v54, v3
	v_cvt_pk_bf16_f32 v54, v55, v56
	v_fma_f32 v55, v58, s25, -v147
	v_fma_f32 v56, v59, s25, -v147
	v_exp_f32_e32 v76, v36
	ds_read_b128 v[36:39], v146 offset:46080
	v_exp_f32_e32 v55, v55
	v_exp_f32_e32 v56, v56
	v_fma_f32 v57, v60, s25, -v147
	v_fma_f32 v58, v61, s25, -v147
	v_exp_f32_e32 v57, v57
	v_exp_f32_e32 v58, v58
	v_add_f32_e32 v59, v55, v56
	v_add_f32_e32 v3, v59, v3
	v_cvt_pk_bf16_f32 v55, v55, v56
	v_add_f32_e32 v56, v57, v58
	v_add_f32_e32 v3, v56, v3
	v_fma_f32 v56, v62, s25, -v147
	v_exp_f32_e32 v68, v56
	v_fma_f32 v56, v63, s25, -v147
	ds_read_b128 v[60:63], v146 offset:46112
	s_waitcnt lgkmcnt(1)
	v_mfma_f32_32x32x16_bf16 v[4:19], v[36:39], v[52:55], v[4:19]
	v_exp_f32_e32 v69, v56
	v_fma_f32 v56, v64, s25, -v147
	v_fma_f32 v36, v45, s25, -v147
	v_exp_f32_e32 v64, v56
	v_fma_f32 v56, v65, s25, -v147
	v_exp_f32_e32 v79, v36
	v_fma_f32 v36, v46, s25, -v147
	v_exp_f32_e32 v65, v56
	v_fma_f32 v56, v66, s25, -v147
	v_exp_f32_e32 v80, v36
	v_fma_f32 v36, v47, s25, -v147
	v_exp_f32_e32 v66, v56
	v_fma_f32 v56, v67, s25, -v147
	v_exp_f32_e32 v81, v36
	ds_read_b128 v[36:39], v146 offset:46144
	v_exp_f32_e32 v67, v56
	v_cvt_pk_bf16_f32 v56, v57, v58
	v_cvt_pk_bf16_f32 v57, v68, v69
	v_cvt_pk_bf16_f32 v58, v64, v65
	v_cvt_pk_bf16_f32 v59, v66, v67
	v_fma_f32 v44, v44, s25, -v147
	s_waitcnt lgkmcnt(1)
	v_mfma_f32_32x32x16_bf16 v[4:19], v[60:63], v[56:59], v[4:19]
	v_exp_f32_e32 v78, v44
	v_fma_f32 v44, v48, s25, -v147
	v_exp_f32_e32 v60, v44
	v_fma_f32 v44, v49, s25, -v147
	v_exp_f32_e32 v61, v44
	v_fma_f32 v44, v50, s25, -v147
	v_fma_f32 v40, v43, s25, -v147
	v_exp_f32_e32 v62, v44
	ds_read_b128 v[44:47], v146 offset:46176
	v_exp_f32_e32 v77, v40
	v_cvt_pk_bf16_f32 v40, v70, v71
	v_cvt_pk_bf16_f32 v41, v72, v73
	v_cvt_pk_bf16_f32 v42, v74, v75
	v_cvt_pk_bf16_f32 v43, v76, v77
	s_lshl_b32 s16, s16, 1
	s_waitcnt lgkmcnt(1)
	v_mfma_f32_32x32x16_bf16 v[4:19], v[36:39], v[40:43], v[4:19]
	v_fma_f32 v36, v51, s25, -v147
	ds_read_b128 v[48:51], v146 offset:50688
	v_exp_f32_e32 v63, v36
	v_cvt_pk_bf16_f32 v36, v78, v79
	v_cvt_pk_bf16_f32 v37, v80, v81
	v_cvt_pk_bf16_f32 v38, v60, v61
	v_cvt_pk_bf16_f32 v39, v62, v63
	s_add_i32 s3, s3, s54
	s_waitcnt lgkmcnt(1)
	v_mfma_f32_32x32x16_bf16 v[4:19], v[44:47], v[36:39], v[4:19]
	v_add_f32_e32 v44, v68, v69
	v_add_f32_e32 v3, v44, v3
	v_add_f32_e32 v44, v64, v65
	v_add_f32_e32 v3, v44, v3
	v_add_f32_e32 v44, v66, v67
	v_add_f32_e32 v3, v44, v3
	ds_read_b128 v[44:47], v146 offset:50720
	s_waitcnt lgkmcnt(1)
; __device__ __forceinline__ unsigned pack2(float a, float b) { unsigned r; asm("v_cvt_pk_bf16_f32 %0, %1, %2" : "=v"(r) : "v"(a), "v"(b)); return r; }
; __device__ __forceinline__ void phase_attn(CP& p, char* smem, int vid0, int grid) {
;     ...
;       lrun += psum;
; #pragma unroll
;       for (int dt = 0; dt < 2; ++dt)
; #pragma unroll
;         for (int s4 = 0; s4 < 4; ++s4) {
;           const bf16x8 vfr = *(const bf16x8*)(Vs + (32 * dt + r) * 72 + 16 * s4 + 8 * hh);
;           oacc[dt] = __builtin_amdgcn_mfma_f32_32x32x16_bf16(vfr, pf[s4], oacc[dt], 0, 0, 0);
;         }
;     }
;     const float ltot = lrun + __shfl_xor(lrun, 32);
;     const float inv = 1.f / ltot;
;     bf16_t* op = p.hxc + xrow * 1024 + h * 64;
; #pragma unroll
;     for (int dt = 0; dt < 2; ++dt)
; #pragma unroll
;       for (int i4 = 0; i4 < 4; ++i4) {
;         const int d = 32 * dt + 8 * i4 + 4 * hh;
;         uint2 u; u.x = pack2(oacc[dt][4 * i4] * inv, oacc[dt][4 * i4 + 1] * inv); u.y = pack2(oacc[dt][4 * i4 + 2] * inv, oacc[dt][4 * i4 + 3] * inv);
;         *(uint2*)(op + d) = u;
;       }
	v_mfma_f32_32x32x16_bf16 v[20:35], v[48:51], v[52:55], v[20:35]
	v_add_f32_e32 v48, v70, v71
	v_add_f32_e32 v3, v48, v3
	v_add_f32_e32 v48, v72, v73
	v_add_f32_e32 v3, v48, v3
	v_add_f32_e32 v48, v74, v75
	v_add_f32_e32 v3, v48, v3
	ds_read_b128 v[48:51], v146 offset:50752
	s_waitcnt lgkmcnt(1)
	v_mfma_f32_32x32x16_bf16 v[20:35], v[44:47], v[56:59], v[20:35]
	v_add_f32_e32 v44, v76, v77
	v_add_f32_e32 v3, v44, v3
	v_add_f32_e32 v52, v78, v79
	v_add_f32_e32 v53, v80, v81
	v_add_f32_e32 v3, v52, v3
	v_add_f32_e32 v54, v60, v61
	v_add_f32_e32 v3, v53, v3
	v_add_f32_e32 v55, v62, v63
	v_add_f32_e32 v3, v54, v3
	v_add_f32_e32 v3, v55, v3
	v_add_f32_e32 v3, v127, v3
	ds_read_b128 v[44:47], v146 offset:50784
	s_waitcnt lgkmcnt(1)
	v_mfma_f32_32x32x16_bf16 v[20:35], v[48:51], v[40:43], v[20:35]
	ds_bpermute_b32 v40, v125, v3
	v_mov_b32_e32 v127, v2
	s_cmpk_gt_i32 s3, 0x3ff
	s_waitcnt lgkmcnt(0)
	v_add_f32_e32 v3, v3, v40
	v_div_scale_f32 v40, s[12:13], v3, v3, 1.0
	v_rcp_f32_e32 v41, v40
	v_mfma_f32_32x32x16_bf16 v[20:35], v[44:47], v[36:39], v[20:35]
	v_fma_f32 v36, -v40, v41, 1.0
	v_fmac_f32_e32 v41, v36, v41
	v_div_scale_f32 v36, vcc, 1.0, v3, 1.0
	v_mul_f32_e32 v37, v36, v41
	v_fma_f32 v38, -v40, v37, v36
	v_fmac_f32_e32 v37, v38, v41
	v_fma_f32 v36, -v40, v37, v36
	v_div_fmas_f32 v36, v36, v41, v37
	v_div_fixup_f32 v3, v36, v3, 1.0
	v_lshlrev_b64 v[36:37], 11, v[128:129]
	v_lshl_add_u64 v[36:37], s[10:11], 0, v[36:37]
	v_mul_f32_e32 v4, v4, v3
	v_mul_f32_e32 v5, v5, v3
	v_lshl_add_u64 v[36:37], v[36:37], 0, s[16:17]
	v_cvt_pk_bf16_f32 v204, v4, v5
	v_mul_f32_e32 v5, v6, v3
	v_mul_f32_e32 v6, v7, v3
	v_cvt_pk_bf16_f32 v205, v5, v6
	v_lshl_add_u64 v[6:7], v[36:37], 0, v[126:127]
	v_and_b32_e32 v214, 32, v1
	v_lshrrev_b32_e32 v214, 2, v214
	v_mov_b32_e32 v215, 0
	v_lshl_add_u64 v[212:213], v[6:7], 0, v[214:215]
	v_mul_f32_e32 v4, v8, v3
	v_mul_f32_e32 v5, v9, v3
	v_cvt_pk_bf16_f32 v206, v4, v5
	v_mul_f32_e32 v5, v10, v3
	v_mul_f32_e32 v8, v11, v3
	v_cvt_pk_bf16_f32 v207, v5, v8
	s_nop 1
	v_permlane32_swap_b32 v204, v206
	v_permlane32_swap_b32 v205, v207
	global_store_dwordx4 v[212:213], v[204:207], off
	s_nop 1
	v_mul_f32_e32 v4, v12, v3
	v_mul_f32_e32 v5, v13, v3
	v_cvt_pk_bf16_f32 v208, v4, v5
	v_mul_f32_e32 v5, v14, v3
	v_mul_f32_e32 v8, v15, v3
	v_cvt_pk_bf16_f32 v209, v5, v8
	v_mul_f32_e32 v4, v16, v3
	v_mul_f32_e32 v5, v17, v3
	v_cvt_pk_bf16_f32 v210, v4, v5
	v_mul_f32_e32 v5, v18, v3
	v_mul_f32_e32 v8, v19, v3
	v_cvt_pk_bf16_f32 v211, v5, v8
	s_nop 1
	v_permlane32_swap_b32 v208, v210
	v_permlane32_swap_b32 v209, v211
	global_store_dwordx4 v[212:213], v[208:211], off offset:32
	s_nop 1
	v_mul_f32_e32 v4, v20, v3
	v_mul_f32_e32 v5, v21, v3
	v_cvt_pk_bf16_f32 v204, v4, v5
	v_mul_f32_e32 v5, v22, v3
	v_mul_f32_e32 v8, v23, v3
	v_cvt_pk_bf16_f32 v205, v5, v8
	v_mul_f32_e32 v4, v24, v3
	v_mul_f32_e32 v5, v25, v3
	v_cvt_pk_bf16_f32 v206, v4, v5
	v_mul_f32_e32 v5, v26, v3
	v_mul_f32_e32 v8, v27, v3
	v_cvt_pk_bf16_f32 v207, v5, v8
	s_nop 1
	v_permlane32_swap_b32 v204, v206
	v_permlane32_swap_b32 v205, v207
	global_store_dwordx4 v[212:213], v[204:207], off offset:64
	s_nop 1
	v_mul_f32_e32 v4, v28, v3
	v_mul_f32_e32 v5, v29, v3
	v_cvt_pk_bf16_f32 v208, v4, v5
	v_mul_f32_e32 v5, v30, v3
	v_mul_f32_e32 v8, v31, v3
	v_cvt_pk_bf16_f32 v209, v5, v8
	v_mul_f32_e32 v4, v32, v3
	v_mul_f32_e32 v5, v33, v3
	v_cvt_pk_bf16_f32 v210, v4, v5
	v_mul_f32_e32 v5, v34, v3
	v_mul_f32_e32 v3, v35, v3
	v_cvt_pk_bf16_f32 v211, v5, v3
	s_nop 1
	v_permlane32_swap_b32 v208, v210
	v_permlane32_swap_b32 v209, v211
	global_store_dwordx4 v[212:213], v[208:211], off offset:96
	s_nop 1
	s_cbranch_scc1 .LBB0_2039
